# scan output dot products reduced through LDS (per-step partial write, one lane per token/column adds them a block later) instead of DPP all-reduce
# baseline (speedup 1.0000x reference)
.Lls3_16_entry:
	v_and_b32_e32 v124, 63, v196
	v_and_b32_e32 v125, 15, v124
	v_lshrrev_b32_e32 v126, 4, v124
	s_min_u32 s29, s0, 4
	s_mul_i32 s29, s29, 0x5600
	v_and_b32_e32 v127, 3, v125
	v_cmp_eq_u32_e64 s[6:7], 1, v127
	v_cmp_eq_u32_e64 s[8:9], 2, v127
	v_cmp_eq_u32_e64 s[10:11], 3, v127
	v_lshl_add_u32 v0, v125, 4, s29
	v_lshl_add_u32 v1, v126, 4, s29
	s_lshl_b32 s37, s16, 11
	v_lshrrev_b32_e32 v125, 3, v124
	v_and_b32_e32 v126, 7, v124
	v_add_u32_e32 v127, s37, v125
	s_lshl_b32 s21, s17, 7
	s_add_u32 s21, s21, 0x10800700
	v_mul_u32_u24_e32 v5, 0xd00, v127
	v_lshl_add_u32 v5, v126, 4, v5
	v_add_u32_e32 v5, s21, v5
	v_lshlrev_b32_e32 v2, 8, v125
	v_lshl_add_u32 v2, v126, 5, v2
	v_add_u32_e32 v2, s29, v2
	v_and_b32_e32 v125, 31, v124
	v_lshrrev_b32_e32 v126, 2, v125
	v_and_b32_e32 v125, 3, v125
	v_add_u32_e32 v127, s37, v126
	s_lshl_b32 s22, s14, 2
	s_lshl_b32 s21, s17, 6
	s_add_u32 s21, s21, s22
	s_lshl_b32 s44, s21, 1
	s_add_u32 s44, s44, 0x10800b00
	v_mul_u32_u24_e32 v6, 0xd00, v127
	s_lshl_b32 s24, s17, 2
	s_add_u32 s24, s24, 0x13e00600
	v_mul_u32_u24_e32 v8, 0x630, v127
	v_lshl_add_u32 v8, v125, 4, v8
	v_add_u32_e32 v8, s24, v8
	v_lshlrev_b32_e32 v4, 6, v126
	v_lshl_add_u32 v4, v125, 4, v4
	v_lshl_add_u32 v6, v125, 1, v6
	v_add_u32_e32 v6, s44, v6
	v_add_u32_e32 v4, s29, v4
	v_and_b32_e32 v125, 15, v124
	v_lshrrev_b32_e32 v126, 4, v124
	v_add_u32_e32 v127, s37, v124
	v_lshlrev_b32_e32 v7, 11, v127
	s_lshl_b32 s44, s21, 1
	s_add_u32 s44, s44, 0x6300600
	v_add_u32_e32 v7, s44, v7
	s_lshl_b32 s44, s28, 3
	s_add_u32 s44, s44, s16
	s_lshl_b32 s44, s44, 2
	s_add_u32 s44, s44, s17
	s_mul_i32 s44, s44, 0x4000
	s_add_u32 s44, s44, 0x4480000
	s_lshl_b32 s24, s22, 2
	s_add_u32 s44, s44, s24
	v_lshlrev_b32_e32 v130, 10, v125
	v_lshl_add_u32 v130, v126, 2, v130
	v_add_u32_e32 v130, s44, v130
	v_readlane_b32 s26, v253, 29
	v_readlane_b32 s27, v253, 30
	v_lshlrev_b32_e32 v131, 3, v125
	v_lshl_add_u32 v131, v126, 1, v131
	v_add_u32_e32 v131, s29, v131
	v_lshl_add_u32 v132, v124, 3, s29
	v_lshl_add_u32 v133, v124, 2, s29
	v_lshl_add_u32 v131, v124, 1, s29
	v_subrev_u32_e32 v131, 0x100, v131
	v_lshrrev_b32_e32 v125, 2, v124
	v_and_b32_e32 v126, 3, v124
	v_lshlrev_b32_e32 v127, 8, v125
	v_lshl_add_u32 v127, v126, 6, v127
	v_add_u32_e32 v127, s29, v127
	v_add_u32_e32 v126, 0, v125
	v_and_b32_e32 v126, 3, v126
	v_lshl_add_u32 v136, v126, 4, v127
	v_add_u32_e32 v126, 1, v125
	v_and_b32_e32 v126, 3, v126
	v_lshl_add_u32 v137, v126, 4, v127
	v_add_u32_e32 v126, 2, v125
	v_and_b32_e32 v126, 3, v126
	v_lshl_add_u32 v138, v126, 4, v127
	v_add_u32_e32 v126, 3, v125
	v_and_b32_e32 v126, 3, v126
	v_lshl_add_u32 v139, v126, 4, v127
	v_mov_b32_e32 v10, 0
	v_mov_b32_e32 v11, 0
	v_mov_b32_e32 v12, 0
	v_mov_b32_e32 v13, 0
	v_mov_b32_e32 v9, 0
	v_mov_b32_e32 v14, 0
	v_mov_b32_e32 v15, 0
	v_mov_b32_e32 v16, 0
	s_setprio 2
	s_movk_i32 s12, 64
	s_nop 0
	global_load_dwordx4 v[70:73], v5, s[94:95]
	global_load_dwordx4 v[74:77], v5, s[94:95] offset:512
	global_load_ushort v78, v6, s[94:95]
	global_load_dword v79, v8, s[94:95]
	v_add_u32_e32 v5, 0x6800, v5
	v_add_u32_e32 v6, 0x6800, v6
	v_add_u32_e32 v8, 0x3180, v8
	s_waitcnt vmcnt(0)
	s_waitcnt vmcnt(2)
	v_lshlrev_b32_e32 v118, 16, v74
	v_and_b32_e32 v119, 0xffff0000, v74
	v_lshlrev_b32_e32 v120, 16, v75
	v_and_b32_e32 v121, 0xffff0000, v75
	ds_write_b128 v2, v[118:121] offset:0
	v_lshlrev_b32_e32 v124, 16, v76
	v_and_b32_e32 v125, 0xffff0000, v76
	v_lshlrev_b32_e32 v126, 16, v77
	v_and_b32_e32 v127, 0xffff0000, v77
	ds_write_b128 v2, v[124:127] offset:16
	v_lshlrev_b32_e32 v118, 16, v70
	v_and_b32_e32 v119, 0xffff0000, v70
	v_lshlrev_b32_e32 v120, 16, v71
	v_and_b32_e32 v121, 0xffff0000, v71
	ds_write_b128 v2, v[118:121] offset:2048
	v_lshlrev_b32_e32 v124, 16, v72
	v_and_b32_e32 v125, 0xffff0000, v72
	v_lshlrev_b32_e32 v126, 16, v73
	v_and_b32_e32 v127, 0xffff0000, v73
	ds_write_b128 v2, v[124:127] offset:2064
	s_waitcnt vmcnt(0)
	v_mov_b32_dpp v80, v79 quad_perm:[1,1,1,1] row_mask:0xf bank_mask:0xf
	v_mov_b32_dpp v81, v79 quad_perm:[2,2,2,2] row_mask:0xf bank_mask:0xf
	v_mov_b32_dpp v79, v79 quad_perm:[0,0,0,0] row_mask:0xf bank_mask:0xf
	v_lshlrev_b32_e32 v78, 16, v78
	v_mul_f32_e32 v81, 0x3d800000, v81
	s_nop 0
	ds_write_b128 v4, v[78:81] offset:4096
	global_load_dwordx4 v[82:85], v5, s[94:95]
	global_load_dwordx4 v[86:89], v5, s[94:95] offset:512
	global_load_ushort v90, v6, s[94:95]
	global_load_dword v91, v8, s[94:95]
	v_add_u32_e32 v5, 0x6800, v5
	v_add_u32_e32 v6, 0x6800, v6
	v_add_u32_e32 v8, 0x3180, v8
	global_load_dwordx4 v[94:97], v5, s[94:95]
	global_load_dwordx4 v[98:101], v5, s[94:95] offset:512
	global_load_ushort v102, v6, s[94:95]
	global_load_dword v103, v8, s[94:95]
	v_add_u32_e32 v5, 0x6800, v5
	v_add_u32_e32 v6, 0x6800, v6
	v_add_u32_e32 v8, 0x3180, v8
	global_load_dwordx4 v[106:109], v5, s[94:95]
	global_load_dwordx4 v[110:113], v5, s[94:95] offset:512
	global_load_ushort v114, v6, s[94:95]
	global_load_dword v115, v8, s[94:95]
	v_add_u32_e32 v5, 0x6800, v5
	v_add_u32_e32 v6, 0x6800, v6
	v_add_u32_e32 v8, 0x3180, v8
	global_load_dwordx4 v[70:73], v5, s[94:95]
	global_load_dwordx4 v[74:77], v5, s[94:95] offset:512
	global_load_ushort v78, v6, s[94:95]
	global_load_dword v79, v8, s[94:95]
	v_add_u32_e32 v5, 0x6800, v5
	v_add_u32_e32 v6, 0x6800, v6
	v_add_u32_e32 v8, 0x3180, v8
	ds_read_b128 v[20:23], v0 offset:0
	ds_read_b128 v[38:41], v0 offset:2048
	ds_read_b128 v[54:57], v1 offset:4096
	ds_read_b128 v[24:27], v0 offset:256
	ds_read_b128 v[42:45], v0 offset:2304
	ds_read_b128 v[58:61], v1 offset:4160
	ds_read_b128 v[28:31], v0 offset:512
	ds_read_b128 v[46:49], v0 offset:2560
	ds_read_b128 v[62:65], v1 offset:4224
.Lls3_16_loop:
	s_waitcnt lgkmcnt(6)
	v_mul_f32_e32 v36, v20, v10
	v_fmac_f32_e32 v36, v21, v11
	v_fmac_f32_e32 v36, v22, v12
	v_fmac_f32_e32 v36, v23, v13
	v_mul_f32_e32 v122, v38, v10
	v_fmac_f32_e32 v122, v39, v11
	v_add_f32_dpp v36, v36, v36 quad_perm:[1,0,3,2] row_mask:0xf bank_mask:0xf bound_ctrl:1
	v_fmac_f32_e32 v122, v40, v12
	v_fmac_f32_e32 v122, v41, v13
	v_add_f32_dpp v36, v36, v36 quad_perm:[2,3,0,1] row_mask:0xf bank_mask:0xf bound_ctrl:1
	v_mul_f32_e32 v10, v56, v10
	v_mul_f32_e32 v11, v56, v11
	v_add_f32_dpp v36, v36, v36 row_half_mirror row_mask:0xf bank_mask:0xf bound_ctrl:1
	v_mul_f32_e32 v12, v56, v12
	v_mul_f32_e32 v13, v56, v13
	v_add_f32_dpp v36, v36, v36 row_mirror row_mask:0xf bank_mask:0xf bound_ctrl:1
	v_mul_f32_e32 v129, v56, v122
	s_waitcnt vmcnt(14)
	v_fma_f32 v128, -v56, v36, v54
	v_mul_f32_e32 v19, v55, v128
	v_lshlrev_b32_e32 v118, 16, v86
	v_fmac_f32_e32 v10, v20, v19
	v_fmac_f32_e32 v11, v21, v19
	v_fmac_f32_e32 v12, v22, v19
	v_fmac_f32_e32 v13, v23, v19
	v_fmac_f32_e32 v129, v57, v19
	ds_write_b32 v133, v129 offset:9216
	ds_read_b128 v[32:35], v0 offset:768
	ds_read_b128 v[50:53], v0 offset:2816
	ds_read_b128 v[66:69], v1 offset:4288
	v_and_b32_e32 v119, 0xffff0000, v86
	v_lshlrev_b32_e32 v120, 16, v87
	v_and_b32_e32 v121, 0xffff0000, v87
	ds_write_b128 v2, v[118:121] offset:4608
	v_lshlrev_b32_e32 v124, 16, v88
	v_and_b32_e32 v125, 0xffff0000, v88
	s_waitcnt lgkmcnt(8)
	v_mul_f32_e32 v36, v24, v10
	v_fmac_f32_e32 v36, v25, v11
	v_fmac_f32_e32 v36, v26, v12
	v_fmac_f32_e32 v36, v27, v13
	v_mul_f32_e32 v122, v42, v10
	v_fmac_f32_e32 v122, v43, v11
	v_add_f32_dpp v36, v36, v36 quad_perm:[1,0,3,2] row_mask:0xf bank_mask:0xf bound_ctrl:1
	v_fmac_f32_e32 v122, v44, v12
	v_fmac_f32_e32 v122, v45, v13
	v_add_f32_dpp v36, v36, v36 quad_perm:[2,3,0,1] row_mask:0xf bank_mask:0xf bound_ctrl:1
	v_mul_f32_e32 v10, v60, v10
	v_mul_f32_e32 v11, v60, v11
	v_add_f32_dpp v36, v36, v36 row_half_mirror row_mask:0xf bank_mask:0xf bound_ctrl:1
	v_mul_f32_e32 v12, v60, v12
	v_mul_f32_e32 v13, v60, v13
	v_add_f32_dpp v36, v36, v36 row_mirror row_mask:0xf bank_mask:0xf bound_ctrl:1
	v_mul_f32_e32 v129, v60, v122
	v_lshlrev_b32_e32 v126, 16, v89
	v_fma_f32 v128, -v60, v36, v58
	v_mul_f32_e32 v19, v59, v128
	v_and_b32_e32 v127, 0xffff0000, v89
	v_fmac_f32_e32 v10, v24, v19
	v_fmac_f32_e32 v11, v25, v19
	v_fmac_f32_e32 v12, v26, v19
	v_fmac_f32_e32 v13, v27, v19
	v_fmac_f32_e32 v129, v61, v19
	ds_write_b32 v133, v129 offset:9472
	ds_read_b128 v[20:23], v0 offset:1024
	ds_read_b128 v[38:41], v0 offset:3072
	ds_read_b128 v[54:57], v1 offset:4352
	ds_write_b128 v2, v[124:127] offset:4624
	v_lshlrev_b32_e32 v118, 16, v82
	v_and_b32_e32 v119, 0xffff0000, v82
	v_lshlrev_b32_e32 v120, 16, v83
	v_and_b32_e32 v121, 0xffff0000, v83
	ds_write_b128 v2, v[118:121] offset:6656
	s_waitcnt lgkmcnt(11)
	v_mul_f32_e32 v36, v28, v10
	v_fmac_f32_e32 v36, v29, v11
	v_fmac_f32_e32 v36, v30, v12
	v_fmac_f32_e32 v36, v31, v13
	v_mul_f32_e32 v122, v46, v10
	v_fmac_f32_e32 v122, v47, v11
	v_add_f32_dpp v36, v36, v36 quad_perm:[1,0,3,2] row_mask:0xf bank_mask:0xf bound_ctrl:1
	v_fmac_f32_e32 v122, v48, v12
	v_fmac_f32_e32 v122, v49, v13
	v_add_f32_dpp v36, v36, v36 quad_perm:[2,3,0,1] row_mask:0xf bank_mask:0xf bound_ctrl:1
	v_mul_f32_e32 v10, v64, v10
	v_mul_f32_e32 v11, v64, v11
	v_add_f32_dpp v36, v36, v36 row_half_mirror row_mask:0xf bank_mask:0xf bound_ctrl:1
	v_mul_f32_e32 v12, v64, v12
	v_mul_f32_e32 v13, v64, v13
	v_add_f32_dpp v36, v36, v36 row_mirror row_mask:0xf bank_mask:0xf bound_ctrl:1
	v_mul_f32_e32 v129, v64, v122
	v_lshlrev_b32_e32 v124, 16, v84
	v_fma_f32 v128, -v64, v36, v62
	v_mul_f32_e32 v19, v63, v128
	v_and_b32_e32 v125, 0xffff0000, v84
	v_fmac_f32_e32 v10, v28, v19
	v_fmac_f32_e32 v11, v29, v19
	v_fmac_f32_e32 v12, v30, v19
	v_fmac_f32_e32 v13, v31, v19
	v_fmac_f32_e32 v129, v65, v19
	ds_write_b32 v133, v129 offset:9728
	ds_read_b128 v[24:27], v0 offset:1280
	ds_read_b128 v[42:45], v0 offset:3328
	ds_read_b128 v[58:61], v1 offset:4416
	v_lshlrev_b32_e32 v126, 16, v85
	v_and_b32_e32 v127, 0xffff0000, v85
	ds_write_b128 v2, v[124:127] offset:6672
	s_waitcnt vmcnt(12)
	v_mov_b32_dpp v92, v91 quad_perm:[1,1,1,1] row_mask:0xf bank_mask:0xf
	v_mov_b32_dpp v93, v91 quad_perm:[2,2,2,2] row_mask:0xf bank_mask:0xf
	s_waitcnt lgkmcnt(12)
	v_mul_f32_e32 v36, v32, v10
	v_fmac_f32_e32 v36, v33, v11
	v_fmac_f32_e32 v36, v34, v12
	v_fmac_f32_e32 v36, v35, v13
	v_mul_f32_e32 v122, v50, v10
	v_fmac_f32_e32 v122, v51, v11
	v_add_f32_dpp v36, v36, v36 quad_perm:[1,0,3,2] row_mask:0xf bank_mask:0xf bound_ctrl:1
	v_fmac_f32_e32 v122, v52, v12
	v_fmac_f32_e32 v122, v53, v13
	v_add_f32_dpp v36, v36, v36 quad_perm:[2,3,0,1] row_mask:0xf bank_mask:0xf bound_ctrl:1
	v_mul_f32_e32 v10, v68, v10
	v_mul_f32_e32 v11, v68, v11
	v_add_f32_dpp v36, v36, v36 row_half_mirror row_mask:0xf bank_mask:0xf bound_ctrl:1
	v_mul_f32_e32 v12, v68, v12
	v_mul_f32_e32 v13, v68, v13
	v_add_f32_dpp v36, v36, v36 row_mirror row_mask:0xf bank_mask:0xf bound_ctrl:1
	v_mul_f32_e32 v129, v68, v122
	v_mov_b32_dpp v91, v91 quad_perm:[0,0,0,0] row_mask:0xf bank_mask:0xf
	v_fma_f32 v128, -v68, v36, v66
	v_mul_f32_e32 v19, v67, v128
	v_lshlrev_b32_e32 v90, 16, v90
	v_fmac_f32_e32 v10, v32, v19
	v_fmac_f32_e32 v11, v33, v19
	v_fmac_f32_e32 v12, v34, v19
	v_fmac_f32_e32 v13, v35, v19
	v_fmac_f32_e32 v129, v69, v19
	ds_write_b32 v133, v129 offset:9984
	ds_read_b128 v[28:31], v0 offset:1536
	ds_read_b128 v[46:49], v0 offset:3584
	ds_read_b128 v[62:65], v1 offset:4480
	v_mul_f32_e32 v93, 0x3d800000, v93
	s_nop 0
	ds_write_b128 v4, v[90:93] offset:8704
	s_waitcnt lgkmcnt(12)
	v_mul_f32_e32 v36, v20, v10
	v_fmac_f32_e32 v36, v21, v11
	v_fmac_f32_e32 v36, v22, v12
	v_fmac_f32_e32 v36, v23, v13
	v_mul_f32_e32 v122, v38, v10
	v_fmac_f32_e32 v122, v39, v11
	v_add_f32_dpp v36, v36, v36 quad_perm:[1,0,3,2] row_mask:0xf bank_mask:0xf bound_ctrl:1
	v_fmac_f32_e32 v122, v40, v12
	v_fmac_f32_e32 v122, v41, v13
	v_add_f32_dpp v36, v36, v36 quad_perm:[2,3,0,1] row_mask:0xf bank_mask:0xf bound_ctrl:1
	v_mul_f32_e32 v10, v56, v10
	v_mul_f32_e32 v11, v56, v11
	v_add_f32_dpp v36, v36, v36 row_half_mirror row_mask:0xf bank_mask:0xf bound_ctrl:1
	v_mul_f32_e32 v12, v56, v12
	v_mul_f32_e32 v13, v56, v13
	v_add_f32_dpp v36, v36, v36 row_mirror row_mask:0xf bank_mask:0xf bound_ctrl:1
	v_mul_f32_e32 v129, v56, v122
	global_load_dwordx4 v[82:85], v5, s[94:95]
	global_load_dwordx4 v[86:89], v5, s[94:95] offset:512
	global_load_ushort v90, v6, s[94:95]
	global_load_dword v91, v8, s[94:95]
	v_add_u32_e32 v5, 0x6800, v5
	v_add_u32_e32 v6, 0x6800, v6
	v_add_u32_e32 v8, 0x3180, v8
	v_fma_f32 v128, -v56, v36, v54
	v_mul_f32_e32 v19, v55, v128
	ds_read_b128 v[140:143], v136 offset:13312
	v_fmac_f32_e32 v10, v20, v19
	v_fmac_f32_e32 v11, v21, v19
	v_fmac_f32_e32 v12, v22, v19
	v_fmac_f32_e32 v13, v23, v19
	v_fmac_f32_e32 v129, v57, v19
	ds_write_b32 v133, v129 offset:10240
	ds_read_b128 v[32:35], v0 offset:1792
	ds_read_b128 v[50:53], v0 offset:3840
	ds_read_b128 v[66:69], v1 offset:4544
	ds_read_b128 v[154:157], v137 offset:13312
	ds_read_b128 v[158:161], v138 offset:13312
	ds_read_b128 v[162:165], v139 offset:13312
	s_waitcnt lgkmcnt(14)
	v_mul_f32_e32 v36, v24, v10
	v_fmac_f32_e32 v36, v25, v11
	v_fmac_f32_e32 v36, v26, v12
	v_fmac_f32_e32 v36, v27, v13
	v_mul_f32_e32 v122, v42, v10
	v_fmac_f32_e32 v122, v43, v11
	v_add_f32_dpp v36, v36, v36 quad_perm:[1,0,3,2] row_mask:0xf bank_mask:0xf bound_ctrl:1
	v_fmac_f32_e32 v122, v44, v12
	v_fmac_f32_e32 v122, v45, v13
	v_add_f32_dpp v36, v36, v36 quad_perm:[2,3,0,1] row_mask:0xf bank_mask:0xf bound_ctrl:1
	v_mul_f32_e32 v10, v60, v10
	v_mul_f32_e32 v11, v60, v11
	v_add_f32_dpp v36, v36, v36 row_half_mirror row_mask:0xf bank_mask:0xf bound_ctrl:1
	v_mul_f32_e32 v12, v60, v12
	v_mul_f32_e32 v13, v60, v13
	v_add_f32_dpp v36, v36, v36 row_mirror row_mask:0xf bank_mask:0xf bound_ctrl:1
	v_mul_f32_e32 v129, v60, v122
	ds_read_b128 v[20:23], v0 offset:4608
	v_fma_f32 v128, -v60, v36, v58
	v_mul_f32_e32 v19, v59, v128
	ds_read_b128 v[38:41], v0 offset:6656
	v_fmac_f32_e32 v10, v24, v19
	v_fmac_f32_e32 v11, v25, v19
	v_fmac_f32_e32 v12, v26, v19
	v_fmac_f32_e32 v13, v27, v19
	v_fmac_f32_e32 v129, v61, v19
	ds_write_b32 v133, v129 offset:10496
	ds_read_b128 v[54:57], v1 offset:8704
	s_waitcnt lgkmcnt(13)
	v_mul_f32_e32 v36, v28, v10
	v_fmac_f32_e32 v36, v29, v11
	v_fmac_f32_e32 v36, v30, v12
	v_fmac_f32_e32 v36, v31, v13
	v_mul_f32_e32 v122, v46, v10
	v_fmac_f32_e32 v122, v47, v11
	v_add_f32_dpp v36, v36, v36 quad_perm:[1,0,3,2] row_mask:0xf bank_mask:0xf bound_ctrl:1
	v_fmac_f32_e32 v122, v48, v12
	v_fmac_f32_e32 v122, v49, v13
	v_add_f32_dpp v36, v36, v36 quad_perm:[2,3,0,1] row_mask:0xf bank_mask:0xf bound_ctrl:1
	v_mul_f32_e32 v10, v64, v10
	v_mul_f32_e32 v11, v64, v11
	v_add_f32_dpp v36, v36, v36 row_half_mirror row_mask:0xf bank_mask:0xf bound_ctrl:1
	v_mul_f32_e32 v12, v64, v12
	v_mul_f32_e32 v13, v64, v13
	v_add_f32_dpp v36, v36, v36 row_mirror row_mask:0xf bank_mask:0xf bound_ctrl:1
	v_mul_f32_e32 v129, v64, v122
	s_waitcnt lgkmcnt(4)
	v_fma_f32 v128, -v64, v36, v62
	v_mul_f32_e32 v19, v63, v128
	v_add_f32_e32 v140, v140, v158
	v_fmac_f32_e32 v10, v28, v19
	v_fmac_f32_e32 v11, v29, v19
	v_fmac_f32_e32 v12, v30, v19
	v_fmac_f32_e32 v13, v31, v19
	v_fmac_f32_e32 v129, v65, v19
	ds_write_b32 v133, v129 offset:10752
	ds_read_b128 v[24:27], v0 offset:4864
	ds_read_b128 v[42:45], v0 offset:6912
	ds_read_b128 v[58:61], v1 offset:8768
	v_add_f32_e32 v141, v141, v159
	v_add_f32_e32 v142, v142, v160
	v_add_f32_e32 v143, v143, v161
	v_add_f32_e32 v154, v154, v162
	v_add_f32_e32 v155, v155, v163
	v_add_f32_e32 v156, v156, v164
	v_add_f32_e32 v157, v157, v165
	v_add_f32_e32 v140, v140, v154
	v_add_f32_e32 v141, v141, v155
	v_add_f32_e32 v142, v142, v156
	v_add_f32_e32 v143, v143, v157
	v_add_f32_e32 v140, v140, v141
	v_add_f32_e32 v142, v142, v143
	v_add_f32_e32 v140, v140, v142
	v_cvt_pk_bf16_f32 v18, v140, v140
	ds_write_b16 v131, v18 offset:17792
	v_add_u32_e32 v131, 0x100, v131
	s_and_b32 s24, s12, 15
	s_cmp_eq_u32 s24, 0
	s_cbranch_scc0 .Lls3_16_noflush
	s_cmp_eq_u32 s12, 64
	s_cbranch_scc1 .Lls3_16_noflush
	s_waitcnt lgkmcnt(0)
	ds_read_b64 v[134:135], v132 offset:17664
	s_waitcnt lgkmcnt(0)
	global_store_dwordx2 v7, v[134:135], s[94:95]
	v_add_u32_e32 v7, 0x20000, v7
	s_nop 0
	ds_read_b64 v[134:135], v132 offset:18176
	s_waitcnt lgkmcnt(0)
	global_store_dwordx2 v7, v[134:135], s[94:95]
	v_add_u32_e32 v7, 0x20000, v7
	s_nop 0
	ds_read_b64 v[134:135], v132 offset:18688
	s_waitcnt lgkmcnt(0)
	global_store_dwordx2 v7, v[134:135], s[94:95]
	v_add_u32_e32 v7, 0x20000, v7
	s_nop 0
	ds_read_b64 v[134:135], v132 offset:19200
	s_waitcnt lgkmcnt(0)
	global_store_dwordx2 v7, v[134:135], s[94:95]
	v_add_u32_e32 v7, 0x20000, v7
	s_nop 0
	ds_read_b64 v[134:135], v132 offset:19712
	s_waitcnt lgkmcnt(0)
	global_store_dwordx2 v7, v[134:135], s[94:95]
	v_add_u32_e32 v7, 0x20000, v7
	s_nop 0
	ds_read_b64 v[134:135], v132 offset:20224
	s_waitcnt lgkmcnt(0)
	global_store_dwordx2 v7, v[134:135], s[94:95]
	v_add_u32_e32 v7, 0x20000, v7
	s_nop 0
	ds_read_b64 v[134:135], v132 offset:20736
	s_waitcnt lgkmcnt(0)
	global_store_dwordx2 v7, v[134:135], s[94:95]
	v_add_u32_e32 v7, 0x20000, v7
	s_nop 0
	ds_read_b64 v[134:135], v132 offset:21248
	s_waitcnt lgkmcnt(0)
	global_store_dwordx2 v7, v[134:135], s[94:95]
	v_add_u32_e32 v7, 0x20000, v7
	s_nop 0
	v_subrev_u32_e32 v131, 0x1000, v131
.Lls3_16_noflush:
	s_waitcnt lgkmcnt(12)
	v_mul_f32_e32 v36, v32, v10
	v_fmac_f32_e32 v36, v33, v11
	v_fmac_f32_e32 v36, v34, v12
	v_fmac_f32_e32 v36, v35, v13
	v_mul_f32_e32 v122, v50, v10
	v_fmac_f32_e32 v122, v51, v11
	v_add_f32_dpp v36, v36, v36 quad_perm:[1,0,3,2] row_mask:0xf bank_mask:0xf bound_ctrl:1
	v_fmac_f32_e32 v122, v52, v12
	v_fmac_f32_e32 v122, v53, v13
	v_add_f32_dpp v36, v36, v36 quad_perm:[2,3,0,1] row_mask:0xf bank_mask:0xf bound_ctrl:1
	v_mul_f32_e32 v10, v68, v10
	v_mul_f32_e32 v11, v68, v11
	v_add_f32_dpp v36, v36, v36 row_half_mirror row_mask:0xf bank_mask:0xf bound_ctrl:1
	v_mul_f32_e32 v12, v68, v12
	v_mul_f32_e32 v13, v68, v13
	v_add_f32_dpp v36, v36, v36 row_mirror row_mask:0xf bank_mask:0xf bound_ctrl:1
	v_mul_f32_e32 v129, v68, v122
	ds_read_b128 v[28:31], v0 offset:5120
	v_fma_f32 v128, -v68, v36, v66
	v_mul_f32_e32 v19, v67, v128
	ds_read_b128 v[46:49], v0 offset:7168
	v_fmac_f32_e32 v10, v32, v19
	v_fmac_f32_e32 v11, v33, v19
	v_fmac_f32_e32 v12, v34, v19
	v_fmac_f32_e32 v13, v35, v19
	v_fmac_f32_e32 v129, v69, v19
	ds_write_b32 v133, v129 offset:11008
	ds_read_b128 v[62:65], v1 offset:8832
	s_waitcnt lgkmcnt(9)
	v_mul_f32_e32 v36, v20, v10
	v_fmac_f32_e32 v36, v21, v11
	v_fmac_f32_e32 v36, v22, v12
	v_fmac_f32_e32 v36, v23, v13
	v_mul_f32_e32 v122, v38, v10
	v_fmac_f32_e32 v122, v39, v11
	v_add_f32_dpp v36, v36, v36 quad_perm:[1,0,3,2] row_mask:0xf bank_mask:0xf bound_ctrl:1
	v_fmac_f32_e32 v122, v40, v12
	v_fmac_f32_e32 v122, v41, v13
	v_add_f32_dpp v36, v36, v36 quad_perm:[2,3,0,1] row_mask:0xf bank_mask:0xf bound_ctrl:1
	v_mul_f32_e32 v10, v56, v10
	v_mul_f32_e32 v11, v56, v11
	v_add_f32_dpp v36, v36, v36 row_half_mirror row_mask:0xf bank_mask:0xf bound_ctrl:1
	v_mul_f32_e32 v12, v56, v12
	v_mul_f32_e32 v13, v56, v13
	v_add_f32_dpp v36, v36, v36 row_mirror row_mask:0xf bank_mask:0xf bound_ctrl:1
	v_mul_f32_e32 v129, v56, v122
	s_waitcnt vmcnt(14)
	v_fma_f32 v128, -v56, v36, v54
	v_mul_f32_e32 v19, v55, v128
	v_lshlrev_b32_e32 v118, 16, v98
	v_fmac_f32_e32 v10, v20, v19
	v_fmac_f32_e32 v11, v21, v19
	v_fmac_f32_e32 v12, v22, v19
	v_fmac_f32_e32 v13, v23, v19
	v_fmac_f32_e32 v129, v57, v19
	ds_write_b32 v133, v129 offset:11264
	ds_read_b128 v[32:35], v0 offset:5376
	ds_read_b128 v[50:53], v0 offset:7424
	ds_read_b128 v[66:69], v1 offset:8896
	v_and_b32_e32 v119, 0xffff0000, v98
	v_lshlrev_b32_e32 v120, 16, v99
	v_and_b32_e32 v121, 0xffff0000, v99
	ds_write_b128 v2, v[118:121] offset:0
	v_lshlrev_b32_e32 v124, 16, v100
	v_and_b32_e32 v125, 0xffff0000, v100
	s_waitcnt lgkmcnt(10)
	v_mul_f32_e32 v36, v24, v10
	v_fmac_f32_e32 v36, v25, v11
	v_fmac_f32_e32 v36, v26, v12
	v_fmac_f32_e32 v36, v27, v13
	v_mul_f32_e32 v122, v42, v10
	v_fmac_f32_e32 v122, v43, v11
	v_add_f32_dpp v36, v36, v36 quad_perm:[1,0,3,2] row_mask:0xf bank_mask:0xf bound_ctrl:1
	v_fmac_f32_e32 v122, v44, v12
	v_fmac_f32_e32 v122, v45, v13
	v_add_f32_dpp v36, v36, v36 quad_perm:[2,3,0,1] row_mask:0xf bank_mask:0xf bound_ctrl:1
	v_mul_f32_e32 v10, v60, v10
	v_mul_f32_e32 v11, v60, v11
	v_add_f32_dpp v36, v36, v36 row_half_mirror row_mask:0xf bank_mask:0xf bound_ctrl:1
	v_mul_f32_e32 v12, v60, v12
	v_mul_f32_e32 v13, v60, v13
	v_add_f32_dpp v36, v36, v36 row_mirror row_mask:0xf bank_mask:0xf bound_ctrl:1
	v_mul_f32_e32 v129, v60, v122
	v_lshlrev_b32_e32 v126, 16, v101
	v_fma_f32 v128, -v60, v36, v58
	v_mul_f32_e32 v19, v59, v128
	v_and_b32_e32 v127, 0xffff0000, v101
	v_fmac_f32_e32 v10, v24, v19
	v_fmac_f32_e32 v11, v25, v19
	v_fmac_f32_e32 v12, v26, v19
	v_fmac_f32_e32 v13, v27, v19
	v_fmac_f32_e32 v129, v61, v19
	ds_write_b32 v133, v129 offset:11520
	ds_read_b128 v[20:23], v0 offset:5632
	ds_read_b128 v[38:41], v0 offset:7680
	ds_read_b128 v[54:57], v1 offset:8960
	ds_write_b128 v2, v[124:127] offset:16
	v_lshlrev_b32_e32 v118, 16, v94
	v_and_b32_e32 v119, 0xffff0000, v94
	v_lshlrev_b32_e32 v120, 16, v95
	v_and_b32_e32 v121, 0xffff0000, v95
	ds_write_b128 v2, v[118:121] offset:2048
	s_waitcnt lgkmcnt(11)
	v_mul_f32_e32 v36, v28, v10
	v_fmac_f32_e32 v36, v29, v11
	v_fmac_f32_e32 v36, v30, v12
	v_fmac_f32_e32 v36, v31, v13
	v_mul_f32_e32 v122, v46, v10
	v_fmac_f32_e32 v122, v47, v11
	v_add_f32_dpp v36, v36, v36 quad_perm:[1,0,3,2] row_mask:0xf bank_mask:0xf bound_ctrl:1
	v_fmac_f32_e32 v122, v48, v12
	v_fmac_f32_e32 v122, v49, v13
	v_add_f32_dpp v36, v36, v36 quad_perm:[2,3,0,1] row_mask:0xf bank_mask:0xf bound_ctrl:1
	v_mul_f32_e32 v10, v64, v10
	v_mul_f32_e32 v11, v64, v11
	v_add_f32_dpp v36, v36, v36 row_half_mirror row_mask:0xf bank_mask:0xf bound_ctrl:1
	v_mul_f32_e32 v12, v64, v12
	v_mul_f32_e32 v13, v64, v13
	v_add_f32_dpp v36, v36, v36 row_mirror row_mask:0xf bank_mask:0xf bound_ctrl:1
	v_mul_f32_e32 v129, v64, v122
	v_lshlrev_b32_e32 v124, 16, v96
	v_fma_f32 v128, -v64, v36, v62
	v_mul_f32_e32 v19, v63, v128
	v_and_b32_e32 v125, 0xffff0000, v96
	v_fmac_f32_e32 v10, v28, v19
	v_fmac_f32_e32 v11, v29, v19
	v_fmac_f32_e32 v12, v30, v19
	v_fmac_f32_e32 v13, v31, v19
	v_fmac_f32_e32 v129, v65, v19
	ds_write_b32 v133, v129 offset:11776
	ds_read_b128 v[24:27], v0 offset:5888
	ds_read_b128 v[42:45], v0 offset:7936
	ds_read_b128 v[58:61], v1 offset:9024
	v_lshlrev_b32_e32 v126, 16, v97
	v_and_b32_e32 v127, 0xffff0000, v97
	ds_write_b128 v2, v[124:127] offset:2064
	s_waitcnt vmcnt(12)
	v_mov_b32_dpp v104, v103 quad_perm:[1,1,1,1] row_mask:0xf bank_mask:0xf
	v_mov_b32_dpp v105, v103 quad_perm:[2,2,2,2] row_mask:0xf bank_mask:0xf
	s_waitcnt lgkmcnt(12)
	v_mul_f32_e32 v36, v32, v10
	v_fmac_f32_e32 v36, v33, v11
	v_fmac_f32_e32 v36, v34, v12
	v_fmac_f32_e32 v36, v35, v13
	v_mul_f32_e32 v122, v50, v10
	v_fmac_f32_e32 v122, v51, v11
	v_add_f32_dpp v36, v36, v36 quad_perm:[1,0,3,2] row_mask:0xf bank_mask:0xf bound_ctrl:1
	v_fmac_f32_e32 v122, v52, v12
	v_fmac_f32_e32 v122, v53, v13
	v_add_f32_dpp v36, v36, v36 quad_perm:[2,3,0,1] row_mask:0xf bank_mask:0xf bound_ctrl:1
	v_mul_f32_e32 v10, v68, v10
	v_mul_f32_e32 v11, v68, v11
	v_add_f32_dpp v36, v36, v36 row_half_mirror row_mask:0xf bank_mask:0xf bound_ctrl:1
	v_mul_f32_e32 v12, v68, v12
	v_mul_f32_e32 v13, v68, v13
	v_add_f32_dpp v36, v36, v36 row_mirror row_mask:0xf bank_mask:0xf bound_ctrl:1
	v_mul_f32_e32 v129, v68, v122
	v_mov_b32_dpp v103, v103 quad_perm:[0,0,0,0] row_mask:0xf bank_mask:0xf
	v_fma_f32 v128, -v68, v36, v66
	v_mul_f32_e32 v19, v67, v128
	v_lshlrev_b32_e32 v102, 16, v102
	v_fmac_f32_e32 v10, v32, v19
	v_fmac_f32_e32 v11, v33, v19
	v_fmac_f32_e32 v12, v34, v19
	v_fmac_f32_e32 v13, v35, v19
	v_fmac_f32_e32 v129, v69, v19
	ds_write_b32 v133, v129 offset:12032
	ds_read_b128 v[28:31], v0 offset:6144
	ds_read_b128 v[46:49], v0 offset:8192
	ds_read_b128 v[62:65], v1 offset:9088
	v_mul_f32_e32 v105, 0x3d800000, v105
	s_nop 0
	ds_write_b128 v4, v[102:105] offset:4096
	s_waitcnt lgkmcnt(12)
	v_mul_f32_e32 v36, v20, v10
	v_fmac_f32_e32 v36, v21, v11
	v_fmac_f32_e32 v36, v22, v12
	v_fmac_f32_e32 v36, v23, v13
	v_mul_f32_e32 v122, v38, v10
	v_fmac_f32_e32 v122, v39, v11
	v_add_f32_dpp v36, v36, v36 quad_perm:[1,0,3,2] row_mask:0xf bank_mask:0xf bound_ctrl:1
	v_fmac_f32_e32 v122, v40, v12
	v_fmac_f32_e32 v122, v41, v13
	v_add_f32_dpp v36, v36, v36 quad_perm:[2,3,0,1] row_mask:0xf bank_mask:0xf bound_ctrl:1
	v_mul_f32_e32 v10, v56, v10
	v_mul_f32_e32 v11, v56, v11
	v_add_f32_dpp v36, v36, v36 row_half_mirror row_mask:0xf bank_mask:0xf bound_ctrl:1
	v_mul_f32_e32 v12, v56, v12
	v_mul_f32_e32 v13, v56, v13
	v_add_f32_dpp v36, v36, v36 row_mirror row_mask:0xf bank_mask:0xf bound_ctrl:1
	v_mul_f32_e32 v129, v56, v122
	global_load_dwordx4 v[94:97], v5, s[94:95]
	global_load_dwordx4 v[98:101], v5, s[94:95] offset:512
	global_load_ushort v102, v6, s[94:95]
	global_load_dword v103, v8, s[94:95]
	v_add_u32_e32 v5, 0x6800, v5
	v_add_u32_e32 v6, 0x6800, v6
	v_add_u32_e32 v8, 0x3180, v8
	v_fma_f32 v128, -v56, v36, v54
	v_mul_f32_e32 v19, v55, v128
	ds_read_b128 v[32:35], v0 offset:6400
	v_fmac_f32_e32 v10, v20, v19
	v_fmac_f32_e32 v11, v21, v19
	v_fmac_f32_e32 v12, v22, v19
	v_fmac_f32_e32 v13, v23, v19
	v_fmac_f32_e32 v129, v57, v19
	ds_write_b32 v133, v129 offset:12288
	ds_read_b128 v[50:53], v0 offset:8448
	ds_read_b128 v[66:69], v1 offset:9152
	s_waitcnt lgkmcnt(10)
	v_mul_f32_e32 v36, v24, v10
	v_fmac_f32_e32 v36, v25, v11
	v_fmac_f32_e32 v36, v26, v12
	v_fmac_f32_e32 v36, v27, v13
	v_mul_f32_e32 v122, v42, v10
	v_fmac_f32_e32 v122, v43, v11
	v_add_f32_dpp v36, v36, v36 quad_perm:[1,0,3,2] row_mask:0xf bank_mask:0xf bound_ctrl:1
	v_fmac_f32_e32 v122, v44, v12
	v_fmac_f32_e32 v122, v45, v13
	v_add_f32_dpp v36, v36, v36 quad_perm:[2,3,0,1] row_mask:0xf bank_mask:0xf bound_ctrl:1
	v_mul_f32_e32 v10, v60, v10
	v_mul_f32_e32 v11, v60, v11
	v_add_f32_dpp v36, v36, v36 row_half_mirror row_mask:0xf bank_mask:0xf bound_ctrl:1
	v_mul_f32_e32 v12, v60, v12
	v_mul_f32_e32 v13, v60, v13
	v_add_f32_dpp v36, v36, v36 row_mirror row_mask:0xf bank_mask:0xf bound_ctrl:1
	v_mul_f32_e32 v129, v60, v122
	ds_read_b128 v[20:23], v0 offset:0
	v_fma_f32 v128, -v60, v36, v58
	v_mul_f32_e32 v19, v59, v128
	ds_read_b128 v[38:41], v0 offset:2048
	v_fmac_f32_e32 v10, v24, v19
	v_fmac_f32_e32 v11, v25, v19
	v_fmac_f32_e32 v12, v26, v19
	v_fmac_f32_e32 v13, v27, v19
	v_fmac_f32_e32 v129, v61, v19
	ds_write_b32 v133, v129 offset:12544
	ds_read_b128 v[54:57], v1 offset:4096
	s_waitcnt lgkmcnt(9)
	v_mul_f32_e32 v36, v28, v10
	v_fmac_f32_e32 v36, v29, v11
	v_fmac_f32_e32 v36, v30, v12
	v_fmac_f32_e32 v36, v31, v13
	v_mul_f32_e32 v122, v46, v10
	v_fmac_f32_e32 v122, v47, v11
	v_add_f32_dpp v36, v36, v36 quad_perm:[1,0,3,2] row_mask:0xf bank_mask:0xf bound_ctrl:1
	v_fmac_f32_e32 v122, v48, v12
	v_fmac_f32_e32 v122, v49, v13
	v_add_f32_dpp v36, v36, v36 quad_perm:[2,3,0,1] row_mask:0xf bank_mask:0xf bound_ctrl:1
	v_mul_f32_e32 v10, v64, v10
	v_mul_f32_e32 v11, v64, v11
	v_add_f32_dpp v36, v36, v36 row_half_mirror row_mask:0xf bank_mask:0xf bound_ctrl:1
	v_mul_f32_e32 v12, v64, v12
	v_mul_f32_e32 v13, v64, v13
	v_add_f32_dpp v36, v36, v36 row_mirror row_mask:0xf bank_mask:0xf bound_ctrl:1
	v_mul_f32_e32 v129, v64, v122
	ds_read_b128 v[24:27], v0 offset:256
	v_fma_f32 v128, -v64, v36, v62
	v_mul_f32_e32 v19, v63, v128
	ds_read_b128 v[42:45], v0 offset:2304
	v_fmac_f32_e32 v10, v28, v19
	v_fmac_f32_e32 v11, v29, v19
	v_fmac_f32_e32 v12, v30, v19
	v_fmac_f32_e32 v13, v31, v19
	v_fmac_f32_e32 v129, v65, v19
	ds_write_b32 v133, v129 offset:12800
	ds_read_b128 v[58:61], v1 offset:4160
	s_waitcnt lgkmcnt(8)
	v_mul_f32_e32 v36, v32, v10
	v_fmac_f32_e32 v36, v33, v11
	v_fmac_f32_e32 v36, v34, v12
	v_fmac_f32_e32 v36, v35, v13
	v_mul_f32_e32 v122, v50, v10
	v_fmac_f32_e32 v122, v51, v11
	v_add_f32_dpp v36, v36, v36 quad_perm:[1,0,3,2] row_mask:0xf bank_mask:0xf bound_ctrl:1
	v_fmac_f32_e32 v122, v52, v12
	v_fmac_f32_e32 v122, v53, v13
	v_add_f32_dpp v36, v36, v36 quad_perm:[2,3,0,1] row_mask:0xf bank_mask:0xf bound_ctrl:1
	v_mul_f32_e32 v10, v68, v10
	v_mul_f32_e32 v11, v68, v11
	v_add_f32_dpp v36, v36, v36 row_half_mirror row_mask:0xf bank_mask:0xf bound_ctrl:1
	v_mul_f32_e32 v12, v68, v12
	v_mul_f32_e32 v13, v68, v13
	v_add_f32_dpp v36, v36, v36 row_mirror row_mask:0xf bank_mask:0xf bound_ctrl:1
	v_mul_f32_e32 v129, v68, v122
	ds_read_b128 v[28:31], v0 offset:512
	v_fma_f32 v128, -v68, v36, v66
	v_mul_f32_e32 v19, v67, v128
	ds_read_b128 v[46:49], v0 offset:2560
	v_fmac_f32_e32 v10, v32, v19
	v_fmac_f32_e32 v11, v33, v19
	v_fmac_f32_e32 v12, v34, v19
	v_fmac_f32_e32 v13, v35, v19
	v_fmac_f32_e32 v129, v69, v19
	ds_write_b32 v133, v129 offset:13056
	ds_read_b128 v[62:65], v1 offset:4224
	s_waitcnt lgkmcnt(8)
	v_mul_f32_e32 v36, v20, v10
	v_fmac_f32_e32 v36, v21, v11
	v_fmac_f32_e32 v36, v22, v12
	v_fmac_f32_e32 v36, v23, v13
	v_mul_f32_e32 v122, v38, v10
	v_fmac_f32_e32 v122, v39, v11
	v_add_f32_dpp v36, v36, v36 quad_perm:[1,0,3,2] row_mask:0xf bank_mask:0xf bound_ctrl:1
	v_fmac_f32_e32 v122, v40, v12
	v_fmac_f32_e32 v122, v41, v13
	v_add_f32_dpp v36, v36, v36 quad_perm:[2,3,0,1] row_mask:0xf bank_mask:0xf bound_ctrl:1
	v_mul_f32_e32 v10, v56, v10
	v_mul_f32_e32 v11, v56, v11
	v_add_f32_dpp v36, v36, v36 row_half_mirror row_mask:0xf bank_mask:0xf bound_ctrl:1
	v_mul_f32_e32 v12, v56, v12
	v_mul_f32_e32 v13, v56, v13
	v_add_f32_dpp v36, v36, v36 row_mirror row_mask:0xf bank_mask:0xf bound_ctrl:1
	v_mul_f32_e32 v129, v56, v122
	s_waitcnt vmcnt(14)
	v_fma_f32 v128, -v56, v36, v54
	v_mul_f32_e32 v19, v55, v128
	v_lshlrev_b32_e32 v118, 16, v110
	v_fmac_f32_e32 v10, v20, v19
	v_fmac_f32_e32 v11, v21, v19
	v_fmac_f32_e32 v12, v22, v19
	v_fmac_f32_e32 v13, v23, v19
	v_fmac_f32_e32 v129, v57, v19
	ds_write_b32 v133, v129 offset:13312
	ds_read_b128 v[32:35], v0 offset:768
	ds_read_b128 v[50:53], v0 offset:2816
	ds_read_b128 v[66:69], v1 offset:4288
	v_and_b32_e32 v119, 0xffff0000, v110
	v_lshlrev_b32_e32 v120, 16, v111
	v_and_b32_e32 v121, 0xffff0000, v111
	ds_write_b128 v2, v[118:121] offset:4608
	v_lshlrev_b32_e32 v124, 16, v112
	v_and_b32_e32 v125, 0xffff0000, v112
	s_waitcnt lgkmcnt(9)
	v_mul_f32_e32 v36, v24, v10
	v_fmac_f32_e32 v36, v25, v11
	v_fmac_f32_e32 v36, v26, v12
	v_fmac_f32_e32 v36, v27, v13
	v_mul_f32_e32 v122, v42, v10
	v_fmac_f32_e32 v122, v43, v11
	v_add_f32_dpp v36, v36, v36 quad_perm:[1,0,3,2] row_mask:0xf bank_mask:0xf bound_ctrl:1
	v_fmac_f32_e32 v122, v44, v12
	v_fmac_f32_e32 v122, v45, v13
	v_add_f32_dpp v36, v36, v36 quad_perm:[2,3,0,1] row_mask:0xf bank_mask:0xf bound_ctrl:1
	v_mul_f32_e32 v10, v60, v10
	v_mul_f32_e32 v11, v60, v11
	v_add_f32_dpp v36, v36, v36 row_half_mirror row_mask:0xf bank_mask:0xf bound_ctrl:1
	v_mul_f32_e32 v12, v60, v12
	v_mul_f32_e32 v13, v60, v13
	v_add_f32_dpp v36, v36, v36 row_mirror row_mask:0xf bank_mask:0xf bound_ctrl:1
	v_mul_f32_e32 v129, v60, v122
	v_lshlrev_b32_e32 v126, 16, v113
	v_fma_f32 v128, -v60, v36, v58
	v_mul_f32_e32 v19, v59, v128
	v_and_b32_e32 v127, 0xffff0000, v113
	v_fmac_f32_e32 v10, v24, v19
	v_fmac_f32_e32 v11, v25, v19
	v_fmac_f32_e32 v12, v26, v19
	v_fmac_f32_e32 v13, v27, v19
	v_fmac_f32_e32 v129, v61, v19
	ds_write_b32 v133, v129 offset:13568
	ds_read_b128 v[20:23], v0 offset:1024
	ds_read_b128 v[38:41], v0 offset:3072
	ds_read_b128 v[54:57], v1 offset:4352
	ds_write_b128 v2, v[124:127] offset:4624
	v_lshlrev_b32_e32 v118, 16, v106
	v_and_b32_e32 v119, 0xffff0000, v106
	v_lshlrev_b32_e32 v120, 16, v107
	v_and_b32_e32 v121, 0xffff0000, v107
	ds_write_b128 v2, v[118:121] offset:6656
	s_waitcnt lgkmcnt(11)
	v_mul_f32_e32 v36, v28, v10
	v_fmac_f32_e32 v36, v29, v11
	v_fmac_f32_e32 v36, v30, v12
	v_fmac_f32_e32 v36, v31, v13
	v_mul_f32_e32 v122, v46, v10
	v_fmac_f32_e32 v122, v47, v11
	v_add_f32_dpp v36, v36, v36 quad_perm:[1,0,3,2] row_mask:0xf bank_mask:0xf bound_ctrl:1
	v_fmac_f32_e32 v122, v48, v12
	v_fmac_f32_e32 v122, v49, v13
	v_add_f32_dpp v36, v36, v36 quad_perm:[2,3,0,1] row_mask:0xf bank_mask:0xf bound_ctrl:1
	v_mul_f32_e32 v10, v64, v10
	v_mul_f32_e32 v11, v64, v11
	v_add_f32_dpp v36, v36, v36 row_half_mirror row_mask:0xf bank_mask:0xf bound_ctrl:1
	v_mul_f32_e32 v12, v64, v12
	v_mul_f32_e32 v13, v64, v13
	v_add_f32_dpp v36, v36, v36 row_mirror row_mask:0xf bank_mask:0xf bound_ctrl:1
	v_mul_f32_e32 v129, v64, v122
	v_lshlrev_b32_e32 v124, 16, v108
	v_fma_f32 v128, -v64, v36, v62
	v_mul_f32_e32 v19, v63, v128
	v_and_b32_e32 v125, 0xffff0000, v108
	v_fmac_f32_e32 v10, v28, v19
	v_fmac_f32_e32 v11, v29, v19
	v_fmac_f32_e32 v12, v30, v19
	v_fmac_f32_e32 v13, v31, v19
	v_fmac_f32_e32 v129, v65, v19
	ds_write_b32 v133, v129 offset:13824
	ds_read_b128 v[24:27], v0 offset:1280
	ds_read_b128 v[42:45], v0 offset:3328
	ds_read_b128 v[58:61], v1 offset:4416
	v_lshlrev_b32_e32 v126, 16, v109
	v_and_b32_e32 v127, 0xffff0000, v109
	ds_write_b128 v2, v[124:127] offset:6672
	s_waitcnt vmcnt(12)
	v_mov_b32_dpp v116, v115 quad_perm:[1,1,1,1] row_mask:0xf bank_mask:0xf
	v_mov_b32_dpp v117, v115 quad_perm:[2,2,2,2] row_mask:0xf bank_mask:0xf
	s_waitcnt lgkmcnt(12)
	v_mul_f32_e32 v36, v32, v10
	v_fmac_f32_e32 v36, v33, v11
	v_fmac_f32_e32 v36, v34, v12
	v_fmac_f32_e32 v36, v35, v13
	v_mul_f32_e32 v122, v50, v10
	v_fmac_f32_e32 v122, v51, v11
	v_add_f32_dpp v36, v36, v36 quad_perm:[1,0,3,2] row_mask:0xf bank_mask:0xf bound_ctrl:1
	v_fmac_f32_e32 v122, v52, v12
	v_fmac_f32_e32 v122, v53, v13
	v_add_f32_dpp v36, v36, v36 quad_perm:[2,3,0,1] row_mask:0xf bank_mask:0xf bound_ctrl:1
	v_mul_f32_e32 v10, v68, v10
	v_mul_f32_e32 v11, v68, v11
	v_add_f32_dpp v36, v36, v36 row_half_mirror row_mask:0xf bank_mask:0xf bound_ctrl:1
	v_mul_f32_e32 v12, v68, v12
	v_mul_f32_e32 v13, v68, v13
	v_add_f32_dpp v36, v36, v36 row_mirror row_mask:0xf bank_mask:0xf bound_ctrl:1
	v_mul_f32_e32 v129, v68, v122
	v_mov_b32_dpp v115, v115 quad_perm:[0,0,0,0] row_mask:0xf bank_mask:0xf
	v_fma_f32 v128, -v68, v36, v66
	v_mul_f32_e32 v19, v67, v128
	v_lshlrev_b32_e32 v114, 16, v114
	v_fmac_f32_e32 v10, v32, v19
	v_fmac_f32_e32 v11, v33, v19
	v_fmac_f32_e32 v12, v34, v19
	v_fmac_f32_e32 v13, v35, v19
	v_fmac_f32_e32 v129, v69, v19
	ds_write_b32 v133, v129 offset:14080
	ds_read_b128 v[28:31], v0 offset:1536
	ds_read_b128 v[46:49], v0 offset:3584
	ds_read_b128 v[62:65], v1 offset:4480
	v_mul_f32_e32 v117, 0x3d800000, v117
	s_nop 0
	ds_write_b128 v4, v[114:117] offset:8704
	s_waitcnt lgkmcnt(12)
	v_mul_f32_e32 v36, v20, v10
	v_fmac_f32_e32 v36, v21, v11
	v_fmac_f32_e32 v36, v22, v12
	v_fmac_f32_e32 v36, v23, v13
	v_mul_f32_e32 v122, v38, v10
	v_fmac_f32_e32 v122, v39, v11
	v_add_f32_dpp v36, v36, v36 quad_perm:[1,0,3,2] row_mask:0xf bank_mask:0xf bound_ctrl:1
	v_fmac_f32_e32 v122, v40, v12
	v_fmac_f32_e32 v122, v41, v13
	v_add_f32_dpp v36, v36, v36 quad_perm:[2,3,0,1] row_mask:0xf bank_mask:0xf bound_ctrl:1
	v_mul_f32_e32 v10, v56, v10
	v_mul_f32_e32 v11, v56, v11
	v_add_f32_dpp v36, v36, v36 row_half_mirror row_mask:0xf bank_mask:0xf bound_ctrl:1
	v_mul_f32_e32 v12, v56, v12
	v_mul_f32_e32 v13, v56, v13
	v_add_f32_dpp v36, v36, v36 row_mirror row_mask:0xf bank_mask:0xf bound_ctrl:1
	v_mul_f32_e32 v129, v56, v122
	global_load_dwordx4 v[106:109], v5, s[94:95]
	global_load_dwordx4 v[110:113], v5, s[94:95] offset:512
	global_load_ushort v114, v6, s[94:95]
	global_load_dword v115, v8, s[94:95]
	v_add_u32_e32 v5, 0x6800, v5
	v_add_u32_e32 v6, 0x6800, v6
	v_add_u32_e32 v8, 0x3180, v8
	v_fma_f32 v128, -v56, v36, v54
	v_mul_f32_e32 v19, v55, v128
	ds_read_b128 v[140:143], v136 offset:9216
	v_fmac_f32_e32 v10, v20, v19
	v_fmac_f32_e32 v11, v21, v19
	v_fmac_f32_e32 v12, v22, v19
	v_fmac_f32_e32 v13, v23, v19
	v_fmac_f32_e32 v129, v57, v19
	ds_write_b32 v133, v129 offset:14336
	ds_read_b128 v[32:35], v0 offset:1792
	ds_read_b128 v[50:53], v0 offset:3840
	ds_read_b128 v[66:69], v1 offset:4544
	ds_read_b128 v[154:157], v137 offset:9216
	ds_read_b128 v[158:161], v138 offset:9216
	ds_read_b128 v[162:165], v139 offset:9216
	s_waitcnt lgkmcnt(14)
	v_mul_f32_e32 v36, v24, v10
	v_fmac_f32_e32 v36, v25, v11
	v_fmac_f32_e32 v36, v26, v12
	v_fmac_f32_e32 v36, v27, v13
	v_mul_f32_e32 v122, v42, v10
	v_fmac_f32_e32 v122, v43, v11
	v_add_f32_dpp v36, v36, v36 quad_perm:[1,0,3,2] row_mask:0xf bank_mask:0xf bound_ctrl:1
	v_fmac_f32_e32 v122, v44, v12
	v_fmac_f32_e32 v122, v45, v13
	v_add_f32_dpp v36, v36, v36 quad_perm:[2,3,0,1] row_mask:0xf bank_mask:0xf bound_ctrl:1
	v_mul_f32_e32 v10, v60, v10
	v_mul_f32_e32 v11, v60, v11
	v_add_f32_dpp v36, v36, v36 row_half_mirror row_mask:0xf bank_mask:0xf bound_ctrl:1
	v_mul_f32_e32 v12, v60, v12
	v_mul_f32_e32 v13, v60, v13
	v_add_f32_dpp v36, v36, v36 row_mirror row_mask:0xf bank_mask:0xf bound_ctrl:1
	v_mul_f32_e32 v129, v60, v122
	ds_read_b128 v[20:23], v0 offset:4608
	v_fma_f32 v128, -v60, v36, v58
	v_mul_f32_e32 v19, v59, v128
	ds_read_b128 v[38:41], v0 offset:6656
	v_fmac_f32_e32 v10, v24, v19
	v_fmac_f32_e32 v11, v25, v19
	v_fmac_f32_e32 v12, v26, v19
	v_fmac_f32_e32 v13, v27, v19
	v_fmac_f32_e32 v129, v61, v19
	ds_write_b32 v133, v129 offset:14592
	ds_read_b128 v[54:57], v1 offset:8704
	s_waitcnt lgkmcnt(13)
	v_mul_f32_e32 v36, v28, v10
	v_fmac_f32_e32 v36, v29, v11
	v_fmac_f32_e32 v36, v30, v12
	v_fmac_f32_e32 v36, v31, v13
	v_mul_f32_e32 v122, v46, v10
	v_fmac_f32_e32 v122, v47, v11
	v_add_f32_dpp v36, v36, v36 quad_perm:[1,0,3,2] row_mask:0xf bank_mask:0xf bound_ctrl:1
	v_fmac_f32_e32 v122, v48, v12
	v_fmac_f32_e32 v122, v49, v13
	v_add_f32_dpp v36, v36, v36 quad_perm:[2,3,0,1] row_mask:0xf bank_mask:0xf bound_ctrl:1
	v_mul_f32_e32 v10, v64, v10
	v_mul_f32_e32 v11, v64, v11
	v_add_f32_dpp v36, v36, v36 row_half_mirror row_mask:0xf bank_mask:0xf bound_ctrl:1
	v_mul_f32_e32 v12, v64, v12
	v_mul_f32_e32 v13, v64, v13
	v_add_f32_dpp v36, v36, v36 row_mirror row_mask:0xf bank_mask:0xf bound_ctrl:1
	v_mul_f32_e32 v129, v64, v122
	s_waitcnt lgkmcnt(4)
	v_fma_f32 v128, -v64, v36, v62
	v_mul_f32_e32 v19, v63, v128
	v_add_f32_e32 v140, v140, v158
	v_fmac_f32_e32 v10, v28, v19
	v_fmac_f32_e32 v11, v29, v19
	v_fmac_f32_e32 v12, v30, v19
	v_fmac_f32_e32 v13, v31, v19
	v_fmac_f32_e32 v129, v65, v19
	ds_write_b32 v133, v129 offset:14848
	ds_read_b128 v[24:27], v0 offset:4864
	ds_read_b128 v[42:45], v0 offset:6912
	ds_read_b128 v[58:61], v1 offset:8768
	v_add_f32_e32 v141, v141, v159
	v_add_f32_e32 v142, v142, v160
	v_add_f32_e32 v143, v143, v161
	v_add_f32_e32 v154, v154, v162
	v_add_f32_e32 v155, v155, v163
	v_add_f32_e32 v156, v156, v164
	v_add_f32_e32 v157, v157, v165
	v_add_f32_e32 v140, v140, v154
	v_add_f32_e32 v141, v141, v155
	v_add_f32_e32 v142, v142, v156
	v_add_f32_e32 v143, v143, v157
	v_add_f32_e32 v140, v140, v141
	v_add_f32_e32 v142, v142, v143
	v_add_f32_e32 v140, v140, v142
	v_cvt_pk_bf16_f32 v18, v140, v140
	ds_write_b16 v131, v18 offset:17664
	s_waitcnt lgkmcnt(12)
	v_mul_f32_e32 v36, v32, v10
	v_fmac_f32_e32 v36, v33, v11
	v_fmac_f32_e32 v36, v34, v12
	v_fmac_f32_e32 v36, v35, v13
	v_mul_f32_e32 v122, v50, v10
	v_fmac_f32_e32 v122, v51, v11
	v_add_f32_dpp v36, v36, v36 quad_perm:[1,0,3,2] row_mask:0xf bank_mask:0xf bound_ctrl:1
	v_fmac_f32_e32 v122, v52, v12
	v_fmac_f32_e32 v122, v53, v13
	v_add_f32_dpp v36, v36, v36 quad_perm:[2,3,0,1] row_mask:0xf bank_mask:0xf bound_ctrl:1
	v_mul_f32_e32 v10, v68, v10
	v_mul_f32_e32 v11, v68, v11
	v_add_f32_dpp v36, v36, v36 row_half_mirror row_mask:0xf bank_mask:0xf bound_ctrl:1
	v_mul_f32_e32 v12, v68, v12
	v_mul_f32_e32 v13, v68, v13
	v_add_f32_dpp v36, v36, v36 row_mirror row_mask:0xf bank_mask:0xf bound_ctrl:1
	v_mul_f32_e32 v129, v68, v122
	ds_read_b128 v[28:31], v0 offset:5120
	v_fma_f32 v128, -v68, v36, v66
	v_mul_f32_e32 v19, v67, v128
	ds_read_b128 v[46:49], v0 offset:7168
	v_fmac_f32_e32 v10, v32, v19
	v_fmac_f32_e32 v11, v33, v19
	v_fmac_f32_e32 v12, v34, v19
	v_fmac_f32_e32 v13, v35, v19
	v_fmac_f32_e32 v129, v69, v19
	ds_write_b32 v133, v129 offset:15104
	ds_read_b128 v[62:65], v1 offset:8832
	s_waitcnt lgkmcnt(9)
	v_mul_f32_e32 v36, v20, v10
	v_fmac_f32_e32 v36, v21, v11
	v_fmac_f32_e32 v36, v22, v12
	v_fmac_f32_e32 v36, v23, v13
	v_mul_f32_e32 v122, v38, v10
	v_fmac_f32_e32 v122, v39, v11
	v_add_f32_dpp v36, v36, v36 quad_perm:[1,0,3,2] row_mask:0xf bank_mask:0xf bound_ctrl:1
	v_fmac_f32_e32 v122, v40, v12
	v_fmac_f32_e32 v122, v41, v13
	v_add_f32_dpp v36, v36, v36 quad_perm:[2,3,0,1] row_mask:0xf bank_mask:0xf bound_ctrl:1
	v_mul_f32_e32 v10, v56, v10
	v_mul_f32_e32 v11, v56, v11
	v_add_f32_dpp v36, v36, v36 row_half_mirror row_mask:0xf bank_mask:0xf bound_ctrl:1
	v_mul_f32_e32 v12, v56, v12
	v_mul_f32_e32 v13, v56, v13
	v_add_f32_dpp v36, v36, v36 row_mirror row_mask:0xf bank_mask:0xf bound_ctrl:1
	v_mul_f32_e32 v129, v56, v122
	s_waitcnt vmcnt(14)
	v_fma_f32 v128, -v56, v36, v54
	v_mul_f32_e32 v19, v55, v128
	v_lshlrev_b32_e32 v118, 16, v74
	v_fmac_f32_e32 v10, v20, v19
	v_fmac_f32_e32 v11, v21, v19
	v_fmac_f32_e32 v12, v22, v19
	v_fmac_f32_e32 v13, v23, v19
	v_fmac_f32_e32 v129, v57, v19
	ds_write_b32 v133, v129 offset:15360
	ds_read_b128 v[32:35], v0 offset:5376
	ds_read_b128 v[50:53], v0 offset:7424
	ds_read_b128 v[66:69], v1 offset:8896
	v_and_b32_e32 v119, 0xffff0000, v74
	v_lshlrev_b32_e32 v120, 16, v75
	v_and_b32_e32 v121, 0xffff0000, v75
	ds_write_b128 v2, v[118:121] offset:0
	v_lshlrev_b32_e32 v124, 16, v76
	v_and_b32_e32 v125, 0xffff0000, v76
	s_waitcnt lgkmcnt(10)
	v_mul_f32_e32 v36, v24, v10
	v_fmac_f32_e32 v36, v25, v11
	v_fmac_f32_e32 v36, v26, v12
	v_fmac_f32_e32 v36, v27, v13
	v_mul_f32_e32 v122, v42, v10
	v_fmac_f32_e32 v122, v43, v11
	v_add_f32_dpp v36, v36, v36 quad_perm:[1,0,3,2] row_mask:0xf bank_mask:0xf bound_ctrl:1
	v_fmac_f32_e32 v122, v44, v12
	v_fmac_f32_e32 v122, v45, v13
	v_add_f32_dpp v36, v36, v36 quad_perm:[2,3,0,1] row_mask:0xf bank_mask:0xf bound_ctrl:1
	v_mul_f32_e32 v10, v60, v10
	v_mul_f32_e32 v11, v60, v11
	v_add_f32_dpp v36, v36, v36 row_half_mirror row_mask:0xf bank_mask:0xf bound_ctrl:1
	v_mul_f32_e32 v12, v60, v12
	v_mul_f32_e32 v13, v60, v13
	v_add_f32_dpp v36, v36, v36 row_mirror row_mask:0xf bank_mask:0xf bound_ctrl:1
	v_mul_f32_e32 v129, v60, v122
	v_lshlrev_b32_e32 v126, 16, v77
	v_fma_f32 v128, -v60, v36, v58
	v_mul_f32_e32 v19, v59, v128
	v_and_b32_e32 v127, 0xffff0000, v77
	v_fmac_f32_e32 v10, v24, v19
	v_fmac_f32_e32 v11, v25, v19
	v_fmac_f32_e32 v12, v26, v19
	v_fmac_f32_e32 v13, v27, v19
	v_fmac_f32_e32 v129, v61, v19
	ds_write_b32 v133, v129 offset:15616
	ds_read_b128 v[20:23], v0 offset:5632
	ds_read_b128 v[38:41], v0 offset:7680
	ds_read_b128 v[54:57], v1 offset:8960
	ds_write_b128 v2, v[124:127] offset:16
	v_lshlrev_b32_e32 v118, 16, v70
	v_and_b32_e32 v119, 0xffff0000, v70
	v_lshlrev_b32_e32 v120, 16, v71
	v_and_b32_e32 v121, 0xffff0000, v71
	ds_write_b128 v2, v[118:121] offset:2048
	s_waitcnt lgkmcnt(11)
	v_mul_f32_e32 v36, v28, v10
	v_fmac_f32_e32 v36, v29, v11
	v_fmac_f32_e32 v36, v30, v12
	v_fmac_f32_e32 v36, v31, v13
	v_mul_f32_e32 v122, v46, v10
	v_fmac_f32_e32 v122, v47, v11
	v_add_f32_dpp v36, v36, v36 quad_perm:[1,0,3,2] row_mask:0xf bank_mask:0xf bound_ctrl:1
	v_fmac_f32_e32 v122, v48, v12
	v_fmac_f32_e32 v122, v49, v13
	v_add_f32_dpp v36, v36, v36 quad_perm:[2,3,0,1] row_mask:0xf bank_mask:0xf bound_ctrl:1
	v_mul_f32_e32 v10, v64, v10
	v_mul_f32_e32 v11, v64, v11
	v_add_f32_dpp v36, v36, v36 row_half_mirror row_mask:0xf bank_mask:0xf bound_ctrl:1
	v_mul_f32_e32 v12, v64, v12
	v_mul_f32_e32 v13, v64, v13
	v_add_f32_dpp v36, v36, v36 row_mirror row_mask:0xf bank_mask:0xf bound_ctrl:1
	v_mul_f32_e32 v129, v64, v122
	v_lshlrev_b32_e32 v124, 16, v72
	v_fma_f32 v128, -v64, v36, v62
	v_mul_f32_e32 v19, v63, v128
	v_and_b32_e32 v125, 0xffff0000, v72
	v_fmac_f32_e32 v10, v28, v19
	v_fmac_f32_e32 v11, v29, v19
	v_fmac_f32_e32 v12, v30, v19
	v_fmac_f32_e32 v13, v31, v19
	v_fmac_f32_e32 v129, v65, v19
	ds_write_b32 v133, v129 offset:15872
	ds_read_b128 v[24:27], v0 offset:5888
	ds_read_b128 v[42:45], v0 offset:7936
	ds_read_b128 v[58:61], v1 offset:9024
	v_lshlrev_b32_e32 v126, 16, v73
	v_and_b32_e32 v127, 0xffff0000, v73
	ds_write_b128 v2, v[124:127] offset:2064
	s_waitcnt vmcnt(12)
	v_mov_b32_dpp v80, v79 quad_perm:[1,1,1,1] row_mask:0xf bank_mask:0xf
	v_mov_b32_dpp v81, v79 quad_perm:[2,2,2,2] row_mask:0xf bank_mask:0xf
	s_waitcnt lgkmcnt(12)
	v_mul_f32_e32 v36, v32, v10
	v_fmac_f32_e32 v36, v33, v11
	v_fmac_f32_e32 v36, v34, v12
	v_fmac_f32_e32 v36, v35, v13
	v_mul_f32_e32 v122, v50, v10
	v_fmac_f32_e32 v122, v51, v11
	v_add_f32_dpp v36, v36, v36 quad_perm:[1,0,3,2] row_mask:0xf bank_mask:0xf bound_ctrl:1
	v_fmac_f32_e32 v122, v52, v12
	v_fmac_f32_e32 v122, v53, v13
	v_add_f32_dpp v36, v36, v36 quad_perm:[2,3,0,1] row_mask:0xf bank_mask:0xf bound_ctrl:1
	v_mul_f32_e32 v10, v68, v10
	v_mul_f32_e32 v11, v68, v11
	v_add_f32_dpp v36, v36, v36 row_half_mirror row_mask:0xf bank_mask:0xf bound_ctrl:1
	v_mul_f32_e32 v12, v68, v12
	v_mul_f32_e32 v13, v68, v13
	v_add_f32_dpp v36, v36, v36 row_mirror row_mask:0xf bank_mask:0xf bound_ctrl:1
	v_mul_f32_e32 v129, v68, v122
	v_mov_b32_dpp v79, v79 quad_perm:[0,0,0,0] row_mask:0xf bank_mask:0xf
	v_fma_f32 v128, -v68, v36, v66
	v_mul_f32_e32 v19, v67, v128
	v_lshlrev_b32_e32 v78, 16, v78
	v_fmac_f32_e32 v10, v32, v19
	v_fmac_f32_e32 v11, v33, v19
	v_fmac_f32_e32 v12, v34, v19
	v_fmac_f32_e32 v13, v35, v19
	v_fmac_f32_e32 v129, v69, v19
	ds_write_b32 v133, v129 offset:16128
	ds_read_b128 v[28:31], v0 offset:6144
	ds_read_b128 v[46:49], v0 offset:8192
	ds_read_b128 v[62:65], v1 offset:9088
	v_mul_f32_e32 v81, 0x3d800000, v81
	s_nop 0
	ds_write_b128 v4, v[78:81] offset:4096
	s_waitcnt lgkmcnt(12)
	v_mul_f32_e32 v36, v20, v10
	v_fmac_f32_e32 v36, v21, v11
	v_fmac_f32_e32 v36, v22, v12
	v_fmac_f32_e32 v36, v23, v13
	v_mul_f32_e32 v122, v38, v10
	v_fmac_f32_e32 v122, v39, v11
	v_add_f32_dpp v36, v36, v36 quad_perm:[1,0,3,2] row_mask:0xf bank_mask:0xf bound_ctrl:1
	v_fmac_f32_e32 v122, v40, v12
	v_fmac_f32_e32 v122, v41, v13
	v_add_f32_dpp v36, v36, v36 quad_perm:[2,3,0,1] row_mask:0xf bank_mask:0xf bound_ctrl:1
	v_mul_f32_e32 v10, v56, v10
	v_mul_f32_e32 v11, v56, v11
	v_add_f32_dpp v36, v36, v36 row_half_mirror row_mask:0xf bank_mask:0xf bound_ctrl:1
	v_mul_f32_e32 v12, v56, v12
	v_mul_f32_e32 v13, v56, v13
	v_add_f32_dpp v36, v36, v36 row_mirror row_mask:0xf bank_mask:0xf bound_ctrl:1
	v_mul_f32_e32 v129, v56, v122
	global_load_dwordx4 v[70:73], v5, s[94:95]
	global_load_dwordx4 v[74:77], v5, s[94:95] offset:512
	global_load_ushort v78, v6, s[94:95]
	global_load_dword v79, v8, s[94:95]
	v_add_u32_e32 v5, 0x6800, v5
	v_add_u32_e32 v6, 0x6800, v6
	v_add_u32_e32 v8, 0x3180, v8
	v_fma_f32 v128, -v56, v36, v54
	v_mul_f32_e32 v19, v55, v128
	ds_read_b128 v[32:35], v0 offset:6400
	v_fmac_f32_e32 v10, v20, v19
	v_fmac_f32_e32 v11, v21, v19
	v_fmac_f32_e32 v12, v22, v19
	v_fmac_f32_e32 v13, v23, v19
	v_fmac_f32_e32 v129, v57, v19
	ds_write_b32 v133, v129 offset:16384
	ds_read_b128 v[50:53], v0 offset:8448
	ds_read_b128 v[66:69], v1 offset:9152
	s_waitcnt lgkmcnt(10)
	v_mul_f32_e32 v36, v24, v10
	v_fmac_f32_e32 v36, v25, v11
	v_fmac_f32_e32 v36, v26, v12
	v_fmac_f32_e32 v36, v27, v13
	v_mul_f32_e32 v122, v42, v10
	v_fmac_f32_e32 v122, v43, v11
	v_add_f32_dpp v36, v36, v36 quad_perm:[1,0,3,2] row_mask:0xf bank_mask:0xf bound_ctrl:1
	v_fmac_f32_e32 v122, v44, v12
	v_fmac_f32_e32 v122, v45, v13
	v_add_f32_dpp v36, v36, v36 quad_perm:[2,3,0,1] row_mask:0xf bank_mask:0xf bound_ctrl:1
	v_mul_f32_e32 v10, v60, v10
	v_mul_f32_e32 v11, v60, v11
	v_add_f32_dpp v36, v36, v36 row_half_mirror row_mask:0xf bank_mask:0xf bound_ctrl:1
	v_mul_f32_e32 v12, v60, v12
	v_mul_f32_e32 v13, v60, v13
	v_add_f32_dpp v36, v36, v36 row_mirror row_mask:0xf bank_mask:0xf bound_ctrl:1
	v_mul_f32_e32 v129, v60, v122
	ds_read_b128 v[20:23], v0 offset:0
	v_fma_f32 v128, -v60, v36, v58
	v_mul_f32_e32 v19, v59, v128
	ds_read_b128 v[38:41], v0 offset:2048
	v_fmac_f32_e32 v10, v24, v19
	v_fmac_f32_e32 v11, v25, v19
	v_fmac_f32_e32 v12, v26, v19
	v_fmac_f32_e32 v13, v27, v19
	v_fmac_f32_e32 v129, v61, v19
	ds_write_b32 v133, v129 offset:16640
	ds_read_b128 v[54:57], v1 offset:4096
	s_waitcnt lgkmcnt(9)
	v_mul_f32_e32 v36, v28, v10
	v_fmac_f32_e32 v36, v29, v11
	v_fmac_f32_e32 v36, v30, v12
	v_fmac_f32_e32 v36, v31, v13
	v_mul_f32_e32 v122, v46, v10
	v_fmac_f32_e32 v122, v47, v11
	v_add_f32_dpp v36, v36, v36 quad_perm:[1,0,3,2] row_mask:0xf bank_mask:0xf bound_ctrl:1
	v_fmac_f32_e32 v122, v48, v12
	v_fmac_f32_e32 v122, v49, v13
	v_add_f32_dpp v36, v36, v36 quad_perm:[2,3,0,1] row_mask:0xf bank_mask:0xf bound_ctrl:1
	v_mul_f32_e32 v10, v64, v10
	v_mul_f32_e32 v11, v64, v11
	v_add_f32_dpp v36, v36, v36 row_half_mirror row_mask:0xf bank_mask:0xf bound_ctrl:1
	v_mul_f32_e32 v12, v64, v12
	v_mul_f32_e32 v13, v64, v13
	v_add_f32_dpp v36, v36, v36 row_mirror row_mask:0xf bank_mask:0xf bound_ctrl:1
	v_mul_f32_e32 v129, v64, v122
	ds_read_b128 v[24:27], v0 offset:256
	v_fma_f32 v128, -v64, v36, v62
	v_mul_f32_e32 v19, v63, v128
	ds_read_b128 v[42:45], v0 offset:2304
	v_fmac_f32_e32 v10, v28, v19
	v_fmac_f32_e32 v11, v29, v19
	v_fmac_f32_e32 v12, v30, v19
	v_fmac_f32_e32 v13, v31, v19
	v_fmac_f32_e32 v129, v65, v19
	ds_write_b32 v133, v129 offset:16896
	ds_read_b128 v[58:61], v1 offset:4160
	s_waitcnt lgkmcnt(8)
	v_mul_f32_e32 v36, v32, v10
	v_fmac_f32_e32 v36, v33, v11
	v_fmac_f32_e32 v36, v34, v12
	v_fmac_f32_e32 v36, v35, v13
	v_mul_f32_e32 v122, v50, v10
	v_fmac_f32_e32 v122, v51, v11
	v_add_f32_dpp v36, v36, v36 quad_perm:[1,0,3,2] row_mask:0xf bank_mask:0xf bound_ctrl:1
	v_fmac_f32_e32 v122, v52, v12
	v_fmac_f32_e32 v122, v53, v13
	v_add_f32_dpp v36, v36, v36 quad_perm:[2,3,0,1] row_mask:0xf bank_mask:0xf bound_ctrl:1
	v_mul_f32_e32 v10, v68, v10
	v_mul_f32_e32 v11, v68, v11
	v_add_f32_dpp v36, v36, v36 row_half_mirror row_mask:0xf bank_mask:0xf bound_ctrl:1
	v_mul_f32_e32 v12, v68, v12
	v_mul_f32_e32 v13, v68, v13
	v_add_f32_dpp v36, v36, v36 row_mirror row_mask:0xf bank_mask:0xf bound_ctrl:1
	v_mul_f32_e32 v129, v68, v122
	ds_read_b128 v[28:31], v0 offset:512
	v_fma_f32 v128, -v68, v36, v66
	v_mul_f32_e32 v19, v67, v128
	ds_read_b128 v[46:49], v0 offset:2560
	v_fmac_f32_e32 v10, v32, v19
	v_fmac_f32_e32 v11, v33, v19
	v_fmac_f32_e32 v12, v34, v19
	v_fmac_f32_e32 v13, v35, v19
	v_fmac_f32_e32 v129, v69, v19
	ds_write_b32 v133, v129 offset:17152
	ds_read_b128 v[62:65], v1 offset:4224
	s_sub_u32 s12, s12, 1
	s_cmp_lg_u32 s12, 0
	s_cbranch_scc1 .Lls3_16_loop
	ds_read_b128 v[140:143], v136 offset:13312
	ds_read_b128 v[154:157], v137 offset:13312
	ds_read_b128 v[158:161], v138 offset:13312
	ds_read_b128 v[162:165], v139 offset:13312
	s_waitcnt lgkmcnt(0)
	v_add_f32_e32 v140, v140, v158
	v_add_f32_e32 v141, v141, v159
	v_add_f32_e32 v142, v142, v160
	v_add_f32_e32 v143, v143, v161
	v_add_f32_e32 v154, v154, v162
	v_add_f32_e32 v155, v155, v163
	v_add_f32_e32 v156, v156, v164
	v_add_f32_e32 v157, v157, v165
	v_add_f32_e32 v140, v140, v154
	v_add_f32_e32 v141, v141, v155
	v_add_f32_e32 v142, v142, v156
	v_add_f32_e32 v143, v143, v157
	v_add_f32_e32 v140, v140, v141
	v_add_f32_e32 v142, v142, v143
	v_add_f32_e32 v140, v140, v142
	v_cvt_pk_bf16_f32 v18, v140, v140
	ds_write_b16 v131, v18 offset:17792
	s_waitcnt lgkmcnt(0)
	ds_read_b64 v[134:135], v132 offset:17664
	s_waitcnt lgkmcnt(0)
	global_store_dwordx2 v7, v[134:135], s[94:95]
	v_add_u32_e32 v7, 0x20000, v7
	s_nop 0
	ds_read_b64 v[134:135], v132 offset:18176
	s_waitcnt lgkmcnt(0)
	global_store_dwordx2 v7, v[134:135], s[94:95]
	v_add_u32_e32 v7, 0x20000, v7
	s_nop 0
	ds_read_b64 v[134:135], v132 offset:18688
	s_waitcnt lgkmcnt(0)
	global_store_dwordx2 v7, v[134:135], s[94:95]
	v_add_u32_e32 v7, 0x20000, v7
	s_nop 0
	ds_read_b64 v[134:135], v132 offset:19200
	s_waitcnt lgkmcnt(0)
	global_store_dwordx2 v7, v[134:135], s[94:95]
	v_add_u32_e32 v7, 0x20000, v7
	s_nop 0
	ds_read_b64 v[134:135], v132 offset:19712
	s_waitcnt lgkmcnt(0)
	global_store_dwordx2 v7, v[134:135], s[94:95]
	v_add_u32_e32 v7, 0x20000, v7
	s_nop 0
	ds_read_b64 v[134:135], v132 offset:20224
	s_waitcnt lgkmcnt(0)
	global_store_dwordx2 v7, v[134:135], s[94:95]
	v_add_u32_e32 v7, 0x20000, v7
	s_nop 0
	ds_read_b64 v[134:135], v132 offset:20736
	s_waitcnt lgkmcnt(0)
	global_store_dwordx2 v7, v[134:135], s[94:95]
	v_add_u32_e32 v7, 0x20000, v7
	s_nop 0
	ds_read_b64 v[134:135], v132 offset:21248
	s_waitcnt lgkmcnt(0)
	global_store_dwordx2 v7, v[134:135], s[94:95]
	v_add_u32_e32 v7, 0x20000, v7
	s_nop 0
	global_store_dword v130, v10, s[26:27] offset:0
	global_store_dword v130, v11, s[26:27] offset:256
	global_store_dword v130, v12, s[26:27] offset:512
	global_store_dword v130, v13, s[26:27] offset:768
	s_waitcnt vmcnt(0) lgkmcnt(0)
	s_setprio 0
	s_branch .Lls_done
.Lls0_8_entry:
	v_and_b32_e32 v98, 63, v196
	v_and_b32_e32 v99, 7, v98
	v_lshrrev_b32_e32 v100, 3, v98
	s_min_u32 s29, s0, 4
	s_mul_i32 s29, s29, 0x5600
	v_and_b32_e32 v101, 3, v99
	v_cmp_eq_u32_e64 s[6:7], 1, v101
	v_cmp_eq_u32_e64 s[8:9], 2, v101
	v_cmp_eq_u32_e64 s[10:11], 3, v101
	v_lshl_add_u32 v0, v99, 5, s29
	v_lshl_add_u32 v1, v100, 2, s29
	s_lshl_b32 s37, s16, 11
	v_lshrrev_b32_e32 v99, 3, v98
	v_and_b32_e32 v100, 7, v98
	v_add_u32_e32 v101, s37, v99
	s_lshl_b32 s21, s17, 7
	s_add_u32 s21, s21, 0x10800000
	v_mul_u32_u24_e32 v5, 0xd00, v101
	v_lshl_add_u32 v5, v100, 4, v5
	v_add_u32_e32 v5, s21, v5
	v_lshlrev_b32_e32 v2, 8, v99
	v_lshl_add_u32 v2, v100, 5, v2
	v_add_u32_e32 v2, s29, v2
	v_lshrrev_b32_e32 v100, 3, v98
	v_and_b32_e32 v99, 7, v98
	v_add_u32_e32 v101, s37, v100
	s_lshl_b32 s22, s14, 3
	s_lshl_b32 s21, s17, 6
	s_add_u32 s21, s21, s22
	s_lshl_b32 s44, s21, 1
	s_add_u32 s44, s44, 0x8400400
	v_lshlrev_b32_e32 v6, 13, v101
	v_lshlrev_b32_e32 v4, 5, v100
	v_lshl_add_u32 v4, v99, 2, v4
	v_lshl_add_u32 v6, v99, 1, v6
	v_add_u32_e32 v6, s44, v6
	v_add_u32_e32 v4, s29, v4
	v_and_b32_e32 v99, 7, v98
	v_lshrrev_b32_e32 v100, 3, v98
	v_add_u32_e32 v101, s37, v98
	v_lshlrev_b32_e32 v7, 11, v101
	s_lshl_b32 s44, s21, 1
	s_add_u32 s44, s44, 0x6300000
	v_add_u32_e32 v7, s44, v7
	s_lshl_b32 s44, s28, 3
	s_add_u32 s44, s44, s16
	s_lshl_b32 s44, s44, 2
	s_add_u32 s44, s44, s17
	s_mul_i32 s44, s44, 0x4000
	s_add_u32 s44, s44, 0x4200000
	s_lshl_b32 s24, s22, 2
	s_add_u32 s44, s44, s24
	v_lshlrev_b32_e32 v111, 11, v99
	v_lshl_add_u32 v111, v100, 2, v111
	v_add_u32_e32 v111, s44, v111
	v_readlane_b32 s26, v253, 29
	v_readlane_b32 s27, v253, 30
	v_lshlrev_b32_e32 v112, 4, v99
	v_lshl_add_u32 v112, v100, 1, v112
	v_add_u32_e32 v112, s29, v112
	v_lshl_add_u32 v113, v98, 4, s29
	v_lshl_add_u32 v118, v98, 2, s29
	v_lshl_add_u32 v112, v98, 1, s29
	v_subrev_u32_e32 v112, 0x200, v112
	v_lshrrev_b32_e32 v99, 3, v98
	v_and_b32_e32 v100, 7, v98
	v_lshlrev_b32_e32 v101, 8, v99
	v_lshl_add_u32 v101, v100, 5, v101
	v_add_u32_e32 v101, s29, v101
	v_bfe_u32 v99, v99, 1, 1
	v_xor_b32_e32 v100, 0, v99
	v_lshl_add_u32 v119, v100, 4, v101
	v_xor_b32_e32 v100, 1, v99
	v_lshl_add_u32 v120, v100, 4, v101
	s_lshr_b32 s44, 0x80000, s17
	s_sub_u32 s44, 0x3f800000, s44
	s_mov_b32 s45, s44
	v_mov_b32_e32 v98, s45
	v_log_f32_e32 v98, v98
	v_lshrrev_b32_e32 v99, 3, v196
	v_and_b32_e32 v99, 7, v99
	v_add_u32_e32 v100, 1, v99
	v_cvt_f32_u32_e32 v100, v100
	v_mul_f32_e32 v100, v98, v100
	v_exp_f32_e32 v107, v100
	v_sub_f32_e32 v101, 0, v100
	v_exp_f32_e32 v103, v101
	v_add_u32_e32 v100, 9, v99
	v_cvt_f32_u32_e32 v100, v100
	v_mul_f32_e32 v100, v98, v100
	v_exp_f32_e32 v108, v100
	v_sub_f32_e32 v101, 0, v100
	v_exp_f32_e32 v104, v101
	v_add_u32_e32 v100, 17, v99
	v_cvt_f32_u32_e32 v100, v100
	v_mul_f32_e32 v100, v98, v100
	v_exp_f32_e32 v109, v100
	v_sub_f32_e32 v101, 0, v100
	v_exp_f32_e32 v105, v101
	v_add_u32_e32 v100, 25, v99
	v_cvt_f32_u32_e32 v100, v100
	v_mul_f32_e32 v100, v98, v100
	v_exp_f32_e32 v110, v100
	v_sub_f32_e32 v101, 0, v100
	v_exp_f32_e32 v106, v101
	v_mul_f32_e32 v100, 0x42000000, v98
	v_exp_f32_e32 v100, v100
	s_nop 1
	v_readfirstlane_b32 s44, v100
	v_mov_b32_e32 v8, 0
	v_mov_b32_e32 v9, 0
	v_mov_b32_e32 v10, 0
	v_mov_b32_e32 v11, 0
	v_mov_b32_e32 v12, 0
	v_mov_b32_e32 v13, 0
	v_mov_b32_e32 v14, 0
	v_mov_b32_e32 v15, 0
	v_mov_b32_e32 v16, 0
	v_mov_b32_e32 v17, 0
	v_mov_b32_e32 v18, 0
	v_mov_b32_e32 v19, 0
	v_mov_b32_e32 v36, 0
	v_mov_b32_e32 v102, 0
	s_setprio 2
	s_movk_i32 s12, 64
	s_nop 0
	global_load_dwordx4 v[62:65], v5, s[94:95]
	global_load_dwordx4 v[66:69], v5, s[94:95] offset:512
	global_load_ushort v31, v6, s[94:95]
	v_add_u32_e32 v5, 0x6800, v5
	v_add_u32_e32 v6, 0x10000, v6
	s_waitcnt vmcnt(0)
	s_waitcnt vmcnt(1)
	v_lshlrev_b32_e32 v94, 16, v66
	v_and_b32_e32 v95, 0xffff0000, v66
	v_lshlrev_b32_e32 v96, 16, v67
	v_and_b32_e32 v97, 0xffff0000, v67
	v_mul_f32_e32 v94, v103, v94
	v_mul_f32_e32 v95, v103, v95
	v_mul_f32_e32 v96, v103, v96
	v_mul_f32_e32 v97, v103, v97
	ds_write_b128 v2, v[94:97] offset:0
	v_lshlrev_b32_e32 v98, 16, v68
	v_and_b32_e32 v99, 0xffff0000, v68
	v_lshlrev_b32_e32 v100, 16, v69
	v_and_b32_e32 v101, 0xffff0000, v69
	v_mul_f32_e32 v98, v103, v98
	v_mul_f32_e32 v99, v103, v99
	v_mul_f32_e32 v100, v103, v100
	v_mul_f32_e32 v101, v103, v101
	ds_write_b128 v2, v[98:101] offset:16
	v_lshlrev_b32_e32 v94, 16, v62
	v_and_b32_e32 v95, 0xffff0000, v62
	v_lshlrev_b32_e32 v96, 16, v63
	v_and_b32_e32 v97, 0xffff0000, v63
	v_mul_f32_e32 v94, v107, v94
	v_mul_f32_e32 v95, v107, v95
	v_mul_f32_e32 v96, v107, v96
	v_mul_f32_e32 v97, v107, v97
	ds_write_b128 v2, v[94:97] offset:2048
	v_lshlrev_b32_e32 v98, 16, v64
	v_and_b32_e32 v99, 0xffff0000, v64
	v_lshlrev_b32_e32 v100, 16, v65
	v_and_b32_e32 v101, 0xffff0000, v65
	v_mul_f32_e32 v98, v107, v98
	v_mul_f32_e32 v99, v107, v99
	v_mul_f32_e32 v100, v107, v100
	v_mul_f32_e32 v101, v107, v101
	ds_write_b128 v2, v[98:101] offset:2064
	s_waitcnt vmcnt(0)
	v_lshlrev_b32_e32 v31, 16, v31
	s_nop 0
	ds_write_b32 v4, v31 offset:4096
	global_load_dwordx4 v[70:73], v5, s[94:95]
	global_load_dwordx4 v[74:77], v5, s[94:95] offset:512
	global_load_ushort v33, v6, s[94:95]
	v_add_u32_e32 v5, 0x6800, v5
	v_add_u32_e32 v6, 0x10000, v6
	global_load_dwordx4 v[78:81], v5, s[94:95]
	global_load_dwordx4 v[82:85], v5, s[94:95] offset:512
	global_load_ushort v34, v6, s[94:95]
	v_add_u32_e32 v5, 0x6800, v5
	v_add_u32_e32 v6, 0x10000, v6
	global_load_dwordx4 v[86:89], v5, s[94:95]
	global_load_dwordx4 v[90:93], v5, s[94:95] offset:512
	global_load_ushort v35, v6, s[94:95]
	v_add_u32_e32 v5, 0x6800, v5
	v_add_u32_e32 v6, 0x10000, v6
	global_load_dwordx4 v[62:65], v5, s[94:95]
	global_load_dwordx4 v[66:69], v5, s[94:95] offset:512
	global_load_ushort v31, v6, s[94:95]
	v_add_u32_e32 v5, 0x6800, v5
	v_add_u32_e32 v6, 0x10000, v6
	ds_read_b128 v[22:25], v0 offset:0
	ds_read_b128 v[26:29], v0 offset:16
	ds_read_b128 v[46:49], v0 offset:2048
	ds_read_b128 v[50:53], v0 offset:2064
	ds_read_b32 v30, v1 offset:4096
.Lls0_8_loop:
	s_waitcnt lgkmcnt(0)
	ds_read_b128 v[38:41], v0 offset:256
	ds_read_b128 v[42:45], v0 offset:272
	ds_read_b128 v[54:57], v0 offset:2304
	ds_read_b128 v[58:61], v0 offset:2320
	ds_read_b32 v32, v1 offset:4128
	v_fmac_f32_e32 v8, v22, v30
	v_fmac_f32_e32 v9, v23, v30
	v_mul_f32_e32 v36, v46, v8
	s_waitcnt vmcnt(10)
	v_fmac_f32_e32 v10, v24, v30
	v_fmac_f32_e32 v36, v47, v9
	v_fmac_f32_e32 v11, v25, v30
	v_lshlrev_b32_e32 v94, 16, v74
	v_fmac_f32_e32 v36, v48, v10
	v_fmac_f32_e32 v12, v26, v30
	v_fmac_f32_e32 v36, v49, v11
	v_and_b32_e32 v95, 0xffff0000, v74
	v_fmac_f32_e32 v13, v27, v30
	v_fmac_f32_e32 v36, v50, v12
	v_fmac_f32_e32 v14, v28, v30
	v_lshlrev_b32_e32 v96, 16, v75
	v_fmac_f32_e32 v36, v51, v13
	v_fmac_f32_e32 v15, v29, v30
	v_fmac_f32_e32 v36, v52, v14
	v_and_b32_e32 v97, 0xffff0000, v75
	v_fmac_f32_e32 v36, v53, v15
	ds_write_b32 v118, v36 offset:8704
	v_mul_f32_e32 v94, v104, v94
	v_mul_f32_e32 v95, v104, v95
	v_mul_f32_e32 v96, v104, v96
	v_mul_f32_e32 v97, v104, v97
	ds_write_b128 v2, v[94:97] offset:4352
	v_lshlrev_b32_e32 v98, 16, v76
	s_waitcnt lgkmcnt(2)
	ds_read_b128 v[22:25], v0 offset:512
	ds_read_b128 v[26:29], v0 offset:528
	ds_read_b128 v[46:49], v0 offset:2560
	ds_read_b128 v[50:53], v0 offset:2576
	ds_read_b32 v30, v1 offset:4160
	v_fmac_f32_e32 v8, v38, v32
	v_fmac_f32_e32 v9, v39, v32
	v_mul_f32_e32 v102, v54, v8
	v_and_b32_e32 v99, 0xffff0000, v76
	v_fmac_f32_e32 v10, v40, v32
	v_fmac_f32_e32 v102, v55, v9
	v_fmac_f32_e32 v11, v41, v32
	v_lshlrev_b32_e32 v100, 16, v77
	v_fmac_f32_e32 v102, v56, v10
	v_fmac_f32_e32 v12, v42, v32
	v_fmac_f32_e32 v102, v57, v11
	v_and_b32_e32 v101, 0xffff0000, v77
	v_fmac_f32_e32 v13, v43, v32
	v_fmac_f32_e32 v102, v58, v12
	v_fmac_f32_e32 v14, v44, v32
	v_mul_f32_e32 v98, v104, v98
	v_fmac_f32_e32 v102, v59, v13
	v_fmac_f32_e32 v15, v45, v32
	v_fmac_f32_e32 v102, v60, v14
	v_mul_f32_e32 v99, v104, v99
	v_fmac_f32_e32 v102, v61, v15
	ds_write_b32 v118, v102 offset:8960
	v_mul_f32_e32 v100, v104, v100
	v_mul_f32_e32 v101, v104, v101
	ds_write_b128 v2, v[98:101] offset:4368
	v_lshlrev_b32_e32 v94, 16, v70
	v_and_b32_e32 v95, 0xffff0000, v70
	v_lshlrev_b32_e32 v96, 16, v71
	s_waitcnt lgkmcnt(2)
	ds_read_b128 v[38:41], v0 offset:768
	ds_read_b128 v[42:45], v0 offset:784
	ds_read_b128 v[54:57], v0 offset:2816
	ds_read_b128 v[58:61], v0 offset:2832
	ds_read_b32 v32, v1 offset:4192
	v_fmac_f32_e32 v8, v22, v30
	v_fmac_f32_e32 v9, v23, v30
	v_mul_f32_e32 v36, v46, v8
	v_and_b32_e32 v97, 0xffff0000, v71
	v_fmac_f32_e32 v10, v24, v30
	v_fmac_f32_e32 v36, v47, v9
	v_fmac_f32_e32 v11, v25, v30
	v_mul_f32_e32 v94, v108, v94
	v_fmac_f32_e32 v36, v48, v10
	v_fmac_f32_e32 v12, v26, v30
	v_fmac_f32_e32 v36, v49, v11
	v_mul_f32_e32 v95, v108, v95
	v_fmac_f32_e32 v13, v27, v30
	v_fmac_f32_e32 v36, v50, v12
	v_fmac_f32_e32 v14, v28, v30
	v_mul_f32_e32 v96, v108, v96
	v_fmac_f32_e32 v36, v51, v13
	v_fmac_f32_e32 v15, v29, v30
	v_fmac_f32_e32 v36, v52, v14
	v_mul_f32_e32 v97, v108, v97
	v_fmac_f32_e32 v36, v53, v15
	ds_write_b32 v118, v36 offset:9216
	ds_write_b128 v2, v[94:97] offset:6400
	v_lshlrev_b32_e32 v98, 16, v72
	v_and_b32_e32 v99, 0xffff0000, v72
	v_lshlrev_b32_e32 v100, 16, v73
	v_and_b32_e32 v101, 0xffff0000, v73
	v_mul_f32_e32 v98, v108, v98
	s_waitcnt lgkmcnt(2)
	ds_read_b128 v[22:25], v0 offset:1024
	ds_read_b128 v[26:29], v0 offset:1040
	ds_read_b128 v[46:49], v0 offset:3072
	ds_read_b128 v[50:53], v0 offset:3088
	ds_read_b32 v30, v1 offset:4224
	v_fmac_f32_e32 v8, v38, v32
	v_fmac_f32_e32 v9, v39, v32
	v_mul_f32_e32 v102, v54, v8
	v_mul_f32_e32 v99, v108, v99
	v_fmac_f32_e32 v10, v40, v32
	v_fmac_f32_e32 v102, v55, v9
	v_fmac_f32_e32 v11, v41, v32
	v_mul_f32_e32 v100, v108, v100
	v_fmac_f32_e32 v102, v56, v10
	v_fmac_f32_e32 v12, v42, v32
	v_fmac_f32_e32 v102, v57, v11
	v_mul_f32_e32 v101, v108, v101
	v_fmac_f32_e32 v13, v43, v32
	v_fmac_f32_e32 v102, v58, v12
	v_fmac_f32_e32 v14, v44, v32
	ds_write_b128 v2, v[98:101] offset:6416
	v_fmac_f32_e32 v102, v59, v13
	v_fmac_f32_e32 v15, v45, v32
	v_fmac_f32_e32 v102, v60, v14
	s_waitcnt vmcnt(9)
	v_fmac_f32_e32 v102, v61, v15
	ds_write_b32 v118, v102 offset:9472
	v_lshlrev_b32_e32 v33, 16, v33
	s_nop 0
	ds_write_b32 v4, v33 offset:8448
	s_waitcnt lgkmcnt(3)
	ds_read_b128 v[38:41], v0 offset:1280
	ds_read_b128 v[42:45], v0 offset:1296
	ds_read_b128 v[54:57], v0 offset:3328
	ds_read_b128 v[58:61], v0 offset:3344
	ds_read_b32 v32, v1 offset:4256
	v_fmac_f32_e32 v8, v22, v30
	v_fmac_f32_e32 v9, v23, v30
	v_mul_f32_e32 v36, v46, v8
	global_load_dwordx4 v[70:73], v5, s[94:95]
	global_load_dwordx4 v[74:77], v5, s[94:95] offset:512
	global_load_ushort v33, v6, s[94:95]
	v_add_u32_e32 v5, 0x6800, v5
	v_add_u32_e32 v6, 0x10000, v6
	v_fmac_f32_e32 v10, v24, v30
	v_fmac_f32_e32 v36, v47, v9
	v_fmac_f32_e32 v11, v25, v30
	ds_read_b128 v[124:127], v119 offset:10752
	v_fmac_f32_e32 v36, v48, v10
	v_fmac_f32_e32 v12, v26, v30
	v_fmac_f32_e32 v36, v49, v11
	ds_read_b128 v[128:131], v120 offset:10752
	v_fmac_f32_e32 v13, v27, v30
	v_fmac_f32_e32 v36, v50, v12
	v_fmac_f32_e32 v14, v28, v30
	v_fmac_f32_e32 v36, v51, v13
	v_fmac_f32_e32 v15, v29, v30
	v_fmac_f32_e32 v36, v52, v14
	v_fmac_f32_e32 v36, v53, v15
	ds_write_b32 v118, v36 offset:9728
	s_waitcnt lgkmcnt(3)
	ds_read_b128 v[22:25], v0 offset:1536
	ds_read_b128 v[26:29], v0 offset:1552
	ds_read_b128 v[46:49], v0 offset:3584
	ds_read_b128 v[50:53], v0 offset:3600
	ds_read_b32 v30, v1 offset:4288
	v_fmac_f32_e32 v8, v38, v32
	v_fmac_f32_e32 v9, v39, v32
	v_mul_f32_e32 v102, v54, v8
	v_fmac_f32_e32 v10, v40, v32
	v_fmac_f32_e32 v102, v55, v9
	v_fmac_f32_e32 v11, v41, v32
	v_fmac_f32_e32 v102, v56, v10
	v_fmac_f32_e32 v12, v42, v32
	v_fmac_f32_e32 v102, v57, v11
	v_fmac_f32_e32 v13, v43, v32
	v_fmac_f32_e32 v102, v58, v12
	v_fmac_f32_e32 v14, v44, v32
	v_fmac_f32_e32 v102, v59, v13
	v_fmac_f32_e32 v15, v45, v32
	v_fmac_f32_e32 v102, v60, v14
	v_fmac_f32_e32 v102, v61, v15
	ds_write_b32 v118, v102 offset:9984
	s_waitcnt lgkmcnt(1)
	ds_read_b128 v[38:41], v0 offset:1792
	ds_read_b128 v[42:45], v0 offset:1808
	ds_read_b128 v[54:57], v0 offset:3840
	ds_read_b128 v[58:61], v0 offset:3856
	ds_read_b32 v32, v1 offset:4320
	v_fmac_f32_e32 v8, v22, v30
	v_fmac_f32_e32 v9, v23, v30
	v_mul_f32_e32 v36, v46, v8
	s_waitcnt lgkmcnt(12)
	v_fmac_f32_e32 v10, v24, v30
	v_fmac_f32_e32 v36, v47, v9
	v_fmac_f32_e32 v11, v25, v30
	v_add_f32_e32 v124, v124, v128
	v_fmac_f32_e32 v36, v48, v10
	v_fmac_f32_e32 v12, v26, v30
	v_fmac_f32_e32 v36, v49, v11
	v_add_f32_e32 v125, v125, v129
	v_fmac_f32_e32 v13, v27, v30
	v_fmac_f32_e32 v36, v50, v12
	v_fmac_f32_e32 v14, v28, v30
	v_add_f32_e32 v126, v126, v130
	v_fmac_f32_e32 v36, v51, v13
	v_fmac_f32_e32 v15, v29, v30
	v_fmac_f32_e32 v36, v52, v14
	v_add_f32_e32 v127, v127, v131
	v_fmac_f32_e32 v36, v53, v15
	ds_write_b32 v118, v36 offset:10240
	v_add_f32_e32 v124, v124, v125
	v_add_f32_e32 v126, v126, v127
	v_add_f32_e32 v124, v124, v126
	v_cvt_pk_bf16_f32 v21, v124, v124
	ds_write_b16 v112, v21 offset:13696
	v_add_u32_e32 v112, 0x200, v112
	s_and_b32 s24, s12, 15
	s_cmp_eq_u32 s24, 0
	s_cbranch_scc0 .Lls0_8_noflush
	s_cmp_eq_u32 s12, 64
	s_cbranch_scc1 .Lls0_8_noflush
	s_waitcnt lgkmcnt(0)
	ds_read_b128 v[114:117], v113 offset:13312
	s_waitcnt lgkmcnt(0)
	global_store_dwordx4 v7, v[114:117], s[94:95]
	v_add_u32_e32 v7, 0x20000, v7
	s_nop 0
	ds_read_b128 v[114:117], v113 offset:14336
	s_waitcnt lgkmcnt(0)
	global_store_dwordx4 v7, v[114:117], s[94:95]
	v_add_u32_e32 v7, 0x20000, v7
	s_nop 0
	ds_read_b128 v[114:117], v113 offset:15360
	s_waitcnt lgkmcnt(0)
	global_store_dwordx4 v7, v[114:117], s[94:95]
	v_add_u32_e32 v7, 0x20000, v7
	s_nop 0
	ds_read_b128 v[114:117], v113 offset:16384
	s_waitcnt lgkmcnt(0)
	global_store_dwordx4 v7, v[114:117], s[94:95]
	v_add_u32_e32 v7, 0x20000, v7
	s_nop 0
	ds_read_b128 v[114:117], v113 offset:17408
	s_waitcnt lgkmcnt(0)
	global_store_dwordx4 v7, v[114:117], s[94:95]
	v_add_u32_e32 v7, 0x20000, v7
	s_nop 0
	ds_read_b128 v[114:117], v113 offset:18432
	s_waitcnt lgkmcnt(0)
	global_store_dwordx4 v7, v[114:117], s[94:95]
	v_add_u32_e32 v7, 0x20000, v7
	s_nop 0
	ds_read_b128 v[114:117], v113 offset:19456
	s_waitcnt lgkmcnt(0)
	global_store_dwordx4 v7, v[114:117], s[94:95]
	v_add_u32_e32 v7, 0x20000, v7
	s_nop 0
	ds_read_b128 v[114:117], v113 offset:20480
	s_waitcnt lgkmcnt(0)
	global_store_dwordx4 v7, v[114:117], s[94:95]
	v_add_u32_e32 v7, 0x20000, v7
	s_nop 0
	v_subrev_u32_e32 v112, 0x2000, v112
.Lls0_8_noflush:
	s_waitcnt lgkmcnt(2)
	ds_read_b128 v[22:25], v0 offset:4352
	ds_read_b128 v[26:29], v0 offset:4368
	ds_read_b128 v[46:49], v0 offset:6400
	ds_read_b128 v[50:53], v0 offset:6416
	ds_read_b32 v30, v1 offset:8448
	v_fmac_f32_e32 v8, v38, v32
	v_fmac_f32_e32 v9, v39, v32
	v_mul_f32_e32 v102, v54, v8
	v_fmac_f32_e32 v10, v40, v32
	v_fmac_f32_e32 v102, v55, v9
	v_fmac_f32_e32 v11, v41, v32
	v_fmac_f32_e32 v102, v56, v10
	v_fmac_f32_e32 v12, v42, v32
	v_fmac_f32_e32 v102, v57, v11
	v_fmac_f32_e32 v13, v43, v32
	v_fmac_f32_e32 v102, v58, v12
	v_fmac_f32_e32 v14, v44, v32
	v_fmac_f32_e32 v102, v59, v13
	v_fmac_f32_e32 v15, v45, v32
	v_fmac_f32_e32 v102, v60, v14
	v_fmac_f32_e32 v102, v61, v15
	ds_write_b32 v118, v102 offset:10496
	s_waitcnt lgkmcnt(1)
	ds_read_b128 v[38:41], v0 offset:4608
	ds_read_b128 v[42:45], v0 offset:4624
	ds_read_b128 v[54:57], v0 offset:6656
	ds_read_b128 v[58:61], v0 offset:6672
	ds_read_b32 v32, v1 offset:8480
	v_fmac_f32_e32 v8, v22, v30
	v_fmac_f32_e32 v9, v23, v30
	v_mul_f32_e32 v36, v46, v8
	s_waitcnt vmcnt(10)
	v_fmac_f32_e32 v10, v24, v30
	v_fmac_f32_e32 v36, v47, v9
	v_fmac_f32_e32 v11, v25, v30
	v_lshlrev_b32_e32 v94, 16, v82
	v_fmac_f32_e32 v36, v48, v10
	v_fmac_f32_e32 v12, v26, v30
	v_fmac_f32_e32 v36, v49, v11
	v_and_b32_e32 v95, 0xffff0000, v82
	v_fmac_f32_e32 v13, v27, v30
	v_fmac_f32_e32 v36, v50, v12
	v_fmac_f32_e32 v14, v28, v30
	v_lshlrev_b32_e32 v96, 16, v83
	v_fmac_f32_e32 v36, v51, v13
	v_fmac_f32_e32 v15, v29, v30
	v_fmac_f32_e32 v36, v52, v14
	v_and_b32_e32 v97, 0xffff0000, v83
	v_fmac_f32_e32 v36, v53, v15
	ds_write_b32 v118, v36 offset:10752
	v_mul_f32_e32 v94, v105, v94
	v_mul_f32_e32 v95, v105, v95
	v_mul_f32_e32 v96, v105, v96
	v_mul_f32_e32 v97, v105, v97
	ds_write_b128 v2, v[94:97] offset:0
	v_lshlrev_b32_e32 v98, 16, v84
	s_waitcnt lgkmcnt(2)
	ds_read_b128 v[22:25], v0 offset:4864
	ds_read_b128 v[26:29], v0 offset:4880
	ds_read_b128 v[46:49], v0 offset:6912
	ds_read_b128 v[50:53], v0 offset:6928
	ds_read_b32 v30, v1 offset:8512
	v_fmac_f32_e32 v8, v38, v32
	v_fmac_f32_e32 v9, v39, v32
	v_mul_f32_e32 v102, v54, v8
	v_and_b32_e32 v99, 0xffff0000, v84
	v_fmac_f32_e32 v10, v40, v32
	v_fmac_f32_e32 v102, v55, v9
	v_fmac_f32_e32 v11, v41, v32
	v_lshlrev_b32_e32 v100, 16, v85
	v_fmac_f32_e32 v102, v56, v10
	v_fmac_f32_e32 v12, v42, v32
	v_fmac_f32_e32 v102, v57, v11
	v_and_b32_e32 v101, 0xffff0000, v85
	v_fmac_f32_e32 v13, v43, v32
	v_fmac_f32_e32 v102, v58, v12
	v_fmac_f32_e32 v14, v44, v32
	v_mul_f32_e32 v98, v105, v98
	v_fmac_f32_e32 v102, v59, v13
	v_fmac_f32_e32 v15, v45, v32
	v_fmac_f32_e32 v102, v60, v14
	v_mul_f32_e32 v99, v105, v99
	v_fmac_f32_e32 v102, v61, v15
	ds_write_b32 v118, v102 offset:11008
	v_mul_f32_e32 v100, v105, v100
	v_mul_f32_e32 v101, v105, v101
	ds_write_b128 v2, v[98:101] offset:16
	v_lshlrev_b32_e32 v94, 16, v78
	v_and_b32_e32 v95, 0xffff0000, v78
	v_lshlrev_b32_e32 v96, 16, v79
	s_waitcnt lgkmcnt(2)
	ds_read_b128 v[38:41], v0 offset:5120
	ds_read_b128 v[42:45], v0 offset:5136
	ds_read_b128 v[54:57], v0 offset:7168
	ds_read_b128 v[58:61], v0 offset:7184
	ds_read_b32 v32, v1 offset:8544
	v_fmac_f32_e32 v8, v22, v30
	v_fmac_f32_e32 v9, v23, v30
	v_mul_f32_e32 v36, v46, v8
	v_and_b32_e32 v97, 0xffff0000, v79
	v_fmac_f32_e32 v10, v24, v30
	v_fmac_f32_e32 v36, v47, v9
	v_fmac_f32_e32 v11, v25, v30
	v_mul_f32_e32 v94, v109, v94
	v_fmac_f32_e32 v36, v48, v10
	v_fmac_f32_e32 v12, v26, v30
	v_fmac_f32_e32 v36, v49, v11
	v_mul_f32_e32 v95, v109, v95
	v_fmac_f32_e32 v13, v27, v30
	v_fmac_f32_e32 v36, v50, v12
	v_fmac_f32_e32 v14, v28, v30
	v_mul_f32_e32 v96, v109, v96
	v_fmac_f32_e32 v36, v51, v13
	v_fmac_f32_e32 v15, v29, v30
	v_fmac_f32_e32 v36, v52, v14
	v_mul_f32_e32 v97, v109, v97
	v_fmac_f32_e32 v36, v53, v15
	ds_write_b32 v118, v36 offset:11264
	ds_write_b128 v2, v[94:97] offset:2048
	v_lshlrev_b32_e32 v98, 16, v80
	v_and_b32_e32 v99, 0xffff0000, v80
	v_lshlrev_b32_e32 v100, 16, v81
	v_and_b32_e32 v101, 0xffff0000, v81
	v_mul_f32_e32 v98, v109, v98
	s_waitcnt lgkmcnt(2)
	ds_read_b128 v[22:25], v0 offset:5376
	ds_read_b128 v[26:29], v0 offset:5392
	ds_read_b128 v[46:49], v0 offset:7424
	ds_read_b128 v[50:53], v0 offset:7440
	ds_read_b32 v30, v1 offset:8576
	v_fmac_f32_e32 v8, v38, v32
	v_fmac_f32_e32 v9, v39, v32
	v_mul_f32_e32 v102, v54, v8
	v_mul_f32_e32 v99, v109, v99
	v_fmac_f32_e32 v10, v40, v32
	v_fmac_f32_e32 v102, v55, v9
	v_fmac_f32_e32 v11, v41, v32
	v_mul_f32_e32 v100, v109, v100
	v_fmac_f32_e32 v102, v56, v10
	v_fmac_f32_e32 v12, v42, v32
	v_fmac_f32_e32 v102, v57, v11
	v_mul_f32_e32 v101, v109, v101
	v_fmac_f32_e32 v13, v43, v32
	v_fmac_f32_e32 v102, v58, v12
	v_fmac_f32_e32 v14, v44, v32
	ds_write_b128 v2, v[98:101] offset:2064
	v_fmac_f32_e32 v102, v59, v13
	v_fmac_f32_e32 v15, v45, v32
	v_fmac_f32_e32 v102, v60, v14
	s_waitcnt vmcnt(9)
	v_fmac_f32_e32 v102, v61, v15
	ds_write_b32 v118, v102 offset:11520
	v_lshlrev_b32_e32 v34, 16, v34
	s_nop 0
	ds_write_b32 v4, v34 offset:4096
	s_waitcnt lgkmcnt(3)
	ds_read_b128 v[38:41], v0 offset:5632
	ds_read_b128 v[42:45], v0 offset:5648
	ds_read_b128 v[54:57], v0 offset:7680
	ds_read_b128 v[58:61], v0 offset:7696
	ds_read_b32 v32, v1 offset:8608
	v_fmac_f32_e32 v8, v22, v30
	v_fmac_f32_e32 v9, v23, v30
	v_mul_f32_e32 v36, v46, v8
	global_load_dwordx4 v[78:81], v5, s[94:95]
	global_load_dwordx4 v[82:85], v5, s[94:95] offset:512
	global_load_ushort v34, v6, s[94:95]
	v_add_u32_e32 v5, 0x6800, v5
	v_add_u32_e32 v6, 0x10000, v6
	v_fmac_f32_e32 v10, v24, v30
	v_fmac_f32_e32 v36, v47, v9
	v_fmac_f32_e32 v11, v25, v30
	ds_read_b128 v[124:127], v119 offset:8704
	v_fmac_f32_e32 v36, v48, v10
	v_fmac_f32_e32 v12, v26, v30
	v_fmac_f32_e32 v36, v49, v11
	ds_read_b128 v[128:131], v120 offset:8704
	v_fmac_f32_e32 v13, v27, v30
	v_fmac_f32_e32 v36, v50, v12
	v_fmac_f32_e32 v14, v28, v30
	v_fmac_f32_e32 v36, v51, v13
	v_fmac_f32_e32 v15, v29, v30
	v_fmac_f32_e32 v36, v52, v14
	v_fmac_f32_e32 v36, v53, v15
	ds_write_b32 v118, v36 offset:11776
	s_waitcnt lgkmcnt(3)
	ds_read_b128 v[22:25], v0 offset:5888
	ds_read_b128 v[26:29], v0 offset:5904
	ds_read_b128 v[46:49], v0 offset:7936
	ds_read_b128 v[50:53], v0 offset:7952
	ds_read_b32 v30, v1 offset:8640
	v_fmac_f32_e32 v8, v38, v32
	v_fmac_f32_e32 v9, v39, v32
	v_mul_f32_e32 v102, v54, v8
	v_fmac_f32_e32 v10, v40, v32
	v_fmac_f32_e32 v102, v55, v9
	v_fmac_f32_e32 v11, v41, v32
	v_fmac_f32_e32 v102, v56, v10
	v_fmac_f32_e32 v12, v42, v32
	v_fmac_f32_e32 v102, v57, v11
	v_fmac_f32_e32 v13, v43, v32
	v_fmac_f32_e32 v102, v58, v12
	v_fmac_f32_e32 v14, v44, v32
	v_fmac_f32_e32 v102, v59, v13
	v_fmac_f32_e32 v15, v45, v32
	v_fmac_f32_e32 v102, v60, v14
	v_fmac_f32_e32 v102, v61, v15
	ds_write_b32 v118, v102 offset:12032
	s_waitcnt lgkmcnt(1)
	ds_read_b128 v[38:41], v0 offset:6144
	ds_read_b128 v[42:45], v0 offset:6160
	ds_read_b128 v[54:57], v0 offset:8192
	ds_read_b128 v[58:61], v0 offset:8208
	ds_read_b32 v32, v1 offset:8672
	v_fmac_f32_e32 v8, v22, v30
	v_fmac_f32_e32 v9, v23, v30
	v_mul_f32_e32 v36, v46, v8
	s_waitcnt lgkmcnt(12)
	v_fmac_f32_e32 v10, v24, v30
	v_fmac_f32_e32 v36, v47, v9
	v_fmac_f32_e32 v11, v25, v30
	v_add_f32_e32 v124, v124, v128
	v_fmac_f32_e32 v36, v48, v10
	v_fmac_f32_e32 v12, v26, v30
	v_fmac_f32_e32 v36, v49, v11
	v_add_f32_e32 v125, v125, v129
	v_fmac_f32_e32 v13, v27, v30
	v_fmac_f32_e32 v36, v50, v12
	v_fmac_f32_e32 v14, v28, v30
	v_add_f32_e32 v126, v126, v130
	v_fmac_f32_e32 v36, v51, v13
	v_fmac_f32_e32 v15, v29, v30
	v_fmac_f32_e32 v36, v52, v14
	v_add_f32_e32 v127, v127, v131
	v_fmac_f32_e32 v36, v53, v15
	ds_write_b32 v118, v36 offset:12288
	v_add_f32_e32 v124, v124, v125
	v_add_f32_e32 v126, v126, v127
	v_add_f32_e32 v124, v124, v126
	v_cvt_pk_bf16_f32 v21, v124, v124
	ds_write_b16 v112, v21 offset:13312
	s_waitcnt lgkmcnt(2)
	ds_read_b128 v[22:25], v0 offset:0
	ds_read_b128 v[26:29], v0 offset:16
	ds_read_b128 v[46:49], v0 offset:2048
	ds_read_b128 v[50:53], v0 offset:2064
	ds_read_b32 v30, v1 offset:4096
	v_fmac_f32_e32 v8, v38, v32
	v_fmac_f32_e32 v9, v39, v32
	v_mul_f32_e32 v102, v54, v8
	v_fmac_f32_e32 v10, v40, v32
	v_fmac_f32_e32 v102, v55, v9
	v_fmac_f32_e32 v11, v41, v32
	v_fmac_f32_e32 v102, v56, v10
	v_fmac_f32_e32 v12, v42, v32
	v_fmac_f32_e32 v102, v57, v11
	v_fmac_f32_e32 v13, v43, v32
	v_fmac_f32_e32 v102, v58, v12
	v_fmac_f32_e32 v14, v44, v32
	v_fmac_f32_e32 v102, v59, v13
	v_fmac_f32_e32 v15, v45, v32
	v_fmac_f32_e32 v102, v60, v14
	v_fmac_f32_e32 v102, v61, v15
	ds_write_b32 v118, v102 offset:12544
	s_waitcnt lgkmcnt(1)
	ds_read_b128 v[38:41], v0 offset:256
	ds_read_b128 v[42:45], v0 offset:272
	ds_read_b128 v[54:57], v0 offset:2304
	ds_read_b128 v[58:61], v0 offset:2320
	ds_read_b32 v32, v1 offset:4128
	v_fmac_f32_e32 v8, v22, v30
	v_fmac_f32_e32 v9, v23, v30
	v_mul_f32_e32 v36, v46, v8
	s_waitcnt vmcnt(10)
	v_fmac_f32_e32 v10, v24, v30
	v_fmac_f32_e32 v36, v47, v9
	v_fmac_f32_e32 v11, v25, v30
	v_lshlrev_b32_e32 v94, 16, v90
	v_fmac_f32_e32 v36, v48, v10
	v_fmac_f32_e32 v12, v26, v30
	v_fmac_f32_e32 v36, v49, v11
	v_and_b32_e32 v95, 0xffff0000, v90
	v_fmac_f32_e32 v13, v27, v30
	v_fmac_f32_e32 v36, v50, v12
	v_fmac_f32_e32 v14, v28, v30
	v_lshlrev_b32_e32 v96, 16, v91
	v_fmac_f32_e32 v36, v51, v13
	v_fmac_f32_e32 v15, v29, v30
	v_fmac_f32_e32 v36, v52, v14
	v_and_b32_e32 v97, 0xffff0000, v91
	v_fmac_f32_e32 v36, v53, v15
	ds_write_b32 v118, v36 offset:8704
	v_mul_f32_e32 v94, v106, v94
	v_mul_f32_e32 v95, v106, v95
	v_mul_f32_e32 v96, v106, v96
	v_mul_f32_e32 v97, v106, v97
	ds_write_b128 v2, v[94:97] offset:4352
	v_lshlrev_b32_e32 v98, 16, v92
	s_waitcnt lgkmcnt(2)
	ds_read_b128 v[22:25], v0 offset:512
	ds_read_b128 v[26:29], v0 offset:528
	ds_read_b128 v[46:49], v0 offset:2560
	ds_read_b128 v[50:53], v0 offset:2576
	ds_read_b32 v30, v1 offset:4160
	v_fmac_f32_e32 v8, v38, v32
	v_fmac_f32_e32 v9, v39, v32
	v_mul_f32_e32 v102, v54, v8
	v_and_b32_e32 v99, 0xffff0000, v92
	v_fmac_f32_e32 v10, v40, v32
	v_fmac_f32_e32 v102, v55, v9
	v_fmac_f32_e32 v11, v41, v32
	v_lshlrev_b32_e32 v100, 16, v93
	v_fmac_f32_e32 v102, v56, v10
	v_fmac_f32_e32 v12, v42, v32
	v_fmac_f32_e32 v102, v57, v11
	v_and_b32_e32 v101, 0xffff0000, v93
	v_fmac_f32_e32 v13, v43, v32
	v_fmac_f32_e32 v102, v58, v12
	v_fmac_f32_e32 v14, v44, v32
	v_mul_f32_e32 v98, v106, v98
	v_fmac_f32_e32 v102, v59, v13
	v_fmac_f32_e32 v15, v45, v32
	v_fmac_f32_e32 v102, v60, v14
	v_mul_f32_e32 v99, v106, v99
	v_fmac_f32_e32 v102, v61, v15
	ds_write_b32 v118, v102 offset:8960
	v_mul_f32_e32 v100, v106, v100
	v_mul_f32_e32 v101, v106, v101
	ds_write_b128 v2, v[98:101] offset:4368
	v_lshlrev_b32_e32 v94, 16, v86
	v_and_b32_e32 v95, 0xffff0000, v86
	v_lshlrev_b32_e32 v96, 16, v87
	s_waitcnt lgkmcnt(2)
	ds_read_b128 v[38:41], v0 offset:768
	ds_read_b128 v[42:45], v0 offset:784
	ds_read_b128 v[54:57], v0 offset:2816
	ds_read_b128 v[58:61], v0 offset:2832
	ds_read_b32 v32, v1 offset:4192
	v_fmac_f32_e32 v8, v22, v30
	v_fmac_f32_e32 v9, v23, v30
	v_mul_f32_e32 v36, v46, v8
	v_and_b32_e32 v97, 0xffff0000, v87
	v_fmac_f32_e32 v10, v24, v30
	v_fmac_f32_e32 v36, v47, v9
	v_fmac_f32_e32 v11, v25, v30
	v_mul_f32_e32 v94, v110, v94
	v_fmac_f32_e32 v36, v48, v10
	v_fmac_f32_e32 v12, v26, v30
	v_fmac_f32_e32 v36, v49, v11
	v_mul_f32_e32 v95, v110, v95
	v_fmac_f32_e32 v13, v27, v30
	v_fmac_f32_e32 v36, v50, v12
	v_fmac_f32_e32 v14, v28, v30
	v_mul_f32_e32 v96, v110, v96
	v_fmac_f32_e32 v36, v51, v13
	v_fmac_f32_e32 v15, v29, v30
	v_fmac_f32_e32 v36, v52, v14
	v_mul_f32_e32 v97, v110, v97
	v_fmac_f32_e32 v36, v53, v15
	ds_write_b32 v118, v36 offset:9216
	ds_write_b128 v2, v[94:97] offset:6400
	v_lshlrev_b32_e32 v98, 16, v88
	v_and_b32_e32 v99, 0xffff0000, v88
	v_lshlrev_b32_e32 v100, 16, v89
	v_and_b32_e32 v101, 0xffff0000, v89
	v_mul_f32_e32 v98, v110, v98
	s_waitcnt lgkmcnt(2)
	ds_read_b128 v[22:25], v0 offset:1024
	ds_read_b128 v[26:29], v0 offset:1040
	ds_read_b128 v[46:49], v0 offset:3072
	ds_read_b128 v[50:53], v0 offset:3088
	ds_read_b32 v30, v1 offset:4224
	v_fmac_f32_e32 v8, v38, v32
	v_fmac_f32_e32 v9, v39, v32
	v_mul_f32_e32 v102, v54, v8
	v_mul_f32_e32 v99, v110, v99
	v_fmac_f32_e32 v10, v40, v32
	v_fmac_f32_e32 v102, v55, v9
	v_fmac_f32_e32 v11, v41, v32
	v_mul_f32_e32 v100, v110, v100
	v_fmac_f32_e32 v102, v56, v10
	v_fmac_f32_e32 v12, v42, v32
	v_fmac_f32_e32 v102, v57, v11
	v_mul_f32_e32 v101, v110, v101
	v_fmac_f32_e32 v13, v43, v32
	v_fmac_f32_e32 v102, v58, v12
	v_fmac_f32_e32 v14, v44, v32
	ds_write_b128 v2, v[98:101] offset:6416
	v_fmac_f32_e32 v102, v59, v13
	v_fmac_f32_e32 v15, v45, v32
	v_fmac_f32_e32 v102, v60, v14
	s_waitcnt vmcnt(9)
	v_fmac_f32_e32 v102, v61, v15
	ds_write_b32 v118, v102 offset:9472
	v_lshlrev_b32_e32 v35, 16, v35
	s_nop 0
	ds_write_b32 v4, v35 offset:8448
	s_waitcnt lgkmcnt(3)
	ds_read_b128 v[38:41], v0 offset:1280
	ds_read_b128 v[42:45], v0 offset:1296
	ds_read_b128 v[54:57], v0 offset:3328
	ds_read_b128 v[58:61], v0 offset:3344
	ds_read_b32 v32, v1 offset:4256
	v_fmac_f32_e32 v8, v22, v30
	v_fmac_f32_e32 v9, v23, v30
	v_mul_f32_e32 v36, v46, v8
	global_load_dwordx4 v[86:89], v5, s[94:95]
	global_load_dwordx4 v[90:93], v5, s[94:95] offset:512
	global_load_ushort v35, v6, s[94:95]
	v_add_u32_e32 v5, 0x6800, v5
	v_add_u32_e32 v6, 0x10000, v6
	v_fmac_f32_e32 v10, v24, v30
	v_fmac_f32_e32 v36, v47, v9
	v_fmac_f32_e32 v11, v25, v30
	ds_read_b128 v[124:127], v119 offset:10752
	v_fmac_f32_e32 v36, v48, v10
	v_fmac_f32_e32 v12, v26, v30
	v_fmac_f32_e32 v36, v49, v11
	ds_read_b128 v[128:131], v120 offset:10752
	v_fmac_f32_e32 v13, v27, v30
	v_fmac_f32_e32 v36, v50, v12
	v_fmac_f32_e32 v14, v28, v30
	v_fmac_f32_e32 v36, v51, v13
	v_fmac_f32_e32 v15, v29, v30
	v_fmac_f32_e32 v36, v52, v14
	v_fmac_f32_e32 v36, v53, v15
	ds_write_b32 v118, v36 offset:9728
	s_waitcnt lgkmcnt(3)
	ds_read_b128 v[22:25], v0 offset:1536
	ds_read_b128 v[26:29], v0 offset:1552
	ds_read_b128 v[46:49], v0 offset:3584
	ds_read_b128 v[50:53], v0 offset:3600
	ds_read_b32 v30, v1 offset:4288
	v_fmac_f32_e32 v8, v38, v32
	v_fmac_f32_e32 v9, v39, v32
	v_mul_f32_e32 v102, v54, v8
	v_fmac_f32_e32 v10, v40, v32
	v_fmac_f32_e32 v102, v55, v9
	v_fmac_f32_e32 v11, v41, v32
	v_fmac_f32_e32 v102, v56, v10
	v_fmac_f32_e32 v12, v42, v32
	v_fmac_f32_e32 v102, v57, v11
	v_fmac_f32_e32 v13, v43, v32
	v_fmac_f32_e32 v102, v58, v12
	v_fmac_f32_e32 v14, v44, v32
	v_fmac_f32_e32 v102, v59, v13
	v_fmac_f32_e32 v15, v45, v32
	v_fmac_f32_e32 v102, v60, v14
	v_fmac_f32_e32 v102, v61, v15
	ds_write_b32 v118, v102 offset:9984
	s_waitcnt lgkmcnt(1)
	ds_read_b128 v[38:41], v0 offset:1792
	ds_read_b128 v[42:45], v0 offset:1808
	ds_read_b128 v[54:57], v0 offset:3840
	ds_read_b128 v[58:61], v0 offset:3856
	ds_read_b32 v32, v1 offset:4320
	v_fmac_f32_e32 v8, v22, v30
	v_fmac_f32_e32 v9, v23, v30
	v_mul_f32_e32 v36, v46, v8
	s_waitcnt lgkmcnt(12)
	v_fmac_f32_e32 v10, v24, v30
	v_fmac_f32_e32 v36, v47, v9
	v_fmac_f32_e32 v11, v25, v30
	v_add_f32_e32 v124, v124, v128
	v_fmac_f32_e32 v36, v48, v10
	v_fmac_f32_e32 v12, v26, v30
	v_fmac_f32_e32 v36, v49, v11
	v_add_f32_e32 v125, v125, v129
	v_fmac_f32_e32 v13, v27, v30
	v_fmac_f32_e32 v36, v50, v12
	v_fmac_f32_e32 v14, v28, v30
	v_add_f32_e32 v126, v126, v130
	v_fmac_f32_e32 v36, v51, v13
	v_fmac_f32_e32 v15, v29, v30
	v_fmac_f32_e32 v36, v52, v14
	v_add_f32_e32 v127, v127, v131
	v_fmac_f32_e32 v36, v53, v15
	ds_write_b32 v118, v36 offset:10240
	v_add_f32_e32 v124, v124, v125
	v_add_f32_e32 v126, v126, v127
	v_add_f32_e32 v124, v124, v126
	v_cvt_pk_bf16_f32 v21, v124, v124
	ds_write_b16 v112, v21 offset:13440
	s_waitcnt lgkmcnt(2)
	ds_read_b128 v[22:25], v0 offset:4352
	ds_read_b128 v[26:29], v0 offset:4368
	ds_read_b128 v[46:49], v0 offset:6400
	ds_read_b128 v[50:53], v0 offset:6416
	ds_read_b32 v30, v1 offset:8448
	v_fmac_f32_e32 v8, v38, v32
	v_fmac_f32_e32 v9, v39, v32
	v_mul_f32_e32 v102, v54, v8
	v_fmac_f32_e32 v10, v40, v32
	v_fmac_f32_e32 v102, v55, v9
	v_fmac_f32_e32 v11, v41, v32
	v_fmac_f32_e32 v102, v56, v10
	v_fmac_f32_e32 v12, v42, v32
	v_fmac_f32_e32 v102, v57, v11
	v_fmac_f32_e32 v13, v43, v32
	v_fmac_f32_e32 v102, v58, v12
	v_fmac_f32_e32 v14, v44, v32
	v_fmac_f32_e32 v102, v59, v13
	v_fmac_f32_e32 v15, v45, v32
	v_fmac_f32_e32 v102, v60, v14
	v_fmac_f32_e32 v102, v61, v15
	ds_write_b32 v118, v102 offset:10496
	s_waitcnt lgkmcnt(1)
	ds_read_b128 v[38:41], v0 offset:4608
	ds_read_b128 v[42:45], v0 offset:4624
	ds_read_b128 v[54:57], v0 offset:6656
	ds_read_b128 v[58:61], v0 offset:6672
	ds_read_b32 v32, v1 offset:8480
	v_fmac_f32_e32 v8, v22, v30
	v_fmac_f32_e32 v9, v23, v30
	v_mul_f32_e32 v36, v46, v8
	s_waitcnt vmcnt(10)
	v_fmac_f32_e32 v10, v24, v30
	v_fmac_f32_e32 v36, v47, v9
	v_fmac_f32_e32 v11, v25, v30
	v_lshlrev_b32_e32 v94, 16, v66
	v_fmac_f32_e32 v36, v48, v10
	v_fmac_f32_e32 v12, v26, v30
	v_fmac_f32_e32 v36, v49, v11
	v_and_b32_e32 v95, 0xffff0000, v66
	v_fmac_f32_e32 v13, v27, v30
	v_fmac_f32_e32 v36, v50, v12
	v_fmac_f32_e32 v14, v28, v30
	v_lshlrev_b32_e32 v96, 16, v67
	v_fmac_f32_e32 v36, v51, v13
	v_fmac_f32_e32 v15, v29, v30
	v_fmac_f32_e32 v36, v52, v14
	v_and_b32_e32 v97, 0xffff0000, v67
	v_fmac_f32_e32 v36, v53, v15
	ds_write_b32 v118, v36 offset:10752
	v_mul_f32_e32 v94, v103, v94
	v_mul_f32_e32 v95, v103, v95
	v_mul_f32_e32 v96, v103, v96
	v_mul_f32_e32 v97, v103, v97
	ds_write_b128 v2, v[94:97] offset:0
	v_lshlrev_b32_e32 v98, 16, v68
	s_waitcnt lgkmcnt(2)
	ds_read_b128 v[22:25], v0 offset:4864
	ds_read_b128 v[26:29], v0 offset:4880
	ds_read_b128 v[46:49], v0 offset:6912
	ds_read_b128 v[50:53], v0 offset:6928
	ds_read_b32 v30, v1 offset:8512
	v_fmac_f32_e32 v8, v38, v32
	v_fmac_f32_e32 v9, v39, v32
	v_mul_f32_e32 v102, v54, v8
	v_and_b32_e32 v99, 0xffff0000, v68
	v_fmac_f32_e32 v10, v40, v32
	v_fmac_f32_e32 v102, v55, v9
	v_fmac_f32_e32 v11, v41, v32
	v_lshlrev_b32_e32 v100, 16, v69
	v_fmac_f32_e32 v102, v56, v10
	v_fmac_f32_e32 v12, v42, v32
	v_fmac_f32_e32 v102, v57, v11
	v_and_b32_e32 v101, 0xffff0000, v69
	v_fmac_f32_e32 v13, v43, v32
	v_fmac_f32_e32 v102, v58, v12
	v_fmac_f32_e32 v14, v44, v32
	v_mul_f32_e32 v98, v103, v98
	v_fmac_f32_e32 v102, v59, v13
	v_fmac_f32_e32 v15, v45, v32
	v_fmac_f32_e32 v102, v60, v14
	v_mul_f32_e32 v99, v103, v99
	v_fmac_f32_e32 v102, v61, v15
	ds_write_b32 v118, v102 offset:11008
	v_mul_f32_e32 v100, v103, v100
	v_mul_f32_e32 v101, v103, v101
	ds_write_b128 v2, v[98:101] offset:16
	v_lshlrev_b32_e32 v94, 16, v62
	v_and_b32_e32 v95, 0xffff0000, v62
	v_lshlrev_b32_e32 v96, 16, v63
	s_waitcnt lgkmcnt(2)
	ds_read_b128 v[38:41], v0 offset:5120
	ds_read_b128 v[42:45], v0 offset:5136
	ds_read_b128 v[54:57], v0 offset:7168
	ds_read_b128 v[58:61], v0 offset:7184
	ds_read_b32 v32, v1 offset:8544
	v_fmac_f32_e32 v8, v22, v30
	v_fmac_f32_e32 v9, v23, v30
	v_mul_f32_e32 v36, v46, v8
	v_and_b32_e32 v97, 0xffff0000, v63
	v_fmac_f32_e32 v10, v24, v30
	v_fmac_f32_e32 v36, v47, v9
	v_fmac_f32_e32 v11, v25, v30
	v_mul_f32_e32 v94, v107, v94
	v_fmac_f32_e32 v36, v48, v10
	v_fmac_f32_e32 v12, v26, v30
	v_fmac_f32_e32 v36, v49, v11
	v_mul_f32_e32 v95, v107, v95
	v_fmac_f32_e32 v13, v27, v30
	v_fmac_f32_e32 v36, v50, v12
	v_fmac_f32_e32 v14, v28, v30
	v_mul_f32_e32 v96, v107, v96
	v_fmac_f32_e32 v36, v51, v13
	v_fmac_f32_e32 v15, v29, v30
	v_fmac_f32_e32 v36, v52, v14
	v_mul_f32_e32 v97, v107, v97
	v_fmac_f32_e32 v36, v53, v15
	ds_write_b32 v118, v36 offset:11264
	ds_write_b128 v2, v[94:97] offset:2048
	v_lshlrev_b32_e32 v98, 16, v64
	v_and_b32_e32 v99, 0xffff0000, v64
	v_lshlrev_b32_e32 v100, 16, v65
	v_and_b32_e32 v101, 0xffff0000, v65
	v_mul_f32_e32 v98, v107, v98
	s_waitcnt lgkmcnt(2)
	ds_read_b128 v[22:25], v0 offset:5376
	ds_read_b128 v[26:29], v0 offset:5392
	ds_read_b128 v[46:49], v0 offset:7424
	ds_read_b128 v[50:53], v0 offset:7440
	ds_read_b32 v30, v1 offset:8576
	v_fmac_f32_e32 v8, v38, v32
	v_fmac_f32_e32 v9, v39, v32
	v_mul_f32_e32 v102, v54, v8
	v_mul_f32_e32 v99, v107, v99
	v_fmac_f32_e32 v10, v40, v32
	v_fmac_f32_e32 v102, v55, v9
	v_fmac_f32_e32 v11, v41, v32
	v_mul_f32_e32 v100, v107, v100
	v_fmac_f32_e32 v102, v56, v10
	v_fmac_f32_e32 v12, v42, v32
	v_fmac_f32_e32 v102, v57, v11
	v_mul_f32_e32 v101, v107, v101
	v_fmac_f32_e32 v13, v43, v32
	v_fmac_f32_e32 v102, v58, v12
	v_fmac_f32_e32 v14, v44, v32
	ds_write_b128 v2, v[98:101] offset:2064
	v_fmac_f32_e32 v102, v59, v13
	v_fmac_f32_e32 v15, v45, v32
	v_fmac_f32_e32 v102, v60, v14
	s_waitcnt vmcnt(9)
	v_fmac_f32_e32 v102, v61, v15
	ds_write_b32 v118, v102 offset:11520
	v_lshlrev_b32_e32 v31, 16, v31
	s_nop 0
	ds_write_b32 v4, v31 offset:4096
	s_waitcnt lgkmcnt(3)
	ds_read_b128 v[38:41], v0 offset:5632
	ds_read_b128 v[42:45], v0 offset:5648
	ds_read_b128 v[54:57], v0 offset:7680
	ds_read_b128 v[58:61], v0 offset:7696
	ds_read_b32 v32, v1 offset:8608
	v_fmac_f32_e32 v8, v22, v30
	v_fmac_f32_e32 v9, v23, v30
	v_mul_f32_e32 v36, v46, v8
	global_load_dwordx4 v[62:65], v5, s[94:95]
	global_load_dwordx4 v[66:69], v5, s[94:95] offset:512
	global_load_ushort v31, v6, s[94:95]
	v_add_u32_e32 v5, 0x6800, v5
	v_add_u32_e32 v6, 0x10000, v6
	v_fmac_f32_e32 v10, v24, v30
	v_fmac_f32_e32 v36, v47, v9
	v_fmac_f32_e32 v11, v25, v30
	ds_read_b128 v[124:127], v119 offset:8704
	v_fmac_f32_e32 v36, v48, v10
	v_fmac_f32_e32 v12, v26, v30
	v_fmac_f32_e32 v36, v49, v11
	ds_read_b128 v[128:131], v120 offset:8704
	v_fmac_f32_e32 v13, v27, v30
	v_fmac_f32_e32 v36, v50, v12
	v_fmac_f32_e32 v14, v28, v30
	v_fmac_f32_e32 v36, v51, v13
	v_fmac_f32_e32 v15, v29, v30
	v_fmac_f32_e32 v36, v52, v14
	v_fmac_f32_e32 v36, v53, v15
	ds_write_b32 v118, v36 offset:11776
	s_waitcnt lgkmcnt(3)
	ds_read_b128 v[22:25], v0 offset:5888
	ds_read_b128 v[26:29], v0 offset:5904
	ds_read_b128 v[46:49], v0 offset:7936
	ds_read_b128 v[50:53], v0 offset:7952
	ds_read_b32 v30, v1 offset:8640
	v_fmac_f32_e32 v8, v38, v32
	v_fmac_f32_e32 v9, v39, v32
	v_mul_f32_e32 v102, v54, v8
	v_fmac_f32_e32 v10, v40, v32
	v_fmac_f32_e32 v102, v55, v9
	v_fmac_f32_e32 v11, v41, v32
	v_fmac_f32_e32 v102, v56, v10
	v_fmac_f32_e32 v12, v42, v32
	v_fmac_f32_e32 v102, v57, v11
	v_fmac_f32_e32 v13, v43, v32
	v_fmac_f32_e32 v102, v58, v12
	v_fmac_f32_e32 v14, v44, v32
	v_fmac_f32_e32 v102, v59, v13
	v_fmac_f32_e32 v15, v45, v32
	v_fmac_f32_e32 v102, v60, v14
	v_fmac_f32_e32 v102, v61, v15
	ds_write_b32 v118, v102 offset:12032
	s_waitcnt lgkmcnt(1)
	ds_read_b128 v[38:41], v0 offset:6144
	ds_read_b128 v[42:45], v0 offset:6160
	ds_read_b128 v[54:57], v0 offset:8192
	ds_read_b128 v[58:61], v0 offset:8208
	ds_read_b32 v32, v1 offset:8672
	v_fmac_f32_e32 v8, v22, v30
	v_fmac_f32_e32 v9, v23, v30
	v_mul_f32_e32 v36, v46, v8
	s_waitcnt lgkmcnt(12)
	v_fmac_f32_e32 v10, v24, v30
	v_fmac_f32_e32 v36, v47, v9
	v_fmac_f32_e32 v11, v25, v30
	v_add_f32_e32 v124, v124, v128
	v_fmac_f32_e32 v36, v48, v10
	v_fmac_f32_e32 v12, v26, v30
	v_fmac_f32_e32 v36, v49, v11
	v_add_f32_e32 v125, v125, v129
	v_fmac_f32_e32 v13, v27, v30
	v_fmac_f32_e32 v36, v50, v12
	v_fmac_f32_e32 v14, v28, v30
	v_add_f32_e32 v126, v126, v130
	v_fmac_f32_e32 v36, v51, v13
	v_fmac_f32_e32 v15, v29, v30
	v_fmac_f32_e32 v36, v52, v14
	v_add_f32_e32 v127, v127, v131
	v_fmac_f32_e32 v36, v53, v15
	ds_write_b32 v118, v36 offset:12288
	v_add_f32_e32 v124, v124, v125
	v_add_f32_e32 v126, v126, v127
	v_add_f32_e32 v124, v124, v126
	v_cvt_pk_bf16_f32 v21, v124, v124
	ds_write_b16 v112, v21 offset:13568
	s_waitcnt lgkmcnt(2)
	ds_read_b128 v[22:25], v0 offset:0
	ds_read_b128 v[26:29], v0 offset:16
	ds_read_b128 v[46:49], v0 offset:2048
	ds_read_b128 v[50:53], v0 offset:2064
	ds_read_b32 v30, v1 offset:4096
	v_fmac_f32_e32 v8, v38, v32
	v_fmac_f32_e32 v9, v39, v32
	v_mul_f32_e32 v102, v54, v8
	v_fmac_f32_e32 v10, v40, v32
	v_fmac_f32_e32 v102, v55, v9
	v_fmac_f32_e32 v11, v41, v32
	v_fmac_f32_e32 v102, v56, v10
	v_fmac_f32_e32 v12, v42, v32
	v_fmac_f32_e32 v102, v57, v11
	v_fmac_f32_e32 v13, v43, v32
	v_fmac_f32_e32 v102, v58, v12
	v_fmac_f32_e32 v14, v44, v32
	v_fmac_f32_e32 v102, v59, v13
	v_fmac_f32_e32 v15, v45, v32
	v_fmac_f32_e32 v102, v60, v14
	v_fmac_f32_e32 v102, v61, v15
	ds_write_b32 v118, v102 offset:12544
	v_mul_f32_e32 v8, s44, v8
	v_mul_f32_e32 v9, s44, v9
	v_mul_f32_e32 v10, s44, v10
	v_mul_f32_e32 v11, s44, v11
	v_mul_f32_e32 v12, s44, v12
	v_mul_f32_e32 v13, s44, v13
	v_mul_f32_e32 v14, s44, v14
	v_mul_f32_e32 v15, s44, v15
	s_sub_u32 s12, s12, 1
	s_cmp_lg_u32 s12, 0
	s_cbranch_scc1 .Lls0_8_loop
	ds_read_b128 v[124:127], v119 offset:10752
	ds_read_b128 v[128:131], v120 offset:10752
	s_waitcnt lgkmcnt(0)
	v_add_f32_e32 v124, v124, v128
	v_add_f32_e32 v125, v125, v129
	v_add_f32_e32 v126, v126, v130
	v_add_f32_e32 v127, v127, v131
	v_add_f32_e32 v124, v124, v125
	v_add_f32_e32 v126, v126, v127
	v_add_f32_e32 v124, v124, v126
	v_cvt_pk_bf16_f32 v21, v124, v124
	ds_write_b16 v112, v21 offset:13696
	s_waitcnt lgkmcnt(0)
	ds_read_b128 v[114:117], v113 offset:13312
	s_waitcnt lgkmcnt(0)
	global_store_dwordx4 v7, v[114:117], s[94:95]
	v_add_u32_e32 v7, 0x20000, v7
	s_nop 0
	ds_read_b128 v[114:117], v113 offset:14336
	s_waitcnt lgkmcnt(0)
	global_store_dwordx4 v7, v[114:117], s[94:95]
	v_add_u32_e32 v7, 0x20000, v7
	s_nop 0
	ds_read_b128 v[114:117], v113 offset:15360
	s_waitcnt lgkmcnt(0)
	global_store_dwordx4 v7, v[114:117], s[94:95]
	v_add_u32_e32 v7, 0x20000, v7
	s_nop 0
	ds_read_b128 v[114:117], v113 offset:16384
	s_waitcnt lgkmcnt(0)
	global_store_dwordx4 v7, v[114:117], s[94:95]
	v_add_u32_e32 v7, 0x20000, v7
	s_nop 0
	ds_read_b128 v[114:117], v113 offset:17408
	s_waitcnt lgkmcnt(0)
	global_store_dwordx4 v7, v[114:117], s[94:95]
	v_add_u32_e32 v7, 0x20000, v7
	s_nop 0
	ds_read_b128 v[114:117], v113 offset:18432
	s_waitcnt lgkmcnt(0)
	global_store_dwordx4 v7, v[114:117], s[94:95]
	v_add_u32_e32 v7, 0x20000, v7
	s_nop 0
	ds_read_b128 v[114:117], v113 offset:19456
	s_waitcnt lgkmcnt(0)
	global_store_dwordx4 v7, v[114:117], s[94:95]
	v_add_u32_e32 v7, 0x20000, v7
	s_nop 0
	ds_read_b128 v[114:117], v113 offset:20480
	s_waitcnt lgkmcnt(0)
	global_store_dwordx4 v7, v[114:117], s[94:95]
	v_add_u32_e32 v7, 0x20000, v7
	s_nop 0
	global_store_dword v111, v8, s[26:27] offset:0
	global_store_dword v111, v9, s[26:27] offset:256
	global_store_dword v111, v10, s[26:27] offset:512
	global_store_dword v111, v11, s[26:27] offset:768
	global_store_dword v111, v12, s[26:27] offset:1024
	global_store_dword v111, v13, s[26:27] offset:1280
	global_store_dword v111, v14, s[26:27] offset:1536
	global_store_dword v111, v15, s[26:27] offset:1792
	s_waitcnt vmcnt(0) lgkmcnt(0)
	s_setprio 0
	s_branch .Lls_done
.Lls2_8_entry:
	v_and_b32_e32 v114, 63, v196
	v_and_b32_e32 v115, 7, v114
	v_lshrrev_b32_e32 v116, 3, v114
	s_min_u32 s29, s0, 4
	s_mul_i32 s29, s29, 0x5600
	v_and_b32_e32 v117, 3, v115
	v_cmp_eq_u32_e64 s[6:7], 1, v117
	v_cmp_eq_u32_e64 s[8:9], 2, v117
	v_cmp_eq_u32_e64 s[10:11], 3, v117
	v_lshl_add_u32 v0, v115, 5, s29
	v_lshl_add_u32 v1, v116, 2, s29
	s_lshl_b32 s37, s16, 11
	v_lshrrev_b32_e32 v115, 3, v114
	v_and_b32_e32 v116, 7, v114
	v_add_u32_e32 v117, s37, v115
	s_lshl_b32 s21, s17, 7
	s_add_u32 s21, s21, 0x10800500
	v_mul_u32_u24_e32 v5, 0xd00, v117
	v_lshl_add_u32 v5, v116, 4, v5
	v_add_u32_e32 v5, s21, v5
	v_lshlrev_b32_e32 v2, 8, v115
	v_lshl_add_u32 v2, v116, 5, v2
	v_add_u32_e32 v2, s29, v2
	s_lshl_b32 s21, s17, 8
	s_add_u32 s21, s21, 0x13e00200
	v_mul_u32_u24_e32 v8, 0x630, v117
	v_lshl_add_u32 v8, v116, 5, v8
	v_add_u32_e32 v8, s21, v8
	v_lshrrev_b32_e32 v116, 3, v114
	v_and_b32_e32 v115, 7, v114
	v_add_u32_e32 v117, s37, v116
	s_lshl_b32 s22, s14, 3
	s_lshl_b32 s21, s17, 6
	s_add_u32 s21, s21, s22
	s_lshl_b32 s44, s21, 1
	s_add_u32 s44, s44, 0x8401220
	v_lshlrev_b32_e32 v6, 13, v117
	v_lshlrev_b32_e32 v4, 5, v116
	v_lshl_add_u32 v4, v115, 2, v4
	v_lshl_add_u32 v6, v115, 1, v6
	v_add_u32_e32 v6, s44, v6
	v_add_u32_e32 v4, s29, v4
	v_and_b32_e32 v115, 7, v114
	v_lshrrev_b32_e32 v116, 3, v114
	v_add_u32_e32 v117, s37, v114
	v_lshlrev_b32_e32 v7, 11, v117
	s_lshl_b32 s44, s21, 1
	s_add_u32 s44, s44, 0x6300400
	v_add_u32_e32 v7, s44, v7
	s_lshl_b32 s44, s28, 3
	s_add_u32 s44, s44, s16
	s_lshl_b32 s44, s44, 2
	s_add_u32 s44, s44, s17
	s_mul_i32 s44, s44, 0x4000
	s_add_u32 s44, s44, 0x4380000
	s_lshl_b32 s24, s22, 2
	s_add_u32 s44, s44, s24
	v_lshlrev_b32_e32 v120, 11, v115
	v_lshl_add_u32 v120, v116, 2, v120
	v_add_u32_e32 v120, s44, v120
	v_readlane_b32 s26, v253, 29
	v_readlane_b32 s27, v253, 30
	v_lshlrev_b32_e32 v121, 4, v115
	v_lshl_add_u32 v121, v116, 1, v121
	v_add_u32_e32 v121, s29, v121
	v_lshl_add_u32 v122, v114, 4, s29
	v_lshl_add_u32 v128, v114, 2, s29
	v_lshl_add_u32 v121, v114, 1, s29
	v_subrev_u32_e32 v121, 0x200, v121
	v_lshrrev_b32_e32 v115, 3, v114
	v_and_b32_e32 v116, 7, v114
	v_lshlrev_b32_e32 v117, 8, v115
	v_lshl_add_u32 v117, v116, 5, v117
	v_add_u32_e32 v117, s29, v117
	v_bfe_u32 v115, v115, 1, 1
	v_xor_b32_e32 v116, 0, v115
	v_lshl_add_u32 v129, v116, 4, v117
	v_xor_b32_e32 v116, 1, v115
	v_lshl_add_u32 v130, v116, 4, v117
	v_mov_b32_e32 v10, 0
	v_mov_b32_e32 v11, 0
	v_mov_b32_e32 v12, 0
	v_mov_b32_e32 v13, 0
	v_mov_b32_e32 v14, 0
	v_mov_b32_e32 v15, 0
	v_mov_b32_e32 v16, 0
	v_mov_b32_e32 v17, 0
	v_mov_b32_e32 v9, 0
	v_mov_b32_e32 v18, 0
	v_mov_b32_e32 v19, 0
	v_mov_b32_e32 v20, 0
	v_mov_b32_e32 v118, 0
	v_mov_b32_e32 v119, 0
	s_setprio 2
	s_movk_i32 s12, 64
	s_nop 0
	global_load_dwordx4 v[62:65], v5, s[94:95]
	global_load_dwordx4 v[66:69], v8, s[94:95]
	global_load_dwordx4 v[70:73], v8, s[94:95] offset:16
	global_load_ushort v23, v6, s[94:95]
	v_add_u32_e32 v5, 0x6800, v5
	v_add_u32_e32 v8, 0x3180, v8
	v_add_u32_e32 v6, 0x10000, v6
	s_waitcnt vmcnt(0)
	s_waitcnt vmcnt(3)
	v_lshlrev_b32_e32 v110, 16, v62
	v_and_b32_e32 v111, 0xffff0000, v62
	v_lshlrev_b32_e32 v112, 16, v63
	v_and_b32_e32 v113, 0xffff0000, v63
	ds_write_b128 v2, v[110:113] offset:0
	v_lshlrev_b32_e32 v114, 16, v64
	v_and_b32_e32 v115, 0xffff0000, v64
	v_lshlrev_b32_e32 v116, 16, v65
	v_and_b32_e32 v117, 0xffff0000, v65
	ds_write_b128 v2, v[114:117] offset:16
	s_waitcnt vmcnt(1)
	ds_write_b128 v2, v[66:69] offset:2048
	ds_write_b128 v2, v[70:73] offset:2064
	s_waitcnt vmcnt(0)
	v_lshlrev_b32_e32 v23, 16, v23
	s_nop 0
	ds_write_b32 v4, v23 offset:4096
	global_load_dwordx4 v[74:77], v5, s[94:95]
	global_load_dwordx4 v[78:81], v8, s[94:95]
	global_load_dwordx4 v[82:85], v8, s[94:95] offset:16
	global_load_ushort v33, v6, s[94:95]
	v_add_u32_e32 v5, 0x6800, v5
	v_add_u32_e32 v8, 0x3180, v8
	v_add_u32_e32 v6, 0x10000, v6
	global_load_dwordx4 v[86:89], v5, s[94:95]
	global_load_dwordx4 v[90:93], v8, s[94:95]
	global_load_dwordx4 v[94:97], v8, s[94:95] offset:16
	global_load_ushort v35, v6, s[94:95]
	v_add_u32_e32 v5, 0x6800, v5
	v_add_u32_e32 v8, 0x3180, v8
	v_add_u32_e32 v6, 0x10000, v6
	global_load_dwordx4 v[98:101], v5, s[94:95]
	global_load_dwordx4 v[102:105], v8, s[94:95]
	global_load_dwordx4 v[106:109], v8, s[94:95] offset:16
	global_load_ushort v36, v6, s[94:95]
	v_add_u32_e32 v5, 0x6800, v5
	v_add_u32_e32 v8, 0x3180, v8
	v_add_u32_e32 v6, 0x10000, v6
	global_load_dwordx4 v[62:65], v5, s[94:95]
	global_load_dwordx4 v[66:69], v8, s[94:95]
	global_load_dwordx4 v[70:73], v8, s[94:95] offset:16
	global_load_ushort v23, v6, s[94:95]
	v_add_u32_e32 v5, 0x6800, v5
	v_add_u32_e32 v8, 0x3180, v8
	v_add_u32_e32 v6, 0x10000, v6
	ds_read_b128 v[24:27], v0 offset:0
	ds_read_b128 v[28:31], v0 offset:16
	ds_read_b128 v[46:49], v0 offset:2048
	ds_read_b128 v[50:53], v0 offset:2064
	ds_read_b32 v32, v1 offset:4096
.Lls2_8_loop:
	s_waitcnt lgkmcnt(0)
	ds_read_b128 v[38:41], v0 offset:256
	ds_read_b128 v[42:45], v0 offset:272
	ds_read_b128 v[54:57], v0 offset:2304
	ds_read_b128 v[58:61], v0 offset:2320
	ds_read_b32 v34, v1 offset:4128
	v_sub_f32_e32 v10, v10, v32
	v_sub_f32_e32 v11, v11, v32
	v_sub_f32_e32 v12, v12, v32
	s_waitcnt vmcnt(15)
	v_sub_f32_e32 v13, v13, v32
	v_sub_f32_e32 v14, v14, v32
	v_sub_f32_e32 v15, v15, v32
	v_lshlrev_b32_e32 v110, 16, v74
	v_sub_f32_e32 v16, v16, v32
	v_sub_f32_e32 v17, v17, v32
	v_fma_f32 v10, v46, v10, v32
	v_and_b32_e32 v111, 0xffff0000, v74
	v_fma_f32 v11, v47, v11, v32
	v_mul_f32_e32 v118, v24, v10
	v_fma_f32 v12, v48, v12, v32
	v_lshlrev_b32_e32 v112, 16, v75
	v_fmac_f32_e32 v118, v25, v11
	v_fma_f32 v13, v49, v13, v32
	v_fmac_f32_e32 v118, v26, v12
	v_and_b32_e32 v113, 0xffff0000, v75
	v_fma_f32 v14, v50, v14, v32
	v_fmac_f32_e32 v118, v27, v13
	v_fma_f32 v15, v51, v15, v32
	v_fmac_f32_e32 v118, v28, v14
	v_fma_f32 v16, v52, v16, v32
	v_fmac_f32_e32 v118, v29, v15
	v_fma_f32 v17, v53, v17, v32
	v_fmac_f32_e32 v118, v30, v16
	v_fmac_f32_e32 v118, v31, v17
	ds_write_b32 v128, v118 offset:8704
	s_waitcnt lgkmcnt(1)
	ds_read_b128 v[24:27], v0 offset:512
	ds_read_b128 v[28:31], v0 offset:528
	ds_read_b128 v[46:49], v0 offset:2560
	ds_read_b128 v[50:53], v0 offset:2576
	ds_read_b32 v32, v1 offset:4160
	v_sub_f32_e32 v10, v10, v34
	v_sub_f32_e32 v11, v11, v34
	v_sub_f32_e32 v12, v12, v34
	ds_write_b128 v2, v[110:113] offset:4352
	v_sub_f32_e32 v13, v13, v34
	v_sub_f32_e32 v14, v14, v34
	v_sub_f32_e32 v15, v15, v34
	v_lshlrev_b32_e32 v114, 16, v76
	v_sub_f32_e32 v16, v16, v34
	v_sub_f32_e32 v17, v17, v34
	v_fma_f32 v10, v54, v10, v34
	v_and_b32_e32 v115, 0xffff0000, v76
	v_fma_f32 v11, v55, v11, v34
	v_mul_f32_e32 v119, v38, v10
	v_fma_f32 v12, v56, v12, v34
	v_lshlrev_b32_e32 v116, 16, v77
	v_fmac_f32_e32 v119, v39, v11
	v_fma_f32 v13, v57, v13, v34
	v_fmac_f32_e32 v119, v40, v12
	v_and_b32_e32 v117, 0xffff0000, v77
	v_fma_f32 v14, v58, v14, v34
	v_fmac_f32_e32 v119, v41, v13
	v_fma_f32 v15, v59, v15, v34
	v_fmac_f32_e32 v119, v42, v14
	v_fma_f32 v16, v60, v16, v34
	v_fmac_f32_e32 v119, v43, v15
	v_fma_f32 v17, v61, v17, v34
	v_fmac_f32_e32 v119, v44, v16
	v_fmac_f32_e32 v119, v45, v17
	ds_write_b32 v128, v119 offset:8960
	s_waitcnt lgkmcnt(2)
	ds_read_b128 v[38:41], v0 offset:768
	ds_read_b128 v[42:45], v0 offset:784
	ds_read_b128 v[54:57], v0 offset:2816
	ds_read_b128 v[58:61], v0 offset:2832
	ds_read_b32 v34, v1 offset:4192
	v_sub_f32_e32 v10, v10, v32
	v_sub_f32_e32 v11, v11, v32
	v_sub_f32_e32 v12, v12, v32
	ds_write_b128 v2, v[114:117] offset:4368
	v_sub_f32_e32 v13, v13, v32
	v_sub_f32_e32 v14, v14, v32
	v_sub_f32_e32 v15, v15, v32
	s_waitcnt vmcnt(13)
	v_sub_f32_e32 v16, v16, v32
	v_sub_f32_e32 v17, v17, v32
	v_fma_f32 v10, v46, v10, v32
	ds_write_b128 v2, v[78:81] offset:6400
	v_fma_f32 v11, v47, v11, v32
	v_mul_f32_e32 v118, v24, v10
	v_fma_f32 v12, v48, v12, v32
	ds_write_b128 v2, v[82:85] offset:6416
	v_fmac_f32_e32 v118, v25, v11
	v_fma_f32 v13, v49, v13, v32
	v_fmac_f32_e32 v118, v26, v12
	s_waitcnt vmcnt(12)
	v_fma_f32 v14, v50, v14, v32
	v_fmac_f32_e32 v118, v27, v13
	v_fma_f32 v15, v51, v15, v32
	v_fmac_f32_e32 v118, v28, v14
	v_fma_f32 v16, v52, v16, v32
	v_fmac_f32_e32 v118, v29, v15
	v_fma_f32 v17, v53, v17, v32
	v_fmac_f32_e32 v118, v30, v16
	v_fmac_f32_e32 v118, v31, v17
	ds_write_b32 v128, v118 offset:9216
	s_waitcnt lgkmcnt(4)
	ds_read_b128 v[24:27], v0 offset:1024
	ds_read_b128 v[28:31], v0 offset:1040
	ds_read_b128 v[46:49], v0 offset:3072
	ds_read_b128 v[50:53], v0 offset:3088
	ds_read_b32 v32, v1 offset:4224
	v_sub_f32_e32 v10, v10, v34
	v_sub_f32_e32 v11, v11, v34
	v_sub_f32_e32 v12, v12, v34
	v_lshlrev_b32_e32 v33, 16, v33
	v_sub_f32_e32 v13, v13, v34
	v_sub_f32_e32 v14, v14, v34
	v_sub_f32_e32 v15, v15, v34
	s_nop 0
	v_sub_f32_e32 v16, v16, v34
	v_sub_f32_e32 v17, v17, v34
	v_fma_f32 v10, v54, v10, v34
	ds_write_b32 v4, v33 offset:8448
	v_fma_f32 v11, v55, v11, v34
	v_mul_f32_e32 v119, v38, v10
	v_fma_f32 v12, v56, v12, v34
	v_fmac_f32_e32 v119, v39, v11
	v_fma_f32 v13, v57, v13, v34
	v_fmac_f32_e32 v119, v40, v12
	v_fma_f32 v14, v58, v14, v34
	v_fmac_f32_e32 v119, v41, v13
	v_fma_f32 v15, v59, v15, v34
	v_fmac_f32_e32 v119, v42, v14
	v_fma_f32 v16, v60, v16, v34
	v_fmac_f32_e32 v119, v43, v15
	v_fma_f32 v17, v61, v17, v34
	v_fmac_f32_e32 v119, v44, v16
	v_fmac_f32_e32 v119, v45, v17
	ds_write_b32 v128, v119 offset:9472
	s_waitcnt lgkmcnt(2)
	ds_read_b128 v[38:41], v0 offset:1280
	ds_read_b128 v[42:45], v0 offset:1296
	ds_read_b128 v[54:57], v0 offset:3328
	ds_read_b128 v[58:61], v0 offset:3344
	ds_read_b32 v34, v1 offset:4256
	v_sub_f32_e32 v10, v10, v32
	v_sub_f32_e32 v11, v11, v32
	v_sub_f32_e32 v12, v12, v32
	global_load_dwordx4 v[74:77], v5, s[94:95]
	global_load_dwordx4 v[78:81], v8, s[94:95]
	global_load_dwordx4 v[82:85], v8, s[94:95] offset:16
	global_load_ushort v33, v6, s[94:95]
	v_add_u32_e32 v5, 0x6800, v5
	v_add_u32_e32 v8, 0x3180, v8
	v_add_u32_e32 v6, 0x10000, v6
	v_sub_f32_e32 v13, v13, v32
	v_sub_f32_e32 v14, v14, v32
	v_sub_f32_e32 v15, v15, v32
	ds_read_b128 v[132:135], v129 offset:10752
	v_sub_f32_e32 v16, v16, v32
	v_sub_f32_e32 v17, v17, v32
	v_fma_f32 v10, v46, v10, v32
	ds_read_b128 v[136:139], v130 offset:10752
	v_fma_f32 v11, v47, v11, v32
	v_mul_f32_e32 v118, v24, v10
	v_fma_f32 v12, v48, v12, v32
	v_fmac_f32_e32 v118, v25, v11
	v_fma_f32 v13, v49, v13, v32
	v_fmac_f32_e32 v118, v26, v12
	v_fma_f32 v14, v50, v14, v32
	v_fmac_f32_e32 v118, v27, v13
	v_fma_f32 v15, v51, v15, v32
	v_fmac_f32_e32 v118, v28, v14
	v_fma_f32 v16, v52, v16, v32
	v_fmac_f32_e32 v118, v29, v15
	v_fma_f32 v17, v53, v17, v32
	v_fmac_f32_e32 v118, v30, v16
	v_fmac_f32_e32 v118, v31, v17
	ds_write_b32 v128, v118 offset:9728
	s_waitcnt lgkmcnt(3)
	ds_read_b128 v[24:27], v0 offset:1536
	ds_read_b128 v[28:31], v0 offset:1552
	ds_read_b128 v[46:49], v0 offset:3584
	ds_read_b128 v[50:53], v0 offset:3600
	ds_read_b32 v32, v1 offset:4288
	v_sub_f32_e32 v10, v10, v34
	v_sub_f32_e32 v11, v11, v34
	v_sub_f32_e32 v12, v12, v34
	v_sub_f32_e32 v13, v13, v34
	v_sub_f32_e32 v14, v14, v34
	v_sub_f32_e32 v15, v15, v34
	v_sub_f32_e32 v16, v16, v34
	v_sub_f32_e32 v17, v17, v34
	v_fma_f32 v10, v54, v10, v34
	v_fma_f32 v11, v55, v11, v34
	v_mul_f32_e32 v119, v38, v10
	v_fma_f32 v12, v56, v12, v34
	v_fmac_f32_e32 v119, v39, v11
	v_fma_f32 v13, v57, v13, v34
	v_fmac_f32_e32 v119, v40, v12
	v_fma_f32 v14, v58, v14, v34
	v_fmac_f32_e32 v119, v41, v13
	v_fma_f32 v15, v59, v15, v34
	v_fmac_f32_e32 v119, v42, v14
	v_fma_f32 v16, v60, v16, v34
	v_fmac_f32_e32 v119, v43, v15
	v_fma_f32 v17, v61, v17, v34
	v_fmac_f32_e32 v119, v44, v16
	v_fmac_f32_e32 v119, v45, v17
	ds_write_b32 v128, v119 offset:9984
	s_waitcnt lgkmcnt(1)
	ds_read_b128 v[38:41], v0 offset:1792
	ds_read_b128 v[42:45], v0 offset:1808
	ds_read_b128 v[54:57], v0 offset:3840
	ds_read_b128 v[58:61], v0 offset:3856
	ds_read_b32 v34, v1 offset:4320
	v_sub_f32_e32 v10, v10, v32
	v_sub_f32_e32 v11, v11, v32
	v_sub_f32_e32 v12, v12, v32
	s_waitcnt lgkmcnt(12)
	v_sub_f32_e32 v13, v13, v32
	v_sub_f32_e32 v14, v14, v32
	v_sub_f32_e32 v15, v15, v32
	v_add_f32_e32 v132, v132, v136
	v_sub_f32_e32 v16, v16, v32
	v_sub_f32_e32 v17, v17, v32
	v_fma_f32 v10, v46, v10, v32
	v_add_f32_e32 v133, v133, v137
	v_fma_f32 v11, v47, v11, v32
	v_mul_f32_e32 v118, v24, v10
	v_fma_f32 v12, v48, v12, v32
	v_add_f32_e32 v134, v134, v138
	v_fmac_f32_e32 v118, v25, v11
	v_fma_f32 v13, v49, v13, v32
	v_fmac_f32_e32 v118, v26, v12
	v_add_f32_e32 v135, v135, v139
	v_fma_f32 v14, v50, v14, v32
	v_fmac_f32_e32 v118, v27, v13
	v_fma_f32 v15, v51, v15, v32
	v_add_f32_e32 v132, v132, v133
	v_fmac_f32_e32 v118, v28, v14
	v_fma_f32 v16, v52, v16, v32
	v_fmac_f32_e32 v118, v29, v15
	v_add_f32_e32 v134, v134, v135
	v_fma_f32 v17, v53, v17, v32
	v_fmac_f32_e32 v118, v30, v16
	v_fmac_f32_e32 v118, v31, v17
	v_add_f32_e32 v132, v132, v134
	ds_write_b32 v128, v118 offset:10240
	v_cvt_pk_bf16_f32 v22, v132, v132
	ds_write_b16 v121, v22 offset:13696
	v_add_u32_e32 v121, 0x200, v121
	s_and_b32 s24, s12, 15
	s_cmp_eq_u32 s24, 0
	s_cbranch_scc0 .Lls2_8_noflush
	s_cmp_eq_u32 s12, 64
	s_cbranch_scc1 .Lls2_8_noflush
	s_waitcnt lgkmcnt(0)
	ds_read_b128 v[124:127], v122 offset:13312
	s_waitcnt lgkmcnt(0)
	global_store_dwordx4 v7, v[124:127], s[94:95]
	v_add_u32_e32 v7, 0x20000, v7
	s_nop 0
	ds_read_b128 v[124:127], v122 offset:14336
	s_waitcnt lgkmcnt(0)
	global_store_dwordx4 v7, v[124:127], s[94:95]
	v_add_u32_e32 v7, 0x20000, v7
	s_nop 0
	ds_read_b128 v[124:127], v122 offset:15360
	s_waitcnt lgkmcnt(0)
	global_store_dwordx4 v7, v[124:127], s[94:95]
	v_add_u32_e32 v7, 0x20000, v7
	s_nop 0
	ds_read_b128 v[124:127], v122 offset:16384
	s_waitcnt lgkmcnt(0)
	global_store_dwordx4 v7, v[124:127], s[94:95]
	v_add_u32_e32 v7, 0x20000, v7
	s_nop 0
	ds_read_b128 v[124:127], v122 offset:17408
	s_waitcnt lgkmcnt(0)
	global_store_dwordx4 v7, v[124:127], s[94:95]
	v_add_u32_e32 v7, 0x20000, v7
	s_nop 0
	ds_read_b128 v[124:127], v122 offset:18432
	s_waitcnt lgkmcnt(0)
	global_store_dwordx4 v7, v[124:127], s[94:95]
	v_add_u32_e32 v7, 0x20000, v7
	s_nop 0
	ds_read_b128 v[124:127], v122 offset:19456
	s_waitcnt lgkmcnt(0)
	global_store_dwordx4 v7, v[124:127], s[94:95]
	v_add_u32_e32 v7, 0x20000, v7
	s_nop 0
	ds_read_b128 v[124:127], v122 offset:20480
	s_waitcnt lgkmcnt(0)
	global_store_dwordx4 v7, v[124:127], s[94:95]
	v_add_u32_e32 v7, 0x20000, v7
	s_nop 0
	v_subrev_u32_e32 v121, 0x2000, v121
.Lls2_8_noflush:
	s_waitcnt lgkmcnt(2)
	ds_read_b128 v[24:27], v0 offset:4352
	ds_read_b128 v[28:31], v0 offset:4368
	ds_read_b128 v[46:49], v0 offset:6400
	ds_read_b128 v[50:53], v0 offset:6416
	ds_read_b32 v32, v1 offset:8448
	v_sub_f32_e32 v10, v10, v34
	v_sub_f32_e32 v11, v11, v34
	v_sub_f32_e32 v12, v12, v34
	v_sub_f32_e32 v13, v13, v34
	v_sub_f32_e32 v14, v14, v34
	v_sub_f32_e32 v15, v15, v34
	v_sub_f32_e32 v16, v16, v34
	v_sub_f32_e32 v17, v17, v34
	v_fma_f32 v10, v54, v10, v34
	v_fma_f32 v11, v55, v11, v34
	v_mul_f32_e32 v119, v38, v10
	v_fma_f32 v12, v56, v12, v34
	v_fmac_f32_e32 v119, v39, v11
	v_fma_f32 v13, v57, v13, v34
	v_fmac_f32_e32 v119, v40, v12
	v_fma_f32 v14, v58, v14, v34
	v_fmac_f32_e32 v119, v41, v13
	v_fma_f32 v15, v59, v15, v34
	v_fmac_f32_e32 v119, v42, v14
	v_fma_f32 v16, v60, v16, v34
	v_fmac_f32_e32 v119, v43, v15
	v_fma_f32 v17, v61, v17, v34
	v_fmac_f32_e32 v119, v44, v16
	v_fmac_f32_e32 v119, v45, v17
	ds_write_b32 v128, v119 offset:10496
	s_waitcnt lgkmcnt(1)
	ds_read_b128 v[38:41], v0 offset:4608
	ds_read_b128 v[42:45], v0 offset:4624
	ds_read_b128 v[54:57], v0 offset:6656
	ds_read_b128 v[58:61], v0 offset:6672
	ds_read_b32 v34, v1 offset:8480
	v_sub_f32_e32 v10, v10, v32
	v_sub_f32_e32 v11, v11, v32
	v_sub_f32_e32 v12, v12, v32
	s_waitcnt vmcnt(15)
	v_sub_f32_e32 v13, v13, v32
	v_sub_f32_e32 v14, v14, v32
	v_sub_f32_e32 v15, v15, v32
	v_lshlrev_b32_e32 v110, 16, v86
	v_sub_f32_e32 v16, v16, v32
	v_sub_f32_e32 v17, v17, v32
	v_fma_f32 v10, v46, v10, v32
	v_and_b32_e32 v111, 0xffff0000, v86
	v_fma_f32 v11, v47, v11, v32
	v_mul_f32_e32 v118, v24, v10
	v_fma_f32 v12, v48, v12, v32
	v_lshlrev_b32_e32 v112, 16, v87
	v_fmac_f32_e32 v118, v25, v11
	v_fma_f32 v13, v49, v13, v32
	v_fmac_f32_e32 v118, v26, v12
	v_and_b32_e32 v113, 0xffff0000, v87
	v_fma_f32 v14, v50, v14, v32
	v_fmac_f32_e32 v118, v27, v13
	v_fma_f32 v15, v51, v15, v32
	v_fmac_f32_e32 v118, v28, v14
	v_fma_f32 v16, v52, v16, v32
	v_fmac_f32_e32 v118, v29, v15
	v_fma_f32 v17, v53, v17, v32
	v_fmac_f32_e32 v118, v30, v16
	v_fmac_f32_e32 v118, v31, v17
	ds_write_b32 v128, v118 offset:10752
	s_waitcnt lgkmcnt(1)
	ds_read_b128 v[24:27], v0 offset:4864
	ds_read_b128 v[28:31], v0 offset:4880
	ds_read_b128 v[46:49], v0 offset:6912
	ds_read_b128 v[50:53], v0 offset:6928
	ds_read_b32 v32, v1 offset:8512
	v_sub_f32_e32 v10, v10, v34
	v_sub_f32_e32 v11, v11, v34
	v_sub_f32_e32 v12, v12, v34
	ds_write_b128 v2, v[110:113] offset:0
	v_sub_f32_e32 v13, v13, v34
	v_sub_f32_e32 v14, v14, v34
	v_sub_f32_e32 v15, v15, v34
	v_lshlrev_b32_e32 v114, 16, v88
	v_sub_f32_e32 v16, v16, v34
	v_sub_f32_e32 v17, v17, v34
	v_fma_f32 v10, v54, v10, v34
	v_and_b32_e32 v115, 0xffff0000, v88
	v_fma_f32 v11, v55, v11, v34
	v_mul_f32_e32 v119, v38, v10
	v_fma_f32 v12, v56, v12, v34
	v_lshlrev_b32_e32 v116, 16, v89
	v_fmac_f32_e32 v119, v39, v11
	v_fma_f32 v13, v57, v13, v34
	v_fmac_f32_e32 v119, v40, v12
	v_and_b32_e32 v117, 0xffff0000, v89
	v_fma_f32 v14, v58, v14, v34
	v_fmac_f32_e32 v119, v41, v13
	v_fma_f32 v15, v59, v15, v34
	v_fmac_f32_e32 v119, v42, v14
	v_fma_f32 v16, v60, v16, v34
	v_fmac_f32_e32 v119, v43, v15
	v_fma_f32 v17, v61, v17, v34
	v_fmac_f32_e32 v119, v44, v16
	v_fmac_f32_e32 v119, v45, v17
	ds_write_b32 v128, v119 offset:11008
	s_waitcnt lgkmcnt(2)
	ds_read_b128 v[38:41], v0 offset:5120
	ds_read_b128 v[42:45], v0 offset:5136
	ds_read_b128 v[54:57], v0 offset:7168
	ds_read_b128 v[58:61], v0 offset:7184
	ds_read_b32 v34, v1 offset:8544
	v_sub_f32_e32 v10, v10, v32
	v_sub_f32_e32 v11, v11, v32
	v_sub_f32_e32 v12, v12, v32
	ds_write_b128 v2, v[114:117] offset:16
	v_sub_f32_e32 v13, v13, v32
	v_sub_f32_e32 v14, v14, v32
	v_sub_f32_e32 v15, v15, v32
	s_waitcnt vmcnt(13)
	v_sub_f32_e32 v16, v16, v32
	v_sub_f32_e32 v17, v17, v32
	v_fma_f32 v10, v46, v10, v32
	ds_write_b128 v2, v[90:93] offset:2048
	v_fma_f32 v11, v47, v11, v32
	v_mul_f32_e32 v118, v24, v10
	v_fma_f32 v12, v48, v12, v32
	ds_write_b128 v2, v[94:97] offset:2064
	v_fmac_f32_e32 v118, v25, v11
	v_fma_f32 v13, v49, v13, v32
	v_fmac_f32_e32 v118, v26, v12
	s_waitcnt vmcnt(12)
	v_fma_f32 v14, v50, v14, v32
	v_fmac_f32_e32 v118, v27, v13
	v_fma_f32 v15, v51, v15, v32
	v_fmac_f32_e32 v118, v28, v14
	v_fma_f32 v16, v52, v16, v32
	v_fmac_f32_e32 v118, v29, v15
	v_fma_f32 v17, v53, v17, v32
	v_fmac_f32_e32 v118, v30, v16
	v_fmac_f32_e32 v118, v31, v17
	ds_write_b32 v128, v118 offset:11264
	s_waitcnt lgkmcnt(4)
	ds_read_b128 v[24:27], v0 offset:5376
	ds_read_b128 v[28:31], v0 offset:5392
	ds_read_b128 v[46:49], v0 offset:7424
	ds_read_b128 v[50:53], v0 offset:7440
	ds_read_b32 v32, v1 offset:8576
	v_sub_f32_e32 v10, v10, v34
	v_sub_f32_e32 v11, v11, v34
	v_sub_f32_e32 v12, v12, v34
	v_lshlrev_b32_e32 v35, 16, v35
	v_sub_f32_e32 v13, v13, v34
	v_sub_f32_e32 v14, v14, v34
	v_sub_f32_e32 v15, v15, v34
	s_nop 0
	v_sub_f32_e32 v16, v16, v34
	v_sub_f32_e32 v17, v17, v34
	v_fma_f32 v10, v54, v10, v34
	ds_write_b32 v4, v35 offset:4096
	v_fma_f32 v11, v55, v11, v34
	v_mul_f32_e32 v119, v38, v10
	v_fma_f32 v12, v56, v12, v34
	v_fmac_f32_e32 v119, v39, v11
	v_fma_f32 v13, v57, v13, v34
	v_fmac_f32_e32 v119, v40, v12
	v_fma_f32 v14, v58, v14, v34
	v_fmac_f32_e32 v119, v41, v13
	v_fma_f32 v15, v59, v15, v34
	v_fmac_f32_e32 v119, v42, v14
	v_fma_f32 v16, v60, v16, v34
	v_fmac_f32_e32 v119, v43, v15
	v_fma_f32 v17, v61, v17, v34
	v_fmac_f32_e32 v119, v44, v16
	v_fmac_f32_e32 v119, v45, v17
	ds_write_b32 v128, v119 offset:11520
	s_waitcnt lgkmcnt(2)
	ds_read_b128 v[38:41], v0 offset:5632
	ds_read_b128 v[42:45], v0 offset:5648
	ds_read_b128 v[54:57], v0 offset:7680
	ds_read_b128 v[58:61], v0 offset:7696
	ds_read_b32 v34, v1 offset:8608
	v_sub_f32_e32 v10, v10, v32
	v_sub_f32_e32 v11, v11, v32
	v_sub_f32_e32 v12, v12, v32
	global_load_dwordx4 v[86:89], v5, s[94:95]
	global_load_dwordx4 v[90:93], v8, s[94:95]
	global_load_dwordx4 v[94:97], v8, s[94:95] offset:16
	global_load_ushort v35, v6, s[94:95]
	v_add_u32_e32 v5, 0x6800, v5
	v_add_u32_e32 v8, 0x3180, v8
	v_add_u32_e32 v6, 0x10000, v6
	v_sub_f32_e32 v13, v13, v32
	v_sub_f32_e32 v14, v14, v32
	v_sub_f32_e32 v15, v15, v32
	ds_read_b128 v[132:135], v129 offset:8704
	v_sub_f32_e32 v16, v16, v32
	v_sub_f32_e32 v17, v17, v32
	v_fma_f32 v10, v46, v10, v32
	ds_read_b128 v[136:139], v130 offset:8704
	v_fma_f32 v11, v47, v11, v32
	v_mul_f32_e32 v118, v24, v10
	v_fma_f32 v12, v48, v12, v32
	v_fmac_f32_e32 v118, v25, v11
	v_fma_f32 v13, v49, v13, v32
	v_fmac_f32_e32 v118, v26, v12
	v_fma_f32 v14, v50, v14, v32
	v_fmac_f32_e32 v118, v27, v13
	v_fma_f32 v15, v51, v15, v32
	v_fmac_f32_e32 v118, v28, v14
	v_fma_f32 v16, v52, v16, v32
	v_fmac_f32_e32 v118, v29, v15
	v_fma_f32 v17, v53, v17, v32
	v_fmac_f32_e32 v118, v30, v16
	v_fmac_f32_e32 v118, v31, v17
	ds_write_b32 v128, v118 offset:11776
	s_waitcnt lgkmcnt(3)
	ds_read_b128 v[24:27], v0 offset:5888
	ds_read_b128 v[28:31], v0 offset:5904
	ds_read_b128 v[46:49], v0 offset:7936
	ds_read_b128 v[50:53], v0 offset:7952
	ds_read_b32 v32, v1 offset:8640
	v_sub_f32_e32 v10, v10, v34
	v_sub_f32_e32 v11, v11, v34
	v_sub_f32_e32 v12, v12, v34
	v_sub_f32_e32 v13, v13, v34
	v_sub_f32_e32 v14, v14, v34
	v_sub_f32_e32 v15, v15, v34
	v_sub_f32_e32 v16, v16, v34
	v_sub_f32_e32 v17, v17, v34
	v_fma_f32 v10, v54, v10, v34
	v_fma_f32 v11, v55, v11, v34
	v_mul_f32_e32 v119, v38, v10
	v_fma_f32 v12, v56, v12, v34
	v_fmac_f32_e32 v119, v39, v11
	v_fma_f32 v13, v57, v13, v34
	v_fmac_f32_e32 v119, v40, v12
	v_fma_f32 v14, v58, v14, v34
	v_fmac_f32_e32 v119, v41, v13
	v_fma_f32 v15, v59, v15, v34
	v_fmac_f32_e32 v119, v42, v14
	v_fma_f32 v16, v60, v16, v34
	v_fmac_f32_e32 v119, v43, v15
	v_fma_f32 v17, v61, v17, v34
	v_fmac_f32_e32 v119, v44, v16
	v_fmac_f32_e32 v119, v45, v17
	ds_write_b32 v128, v119 offset:12032
	s_waitcnt lgkmcnt(1)
	ds_read_b128 v[38:41], v0 offset:6144
	ds_read_b128 v[42:45], v0 offset:6160
	ds_read_b128 v[54:57], v0 offset:8192
	ds_read_b128 v[58:61], v0 offset:8208
	ds_read_b32 v34, v1 offset:8672
	v_sub_f32_e32 v10, v10, v32
	v_sub_f32_e32 v11, v11, v32
	v_sub_f32_e32 v12, v12, v32
	s_waitcnt lgkmcnt(12)
	v_sub_f32_e32 v13, v13, v32
	v_sub_f32_e32 v14, v14, v32
	v_sub_f32_e32 v15, v15, v32
	v_add_f32_e32 v132, v132, v136
	v_sub_f32_e32 v16, v16, v32
	v_sub_f32_e32 v17, v17, v32
	v_fma_f32 v10, v46, v10, v32
	v_add_f32_e32 v133, v133, v137
	v_fma_f32 v11, v47, v11, v32
	v_mul_f32_e32 v118, v24, v10
	v_fma_f32 v12, v48, v12, v32
	v_add_f32_e32 v134, v134, v138
	v_fmac_f32_e32 v118, v25, v11
	v_fma_f32 v13, v49, v13, v32
	v_fmac_f32_e32 v118, v26, v12
	v_add_f32_e32 v135, v135, v139
	v_fma_f32 v14, v50, v14, v32
	v_fmac_f32_e32 v118, v27, v13
	v_fma_f32 v15, v51, v15, v32
	v_add_f32_e32 v132, v132, v133
	v_fmac_f32_e32 v118, v28, v14
	v_fma_f32 v16, v52, v16, v32
	v_fmac_f32_e32 v118, v29, v15
	v_add_f32_e32 v134, v134, v135
	v_fma_f32 v17, v53, v17, v32
	v_fmac_f32_e32 v118, v30, v16
	v_fmac_f32_e32 v118, v31, v17
	v_add_f32_e32 v132, v132, v134
	ds_write_b32 v128, v118 offset:12288
	v_cvt_pk_bf16_f32 v22, v132, v132
	ds_write_b16 v121, v22 offset:13312
	s_waitcnt lgkmcnt(2)
	ds_read_b128 v[24:27], v0 offset:0
	ds_read_b128 v[28:31], v0 offset:16
	ds_read_b128 v[46:49], v0 offset:2048
	ds_read_b128 v[50:53], v0 offset:2064
	ds_read_b32 v32, v1 offset:4096
	v_sub_f32_e32 v10, v10, v34
	v_sub_f32_e32 v11, v11, v34
	v_sub_f32_e32 v12, v12, v34
	v_sub_f32_e32 v13, v13, v34
	v_sub_f32_e32 v14, v14, v34
	v_sub_f32_e32 v15, v15, v34
	v_sub_f32_e32 v16, v16, v34
	v_sub_f32_e32 v17, v17, v34
	v_fma_f32 v10, v54, v10, v34
	v_fma_f32 v11, v55, v11, v34
	v_mul_f32_e32 v119, v38, v10
	v_fma_f32 v12, v56, v12, v34
	v_fmac_f32_e32 v119, v39, v11
	v_fma_f32 v13, v57, v13, v34
	v_fmac_f32_e32 v119, v40, v12
	v_fma_f32 v14, v58, v14, v34
	v_fmac_f32_e32 v119, v41, v13
	v_fma_f32 v15, v59, v15, v34
	v_fmac_f32_e32 v119, v42, v14
	v_fma_f32 v16, v60, v16, v34
	v_fmac_f32_e32 v119, v43, v15
	v_fma_f32 v17, v61, v17, v34
	v_fmac_f32_e32 v119, v44, v16
	v_fmac_f32_e32 v119, v45, v17
	ds_write_b32 v128, v119 offset:12544
	s_waitcnt lgkmcnt(1)
	ds_read_b128 v[38:41], v0 offset:256
	ds_read_b128 v[42:45], v0 offset:272
	ds_read_b128 v[54:57], v0 offset:2304
	ds_read_b128 v[58:61], v0 offset:2320
	ds_read_b32 v34, v1 offset:4128
	v_sub_f32_e32 v10, v10, v32
	v_sub_f32_e32 v11, v11, v32
	v_sub_f32_e32 v12, v12, v32
	s_waitcnt vmcnt(15)
	v_sub_f32_e32 v13, v13, v32
	v_sub_f32_e32 v14, v14, v32
	v_sub_f32_e32 v15, v15, v32
	v_lshlrev_b32_e32 v110, 16, v98
	v_sub_f32_e32 v16, v16, v32
	v_sub_f32_e32 v17, v17, v32
	v_fma_f32 v10, v46, v10, v32
	v_and_b32_e32 v111, 0xffff0000, v98
	v_fma_f32 v11, v47, v11, v32
	v_mul_f32_e32 v118, v24, v10
	v_fma_f32 v12, v48, v12, v32
	v_lshlrev_b32_e32 v112, 16, v99
	v_fmac_f32_e32 v118, v25, v11
	v_fma_f32 v13, v49, v13, v32
	v_fmac_f32_e32 v118, v26, v12
	v_and_b32_e32 v113, 0xffff0000, v99
	v_fma_f32 v14, v50, v14, v32
	v_fmac_f32_e32 v118, v27, v13
	v_fma_f32 v15, v51, v15, v32
	v_fmac_f32_e32 v118, v28, v14
	v_fma_f32 v16, v52, v16, v32
	v_fmac_f32_e32 v118, v29, v15
	v_fma_f32 v17, v53, v17, v32
	v_fmac_f32_e32 v118, v30, v16
	v_fmac_f32_e32 v118, v31, v17
	ds_write_b32 v128, v118 offset:8704
	s_waitcnt lgkmcnt(1)
	ds_read_b128 v[24:27], v0 offset:512
	ds_read_b128 v[28:31], v0 offset:528
	ds_read_b128 v[46:49], v0 offset:2560
	ds_read_b128 v[50:53], v0 offset:2576
	ds_read_b32 v32, v1 offset:4160
	v_sub_f32_e32 v10, v10, v34
	v_sub_f32_e32 v11, v11, v34
	v_sub_f32_e32 v12, v12, v34
	ds_write_b128 v2, v[110:113] offset:4352
	v_sub_f32_e32 v13, v13, v34
	v_sub_f32_e32 v14, v14, v34
	v_sub_f32_e32 v15, v15, v34
	v_lshlrev_b32_e32 v114, 16, v100
	v_sub_f32_e32 v16, v16, v34
	v_sub_f32_e32 v17, v17, v34
	v_fma_f32 v10, v54, v10, v34
	v_and_b32_e32 v115, 0xffff0000, v100
	v_fma_f32 v11, v55, v11, v34
	v_mul_f32_e32 v119, v38, v10
	v_fma_f32 v12, v56, v12, v34
	v_lshlrev_b32_e32 v116, 16, v101
	v_fmac_f32_e32 v119, v39, v11
	v_fma_f32 v13, v57, v13, v34
	v_fmac_f32_e32 v119, v40, v12
	v_and_b32_e32 v117, 0xffff0000, v101
	v_fma_f32 v14, v58, v14, v34
	v_fmac_f32_e32 v119, v41, v13
	v_fma_f32 v15, v59, v15, v34
	v_fmac_f32_e32 v119, v42, v14
	v_fma_f32 v16, v60, v16, v34
	v_fmac_f32_e32 v119, v43, v15
	v_fma_f32 v17, v61, v17, v34
	v_fmac_f32_e32 v119, v44, v16
	v_fmac_f32_e32 v119, v45, v17
	ds_write_b32 v128, v119 offset:8960
	s_waitcnt lgkmcnt(2)
	ds_read_b128 v[38:41], v0 offset:768
	ds_read_b128 v[42:45], v0 offset:784
	ds_read_b128 v[54:57], v0 offset:2816
	ds_read_b128 v[58:61], v0 offset:2832
	ds_read_b32 v34, v1 offset:4192
	v_sub_f32_e32 v10, v10, v32
	v_sub_f32_e32 v11, v11, v32
	v_sub_f32_e32 v12, v12, v32
	ds_write_b128 v2, v[114:117] offset:4368
	v_sub_f32_e32 v13, v13, v32
	v_sub_f32_e32 v14, v14, v32
	v_sub_f32_e32 v15, v15, v32
	s_waitcnt vmcnt(13)
	v_sub_f32_e32 v16, v16, v32
	v_sub_f32_e32 v17, v17, v32
	v_fma_f32 v10, v46, v10, v32
	ds_write_b128 v2, v[102:105] offset:6400
	v_fma_f32 v11, v47, v11, v32
	v_mul_f32_e32 v118, v24, v10
	v_fma_f32 v12, v48, v12, v32
	ds_write_b128 v2, v[106:109] offset:6416
	v_fmac_f32_e32 v118, v25, v11
	v_fma_f32 v13, v49, v13, v32
	v_fmac_f32_e32 v118, v26, v12
	s_waitcnt vmcnt(12)
	v_fma_f32 v14, v50, v14, v32
	v_fmac_f32_e32 v118, v27, v13
	v_fma_f32 v15, v51, v15, v32
	v_fmac_f32_e32 v118, v28, v14
	v_fma_f32 v16, v52, v16, v32
	v_fmac_f32_e32 v118, v29, v15
	v_fma_f32 v17, v53, v17, v32
	v_fmac_f32_e32 v118, v30, v16
	v_fmac_f32_e32 v118, v31, v17
	ds_write_b32 v128, v118 offset:9216
	s_waitcnt lgkmcnt(4)
	ds_read_b128 v[24:27], v0 offset:1024
	ds_read_b128 v[28:31], v0 offset:1040
	ds_read_b128 v[46:49], v0 offset:3072
	ds_read_b128 v[50:53], v0 offset:3088
	ds_read_b32 v32, v1 offset:4224
	v_sub_f32_e32 v10, v10, v34
	v_sub_f32_e32 v11, v11, v34
	v_sub_f32_e32 v12, v12, v34
	v_lshlrev_b32_e32 v36, 16, v36
	v_sub_f32_e32 v13, v13, v34
	v_sub_f32_e32 v14, v14, v34
	v_sub_f32_e32 v15, v15, v34
	s_nop 0
	v_sub_f32_e32 v16, v16, v34
	v_sub_f32_e32 v17, v17, v34
	v_fma_f32 v10, v54, v10, v34
	ds_write_b32 v4, v36 offset:8448
	v_fma_f32 v11, v55, v11, v34
	v_mul_f32_e32 v119, v38, v10
	v_fma_f32 v12, v56, v12, v34
	v_fmac_f32_e32 v119, v39, v11
	v_fma_f32 v13, v57, v13, v34
	v_fmac_f32_e32 v119, v40, v12
	v_fma_f32 v14, v58, v14, v34
	v_fmac_f32_e32 v119, v41, v13
	v_fma_f32 v15, v59, v15, v34
	v_fmac_f32_e32 v119, v42, v14
	v_fma_f32 v16, v60, v16, v34
	v_fmac_f32_e32 v119, v43, v15
	v_fma_f32 v17, v61, v17, v34
	v_fmac_f32_e32 v119, v44, v16
	v_fmac_f32_e32 v119, v45, v17
	ds_write_b32 v128, v119 offset:9472
	s_waitcnt lgkmcnt(2)
	ds_read_b128 v[38:41], v0 offset:1280
	ds_read_b128 v[42:45], v0 offset:1296
	ds_read_b128 v[54:57], v0 offset:3328
	ds_read_b128 v[58:61], v0 offset:3344
	ds_read_b32 v34, v1 offset:4256
	v_sub_f32_e32 v10, v10, v32
	v_sub_f32_e32 v11, v11, v32
	v_sub_f32_e32 v12, v12, v32
	global_load_dwordx4 v[98:101], v5, s[94:95]
	global_load_dwordx4 v[102:105], v8, s[94:95]
	global_load_dwordx4 v[106:109], v8, s[94:95] offset:16
	global_load_ushort v36, v6, s[94:95]
	v_add_u32_e32 v5, 0x6800, v5
	v_add_u32_e32 v8, 0x3180, v8
	v_add_u32_e32 v6, 0x10000, v6
	v_sub_f32_e32 v13, v13, v32
	v_sub_f32_e32 v14, v14, v32
	v_sub_f32_e32 v15, v15, v32
	ds_read_b128 v[132:135], v129 offset:10752
	v_sub_f32_e32 v16, v16, v32
	v_sub_f32_e32 v17, v17, v32
	v_fma_f32 v10, v46, v10, v32
	ds_read_b128 v[136:139], v130 offset:10752
	v_fma_f32 v11, v47, v11, v32
	v_mul_f32_e32 v118, v24, v10
	v_fma_f32 v12, v48, v12, v32
	v_fmac_f32_e32 v118, v25, v11
	v_fma_f32 v13, v49, v13, v32
	v_fmac_f32_e32 v118, v26, v12
	v_fma_f32 v14, v50, v14, v32
	v_fmac_f32_e32 v118, v27, v13
	v_fma_f32 v15, v51, v15, v32
	v_fmac_f32_e32 v118, v28, v14
	v_fma_f32 v16, v52, v16, v32
	v_fmac_f32_e32 v118, v29, v15
	v_fma_f32 v17, v53, v17, v32
	v_fmac_f32_e32 v118, v30, v16
	v_fmac_f32_e32 v118, v31, v17
	ds_write_b32 v128, v118 offset:9728
	s_waitcnt lgkmcnt(3)
	ds_read_b128 v[24:27], v0 offset:1536
	ds_read_b128 v[28:31], v0 offset:1552
	ds_read_b128 v[46:49], v0 offset:3584
	ds_read_b128 v[50:53], v0 offset:3600
	ds_read_b32 v32, v1 offset:4288
	v_sub_f32_e32 v10, v10, v34
	v_sub_f32_e32 v11, v11, v34
	v_sub_f32_e32 v12, v12, v34
	v_sub_f32_e32 v13, v13, v34
	v_sub_f32_e32 v14, v14, v34
	v_sub_f32_e32 v15, v15, v34
	v_sub_f32_e32 v16, v16, v34
	v_sub_f32_e32 v17, v17, v34
	v_fma_f32 v10, v54, v10, v34
	v_fma_f32 v11, v55, v11, v34
	v_mul_f32_e32 v119, v38, v10
	v_fma_f32 v12, v56, v12, v34
	v_fmac_f32_e32 v119, v39, v11
	v_fma_f32 v13, v57, v13, v34
	v_fmac_f32_e32 v119, v40, v12
	v_fma_f32 v14, v58, v14, v34
	v_fmac_f32_e32 v119, v41, v13
	v_fma_f32 v15, v59, v15, v34
	v_fmac_f32_e32 v119, v42, v14
	v_fma_f32 v16, v60, v16, v34
	v_fmac_f32_e32 v119, v43, v15
	v_fma_f32 v17, v61, v17, v34
	v_fmac_f32_e32 v119, v44, v16
	v_fmac_f32_e32 v119, v45, v17
	ds_write_b32 v128, v119 offset:9984
	s_waitcnt lgkmcnt(1)
	ds_read_b128 v[38:41], v0 offset:1792
	ds_read_b128 v[42:45], v0 offset:1808
	ds_read_b128 v[54:57], v0 offset:3840
	ds_read_b128 v[58:61], v0 offset:3856
	ds_read_b32 v34, v1 offset:4320
	v_sub_f32_e32 v10, v10, v32
	v_sub_f32_e32 v11, v11, v32
	v_sub_f32_e32 v12, v12, v32
	s_waitcnt lgkmcnt(12)
	v_sub_f32_e32 v13, v13, v32
	v_sub_f32_e32 v14, v14, v32
	v_sub_f32_e32 v15, v15, v32
	v_add_f32_e32 v132, v132, v136
	v_sub_f32_e32 v16, v16, v32
	v_sub_f32_e32 v17, v17, v32
	v_fma_f32 v10, v46, v10, v32
	v_add_f32_e32 v133, v133, v137
	v_fma_f32 v11, v47, v11, v32
	v_mul_f32_e32 v118, v24, v10
	v_fma_f32 v12, v48, v12, v32
	v_add_f32_e32 v134, v134, v138
	v_fmac_f32_e32 v118, v25, v11
	v_fma_f32 v13, v49, v13, v32
	v_fmac_f32_e32 v118, v26, v12
	v_add_f32_e32 v135, v135, v139
	v_fma_f32 v14, v50, v14, v32
	v_fmac_f32_e32 v118, v27, v13
	v_fma_f32 v15, v51, v15, v32
	v_add_f32_e32 v132, v132, v133
	v_fmac_f32_e32 v118, v28, v14
	v_fma_f32 v16, v52, v16, v32
	v_fmac_f32_e32 v118, v29, v15
	v_add_f32_e32 v134, v134, v135
	v_fma_f32 v17, v53, v17, v32
	v_fmac_f32_e32 v118, v30, v16
	v_fmac_f32_e32 v118, v31, v17
	v_add_f32_e32 v132, v132, v134
	ds_write_b32 v128, v118 offset:10240
	v_cvt_pk_bf16_f32 v22, v132, v132
	ds_write_b16 v121, v22 offset:13440
	s_waitcnt lgkmcnt(2)
	ds_read_b128 v[24:27], v0 offset:4352
	ds_read_b128 v[28:31], v0 offset:4368
	ds_read_b128 v[46:49], v0 offset:6400
	ds_read_b128 v[50:53], v0 offset:6416
	ds_read_b32 v32, v1 offset:8448
	v_sub_f32_e32 v10, v10, v34
	v_sub_f32_e32 v11, v11, v34
	v_sub_f32_e32 v12, v12, v34
	v_sub_f32_e32 v13, v13, v34
	v_sub_f32_e32 v14, v14, v34
	v_sub_f32_e32 v15, v15, v34
	v_sub_f32_e32 v16, v16, v34
	v_sub_f32_e32 v17, v17, v34
	v_fma_f32 v10, v54, v10, v34
	v_fma_f32 v11, v55, v11, v34
	v_mul_f32_e32 v119, v38, v10
	v_fma_f32 v12, v56, v12, v34
	v_fmac_f32_e32 v119, v39, v11
	v_fma_f32 v13, v57, v13, v34
	v_fmac_f32_e32 v119, v40, v12
	v_fma_f32 v14, v58, v14, v34
	v_fmac_f32_e32 v119, v41, v13
	v_fma_f32 v15, v59, v15, v34
	v_fmac_f32_e32 v119, v42, v14
	v_fma_f32 v16, v60, v16, v34
	v_fmac_f32_e32 v119, v43, v15
	v_fma_f32 v17, v61, v17, v34
	v_fmac_f32_e32 v119, v44, v16
	v_fmac_f32_e32 v119, v45, v17
	ds_write_b32 v128, v119 offset:10496
	s_waitcnt lgkmcnt(1)
	ds_read_b128 v[38:41], v0 offset:4608
	ds_read_b128 v[42:45], v0 offset:4624
	ds_read_b128 v[54:57], v0 offset:6656
	ds_read_b128 v[58:61], v0 offset:6672
	ds_read_b32 v34, v1 offset:8480
	v_sub_f32_e32 v10, v10, v32
	v_sub_f32_e32 v11, v11, v32
	v_sub_f32_e32 v12, v12, v32
	s_waitcnt vmcnt(15)
	v_sub_f32_e32 v13, v13, v32
	v_sub_f32_e32 v14, v14, v32
	v_sub_f32_e32 v15, v15, v32
	v_lshlrev_b32_e32 v110, 16, v62
	v_sub_f32_e32 v16, v16, v32
	v_sub_f32_e32 v17, v17, v32
	v_fma_f32 v10, v46, v10, v32
	v_and_b32_e32 v111, 0xffff0000, v62
	v_fma_f32 v11, v47, v11, v32
	v_mul_f32_e32 v118, v24, v10
	v_fma_f32 v12, v48, v12, v32
	v_lshlrev_b32_e32 v112, 16, v63
	v_fmac_f32_e32 v118, v25, v11
	v_fma_f32 v13, v49, v13, v32
	v_fmac_f32_e32 v118, v26, v12
	v_and_b32_e32 v113, 0xffff0000, v63
	v_fma_f32 v14, v50, v14, v32
	v_fmac_f32_e32 v118, v27, v13
	v_fma_f32 v15, v51, v15, v32
	v_fmac_f32_e32 v118, v28, v14
	v_fma_f32 v16, v52, v16, v32
	v_fmac_f32_e32 v118, v29, v15
	v_fma_f32 v17, v53, v17, v32
	v_fmac_f32_e32 v118, v30, v16
	v_fmac_f32_e32 v118, v31, v17
	ds_write_b32 v128, v118 offset:10752
	s_waitcnt lgkmcnt(1)
	ds_read_b128 v[24:27], v0 offset:4864
	ds_read_b128 v[28:31], v0 offset:4880
	ds_read_b128 v[46:49], v0 offset:6912
	ds_read_b128 v[50:53], v0 offset:6928
	ds_read_b32 v32, v1 offset:8512
	v_sub_f32_e32 v10, v10, v34
	v_sub_f32_e32 v11, v11, v34
	v_sub_f32_e32 v12, v12, v34
	ds_write_b128 v2, v[110:113] offset:0
	v_sub_f32_e32 v13, v13, v34
	v_sub_f32_e32 v14, v14, v34
	v_sub_f32_e32 v15, v15, v34
	v_lshlrev_b32_e32 v114, 16, v64
	v_sub_f32_e32 v16, v16, v34
	v_sub_f32_e32 v17, v17, v34
	v_fma_f32 v10, v54, v10, v34
	v_and_b32_e32 v115, 0xffff0000, v64
	v_fma_f32 v11, v55, v11, v34
	v_mul_f32_e32 v119, v38, v10
	v_fma_f32 v12, v56, v12, v34
	v_lshlrev_b32_e32 v116, 16, v65
	v_fmac_f32_e32 v119, v39, v11
	v_fma_f32 v13, v57, v13, v34
	v_fmac_f32_e32 v119, v40, v12
	v_and_b32_e32 v117, 0xffff0000, v65
	v_fma_f32 v14, v58, v14, v34
	v_fmac_f32_e32 v119, v41, v13
	v_fma_f32 v15, v59, v15, v34
	v_fmac_f32_e32 v119, v42, v14
	v_fma_f32 v16, v60, v16, v34
	v_fmac_f32_e32 v119, v43, v15
	v_fma_f32 v17, v61, v17, v34
	v_fmac_f32_e32 v119, v44, v16
	v_fmac_f32_e32 v119, v45, v17
	ds_write_b32 v128, v119 offset:11008
	s_waitcnt lgkmcnt(2)
	ds_read_b128 v[38:41], v0 offset:5120
	ds_read_b128 v[42:45], v0 offset:5136
	ds_read_b128 v[54:57], v0 offset:7168
	ds_read_b128 v[58:61], v0 offset:7184
	ds_read_b32 v34, v1 offset:8544
	v_sub_f32_e32 v10, v10, v32
	v_sub_f32_e32 v11, v11, v32
	v_sub_f32_e32 v12, v12, v32
	ds_write_b128 v2, v[114:117] offset:16
	v_sub_f32_e32 v13, v13, v32
	v_sub_f32_e32 v14, v14, v32
	v_sub_f32_e32 v15, v15, v32
	s_waitcnt vmcnt(13)
	v_sub_f32_e32 v16, v16, v32
	v_sub_f32_e32 v17, v17, v32
	v_fma_f32 v10, v46, v10, v32
	ds_write_b128 v2, v[66:69] offset:2048
	v_fma_f32 v11, v47, v11, v32
	v_mul_f32_e32 v118, v24, v10
	v_fma_f32 v12, v48, v12, v32
	ds_write_b128 v2, v[70:73] offset:2064
	v_fmac_f32_e32 v118, v25, v11
	v_fma_f32 v13, v49, v13, v32
	v_fmac_f32_e32 v118, v26, v12
	s_waitcnt vmcnt(12)
	v_fma_f32 v14, v50, v14, v32
	v_fmac_f32_e32 v118, v27, v13
	v_fma_f32 v15, v51, v15, v32
	v_fmac_f32_e32 v118, v28, v14
	v_fma_f32 v16, v52, v16, v32
	v_fmac_f32_e32 v118, v29, v15
	v_fma_f32 v17, v53, v17, v32
	v_fmac_f32_e32 v118, v30, v16
	v_fmac_f32_e32 v118, v31, v17
	ds_write_b32 v128, v118 offset:11264
	s_waitcnt lgkmcnt(4)
	ds_read_b128 v[24:27], v0 offset:5376
	ds_read_b128 v[28:31], v0 offset:5392
	ds_read_b128 v[46:49], v0 offset:7424
	ds_read_b128 v[50:53], v0 offset:7440
	ds_read_b32 v32, v1 offset:8576
	v_sub_f32_e32 v10, v10, v34
	v_sub_f32_e32 v11, v11, v34
	v_sub_f32_e32 v12, v12, v34
	v_lshlrev_b32_e32 v23, 16, v23
	v_sub_f32_e32 v13, v13, v34
	v_sub_f32_e32 v14, v14, v34
	v_sub_f32_e32 v15, v15, v34
	s_nop 0
	v_sub_f32_e32 v16, v16, v34
	v_sub_f32_e32 v17, v17, v34
	v_fma_f32 v10, v54, v10, v34
	ds_write_b32 v4, v23 offset:4096
	v_fma_f32 v11, v55, v11, v34
	v_mul_f32_e32 v119, v38, v10
	v_fma_f32 v12, v56, v12, v34
	v_fmac_f32_e32 v119, v39, v11
	v_fma_f32 v13, v57, v13, v34
	v_fmac_f32_e32 v119, v40, v12
	v_fma_f32 v14, v58, v14, v34
	v_fmac_f32_e32 v119, v41, v13
	v_fma_f32 v15, v59, v15, v34
	v_fmac_f32_e32 v119, v42, v14
	v_fma_f32 v16, v60, v16, v34
	v_fmac_f32_e32 v119, v43, v15
	v_fma_f32 v17, v61, v17, v34
	v_fmac_f32_e32 v119, v44, v16
	v_fmac_f32_e32 v119, v45, v17
	ds_write_b32 v128, v119 offset:11520
	s_waitcnt lgkmcnt(2)
	ds_read_b128 v[38:41], v0 offset:5632
	ds_read_b128 v[42:45], v0 offset:5648
	ds_read_b128 v[54:57], v0 offset:7680
	ds_read_b128 v[58:61], v0 offset:7696
	ds_read_b32 v34, v1 offset:8608
	v_sub_f32_e32 v10, v10, v32
	v_sub_f32_e32 v11, v11, v32
	v_sub_f32_e32 v12, v12, v32
	global_load_dwordx4 v[62:65], v5, s[94:95]
	global_load_dwordx4 v[66:69], v8, s[94:95]
	global_load_dwordx4 v[70:73], v8, s[94:95] offset:16
	global_load_ushort v23, v6, s[94:95]
	v_add_u32_e32 v5, 0x6800, v5
	v_add_u32_e32 v8, 0x3180, v8
	v_add_u32_e32 v6, 0x10000, v6
	v_sub_f32_e32 v13, v13, v32
	v_sub_f32_e32 v14, v14, v32
	v_sub_f32_e32 v15, v15, v32
	ds_read_b128 v[132:135], v129 offset:8704
	v_sub_f32_e32 v16, v16, v32
	v_sub_f32_e32 v17, v17, v32
	v_fma_f32 v10, v46, v10, v32
	ds_read_b128 v[136:139], v130 offset:8704
	v_fma_f32 v11, v47, v11, v32
	v_mul_f32_e32 v118, v24, v10
	v_fma_f32 v12, v48, v12, v32
	v_fmac_f32_e32 v118, v25, v11
	v_fma_f32 v13, v49, v13, v32
	v_fmac_f32_e32 v118, v26, v12
	v_fma_f32 v14, v50, v14, v32
	v_fmac_f32_e32 v118, v27, v13
	v_fma_f32 v15, v51, v15, v32
	v_fmac_f32_e32 v118, v28, v14
	v_fma_f32 v16, v52, v16, v32
	v_fmac_f32_e32 v118, v29, v15
	v_fma_f32 v17, v53, v17, v32
	v_fmac_f32_e32 v118, v30, v16
	v_fmac_f32_e32 v118, v31, v17
	ds_write_b32 v128, v118 offset:11776
	s_waitcnt lgkmcnt(3)
	ds_read_b128 v[24:27], v0 offset:5888
	ds_read_b128 v[28:31], v0 offset:5904
	ds_read_b128 v[46:49], v0 offset:7936
	ds_read_b128 v[50:53], v0 offset:7952
	ds_read_b32 v32, v1 offset:8640
	v_sub_f32_e32 v10, v10, v34
	v_sub_f32_e32 v11, v11, v34
	v_sub_f32_e32 v12, v12, v34
	v_sub_f32_e32 v13, v13, v34
	v_sub_f32_e32 v14, v14, v34
	v_sub_f32_e32 v15, v15, v34
	v_sub_f32_e32 v16, v16, v34
	v_sub_f32_e32 v17, v17, v34
	v_fma_f32 v10, v54, v10, v34
	v_fma_f32 v11, v55, v11, v34
	v_mul_f32_e32 v119, v38, v10
	v_fma_f32 v12, v56, v12, v34
	v_fmac_f32_e32 v119, v39, v11
	v_fma_f32 v13, v57, v13, v34
	v_fmac_f32_e32 v119, v40, v12
	v_fma_f32 v14, v58, v14, v34
	v_fmac_f32_e32 v119, v41, v13
	v_fma_f32 v15, v59, v15, v34
	v_fmac_f32_e32 v119, v42, v14
	v_fma_f32 v16, v60, v16, v34
	v_fmac_f32_e32 v119, v43, v15
	v_fma_f32 v17, v61, v17, v34
	v_fmac_f32_e32 v119, v44, v16
	v_fmac_f32_e32 v119, v45, v17
	ds_write_b32 v128, v119 offset:12032
	s_waitcnt lgkmcnt(1)
	ds_read_b128 v[38:41], v0 offset:6144
	ds_read_b128 v[42:45], v0 offset:6160
	ds_read_b128 v[54:57], v0 offset:8192
	ds_read_b128 v[58:61], v0 offset:8208
	ds_read_b32 v34, v1 offset:8672
	v_sub_f32_e32 v10, v10, v32
	v_sub_f32_e32 v11, v11, v32
	v_sub_f32_e32 v12, v12, v32
	s_waitcnt lgkmcnt(12)
	v_sub_f32_e32 v13, v13, v32
	v_sub_f32_e32 v14, v14, v32
	v_sub_f32_e32 v15, v15, v32
	v_add_f32_e32 v132, v132, v136
	v_sub_f32_e32 v16, v16, v32
	v_sub_f32_e32 v17, v17, v32
	v_fma_f32 v10, v46, v10, v32
	v_add_f32_e32 v133, v133, v137
	v_fma_f32 v11, v47, v11, v32
	v_mul_f32_e32 v118, v24, v10
	v_fma_f32 v12, v48, v12, v32
	v_add_f32_e32 v134, v134, v138
	v_fmac_f32_e32 v118, v25, v11
	v_fma_f32 v13, v49, v13, v32
	v_fmac_f32_e32 v118, v26, v12
	v_add_f32_e32 v135, v135, v139
	v_fma_f32 v14, v50, v14, v32
	v_fmac_f32_e32 v118, v27, v13
	v_fma_f32 v15, v51, v15, v32
	v_add_f32_e32 v132, v132, v133
	v_fmac_f32_e32 v118, v28, v14
	v_fma_f32 v16, v52, v16, v32
	v_fmac_f32_e32 v118, v29, v15
	v_add_f32_e32 v134, v134, v135
	v_fma_f32 v17, v53, v17, v32
	v_fmac_f32_e32 v118, v30, v16
	v_fmac_f32_e32 v118, v31, v17
	v_add_f32_e32 v132, v132, v134
	ds_write_b32 v128, v118 offset:12288
	v_cvt_pk_bf16_f32 v22, v132, v132
	ds_write_b16 v121, v22 offset:13568
	s_waitcnt lgkmcnt(2)
	ds_read_b128 v[24:27], v0 offset:0
	ds_read_b128 v[28:31], v0 offset:16
	ds_read_b128 v[46:49], v0 offset:2048
	ds_read_b128 v[50:53], v0 offset:2064
	ds_read_b32 v32, v1 offset:4096
	v_sub_f32_e32 v10, v10, v34
	v_sub_f32_e32 v11, v11, v34
	v_sub_f32_e32 v12, v12, v34
	v_sub_f32_e32 v13, v13, v34
	v_sub_f32_e32 v14, v14, v34
	v_sub_f32_e32 v15, v15, v34
	v_sub_f32_e32 v16, v16, v34
	v_sub_f32_e32 v17, v17, v34
	v_fma_f32 v10, v54, v10, v34
	v_fma_f32 v11, v55, v11, v34
	v_mul_f32_e32 v119, v38, v10
	v_fma_f32 v12, v56, v12, v34
	v_fmac_f32_e32 v119, v39, v11
	v_fma_f32 v13, v57, v13, v34
	v_fmac_f32_e32 v119, v40, v12
	v_fma_f32 v14, v58, v14, v34
	v_fmac_f32_e32 v119, v41, v13
	v_fma_f32 v15, v59, v15, v34
	v_fmac_f32_e32 v119, v42, v14
	v_fma_f32 v16, v60, v16, v34
	v_fmac_f32_e32 v119, v43, v15
	v_fma_f32 v17, v61, v17, v34
	v_fmac_f32_e32 v119, v44, v16
	v_fmac_f32_e32 v119, v45, v17
	ds_write_b32 v128, v119 offset:12544
	s_sub_u32 s12, s12, 1
	s_cmp_lg_u32 s12, 0
	s_cbranch_scc1 .Lls2_8_loop
	ds_read_b128 v[132:135], v129 offset:10752
	ds_read_b128 v[136:139], v130 offset:10752
	s_waitcnt lgkmcnt(0)
	v_add_f32_e32 v132, v132, v136
	v_add_f32_e32 v133, v133, v137
	v_add_f32_e32 v134, v134, v138
	v_add_f32_e32 v135, v135, v139
	v_add_f32_e32 v132, v132, v133
	v_add_f32_e32 v134, v134, v135
	v_add_f32_e32 v132, v132, v134
	v_cvt_pk_bf16_f32 v22, v132, v132
	ds_write_b16 v121, v22 offset:13696
	s_waitcnt lgkmcnt(0)
	ds_read_b128 v[124:127], v122 offset:13312
	s_waitcnt lgkmcnt(0)
	global_store_dwordx4 v7, v[124:127], s[94:95]
	v_add_u32_e32 v7, 0x20000, v7
	s_nop 0
	ds_read_b128 v[124:127], v122 offset:14336
	s_waitcnt lgkmcnt(0)
	global_store_dwordx4 v7, v[124:127], s[94:95]
	v_add_u32_e32 v7, 0x20000, v7
	s_nop 0
	ds_read_b128 v[124:127], v122 offset:15360
	s_waitcnt lgkmcnt(0)
	global_store_dwordx4 v7, v[124:127], s[94:95]
	v_add_u32_e32 v7, 0x20000, v7
	s_nop 0
	ds_read_b128 v[124:127], v122 offset:16384
	s_waitcnt lgkmcnt(0)
	global_store_dwordx4 v7, v[124:127], s[94:95]
	v_add_u32_e32 v7, 0x20000, v7
	s_nop 0
	ds_read_b128 v[124:127], v122 offset:17408
	s_waitcnt lgkmcnt(0)
	global_store_dwordx4 v7, v[124:127], s[94:95]
	v_add_u32_e32 v7, 0x20000, v7
	s_nop 0
	ds_read_b128 v[124:127], v122 offset:18432
	s_waitcnt lgkmcnt(0)
	global_store_dwordx4 v7, v[124:127], s[94:95]
	v_add_u32_e32 v7, 0x20000, v7
	s_nop 0
	ds_read_b128 v[124:127], v122 offset:19456
	s_waitcnt lgkmcnt(0)
	global_store_dwordx4 v7, v[124:127], s[94:95]
	v_add_u32_e32 v7, 0x20000, v7
	s_nop 0
	ds_read_b128 v[124:127], v122 offset:20480
	s_waitcnt lgkmcnt(0)
	global_store_dwordx4 v7, v[124:127], s[94:95]
	v_add_u32_e32 v7, 0x20000, v7
	s_nop 0
	global_store_dword v120, v10, s[26:27] offset:0
	global_store_dword v120, v11, s[26:27] offset:256
	global_store_dword v120, v12, s[26:27] offset:512
	global_store_dword v120, v13, s[26:27] offset:768
	global_store_dword v120, v14, s[26:27] offset:1024
	global_store_dword v120, v15, s[26:27] offset:1280
	global_store_dword v120, v16, s[26:27] offset:1536
	global_store_dword v120, v17, s[26:27] offset:1792
	s_waitcnt vmcnt(0) lgkmcnt(0)
	s_setprio 0
	s_branch .Lls_done
.Lls1_8_entry:
	v_and_b32_e32 v114, 63, v196
	v_and_b32_e32 v115, 7, v114
	v_lshrrev_b32_e32 v116, 3, v114
	s_min_u32 s29, s0, 4
	s_mul_i32 s29, s29, 0x5600
	v_and_b32_e32 v117, 3, v115
	v_cmp_eq_u32_e64 s[6:7], 1, v117
	v_cmp_eq_u32_e64 s[8:9], 2, v117
	v_cmp_eq_u32_e64 s[10:11], 3, v117
	v_lshl_add_u32 v0, v115, 4, s29
	v_lshl_add_u32 v1, v116, 2, s29
	s_lshl_b32 s37, s16, 11
	v_lshrrev_b32_e32 v115, 3, v114
	v_and_b32_e32 v116, 7, v114
	v_add_u32_e32 v117, s37, v115
	s_lshl_b32 s21, s17, 7
	s_add_u32 s21, s21, 0x13e00000
	v_mul_u32_u24_e32 v8, 0x630, v117
	v_lshl_add_u32 v8, v116, 4, v8
	v_add_u32_e32 v8, s21, v8
	v_lshlrev_b32_e32 v119, 7, v115
	v_lshl_add_u32 v119, v116, 4, v119
	v_add_u32_e32 v119, s29, v119
	v_and_b32_e32 v115, 31, v114
	v_lshrrev_b32_e32 v116, 2, v115
	v_and_b32_e32 v115, 3, v115
	v_add_u32_e32 v117, s37, v116
	v_cmp_gt_u32_e32 vcc, 32, v114
	s_lshl_b32 s21, s17, 6
	s_add_u32 s22, s21, 0x10800400
	s_add_u32 s44, s21, 0x8400900
	v_mov_b32_e32 v9, 0x2000
	v_mov_b32_e32 v18, 0xd00
	v_cndmask_b32_e32 v9, v9, v18, vcc
	v_mov_b32_e32 v5, s44
	v_mov_b32_e32 v18, s22
	v_cndmask_b32_e32 v5, v5, v18, vcc
	v_mul_lo_u32 v18, v117, v9
	v_add_u32_e32 v5, v5, v18
	v_lshl_add_u32 v5, v115, 4, v5
	v_lshlrev_b32_e32 v9, 3, v9
	v_mov_b32_e32 v2, 0
	v_mov_b32_e32 v18, 1024
	v_cndmask_b32_e32 v2, v2, v18, vcc
	v_lshl_add_u32 v2, v116, 7, v2
	v_lshl_add_u32 v2, v115, 5, v2
	v_add_u32_e32 v2, s29, v2
	v_lshrrev_b32_e32 v116, 3, v114
	v_and_b32_e32 v115, 7, v114
	v_add_u32_e32 v117, s37, v116
	s_lshl_b32 s22, s14, 3
	s_lshl_b32 s21, s17, 6
	s_add_u32 s21, s21, s22
	s_lshl_b32 s44, s21, 1
	s_add_u32 s44, s44, 0x8400a00
	v_lshlrev_b32_e32 v6, 13, v117
	v_lshlrev_b32_e32 v4, 5, v116
	v_lshl_add_u32 v4, v115, 2, v4
	v_lshl_add_u32 v6, v115, 1, v6
	v_add_u32_e32 v6, s44, v6
	v_add_u32_e32 v4, s29, v4
	v_and_b32_e32 v115, 7, v114
	v_lshrrev_b32_e32 v116, 3, v114
	v_add_u32_e32 v117, s37, v114
	v_lshlrev_b32_e32 v7, 11, v117
	s_lshl_b32 s44, s21, 1
	s_add_u32 s44, s44, 0x6300200
	v_add_u32_e32 v7, s44, v7
	s_lshl_b32 s44, s28, 3
	s_add_u32 s44, s44, s16
	s_lshl_b32 s44, s44, 2
	s_add_u32 s44, s44, s17
	s_mul_i32 s44, s44, 0x2000
	s_add_u32 s44, s44, 0x4300000
	s_lshl_b32 s24, s22, 2
	s_add_u32 s44, s44, s24
	v_lshlrev_b32_e32 v120, 10, v115
	v_lshl_add_u32 v120, v116, 2, v120
	v_add_u32_e32 v120, s44, v120
	v_readlane_b32 s26, v253, 29
	v_readlane_b32 s27, v253, 30
	v_lshlrev_b32_e32 v121, 4, v115
	v_lshl_add_u32 v121, v116, 1, v121
	v_add_u32_e32 v121, s29, v121
	v_lshl_add_u32 v122, v114, 4, s29
	v_lshl_add_u32 v128, v114, 2, s29
	v_lshl_add_u32 v121, v114, 1, s29
	v_subrev_u32_e32 v121, 0x200, v121
	v_lshrrev_b32_e32 v115, 3, v114
	v_and_b32_e32 v116, 7, v114
	v_lshlrev_b32_e32 v117, 8, v115
	v_lshl_add_u32 v117, v116, 5, v117
	v_add_u32_e32 v117, s29, v117
	v_bfe_u32 v115, v115, 1, 1
	v_xor_b32_e32 v116, 0, v115
	v_lshl_add_u32 v129, v116, 4, v117
	v_xor_b32_e32 v116, 1, v115
	v_lshl_add_u32 v130, v116, 4, v117
	v_mov_b32_e32 v10, 0
	v_mov_b32_e32 v11, 0
	v_mov_b32_e32 v12, 0
	v_mov_b32_e32 v13, 0
	v_mov_b32_e32 v14, 0
	v_mov_b32_e32 v15, 0
	v_mov_b32_e32 v16, 0
	v_mov_b32_e32 v17, 0
	v_mov_b32_e32 v61, 0
	v_mov_b32_e32 v118, 0
	s_setprio 2
	s_movk_i32 s12, 64
	s_nop 0
	global_load_dwordx4 v[78:81], v5, s[94:95]
	global_load_dwordx4 v[82:85], v8, s[94:95]
	global_load_ushort v36, v6, s[94:95]
	v_add_u32_e32 v5, v5, v9
	v_add_u32_e32 v8, 0x3180, v8
	v_add_u32_e32 v6, 0x10000, v6
	s_waitcnt vmcnt(0)
	s_waitcnt vmcnt(2)
	v_lshlrev_b32_e32 v110, 16, v78
	v_and_b32_e32 v111, 0xffff0000, v78
	v_lshlrev_b32_e32 v112, 16, v79
	v_and_b32_e32 v113, 0xffff0000, v79
	ds_write_b128 v2, v[110:113] offset:0
	v_lshlrev_b32_e32 v114, 16, v80
	v_and_b32_e32 v115, 0xffff0000, v80
	v_lshlrev_b32_e32 v116, 16, v81
	v_and_b32_e32 v117, 0xffff0000, v81
	ds_write_b128 v2, v[114:117] offset:16
	s_waitcnt vmcnt(1)
	ds_write_b128 v119, v[82:85] offset:2048
	s_waitcnt vmcnt(0)
	v_lshlrev_b32_e32 v36, 16, v36
	s_nop 0
	ds_write_b32 v4, v36 offset:3072
	global_load_dwordx4 v[86:89], v5, s[94:95]
	global_load_dwordx4 v[90:93], v8, s[94:95]
	global_load_ushort v55, v6, s[94:95]
	v_add_u32_e32 v5, v5, v9
	v_add_u32_e32 v8, 0x3180, v8
	v_add_u32_e32 v6, 0x10000, v6
	global_load_dwordx4 v[94:97], v5, s[94:95]
	global_load_dwordx4 v[98:101], v8, s[94:95]
	global_load_ushort v57, v6, s[94:95]
	v_add_u32_e32 v5, v5, v9
	v_add_u32_e32 v8, 0x3180, v8
	v_add_u32_e32 v6, 0x10000, v6
	global_load_dwordx4 v[102:105], v5, s[94:95]
	global_load_dwordx4 v[106:109], v8, s[94:95]
	global_load_ushort v59, v6, s[94:95]
	v_add_u32_e32 v5, v5, v9
	v_add_u32_e32 v8, 0x3180, v8
	v_add_u32_e32 v6, 0x10000, v6
	global_load_dwordx4 v[78:81], v5, s[94:95]
	global_load_dwordx4 v[82:85], v8, s[94:95]
	global_load_ushort v36, v6, s[94:95]
	v_add_u32_e32 v5, v5, v9
	v_add_u32_e32 v8, 0x3180, v8
	v_add_u32_e32 v6, 0x10000, v6
	ds_read_b128 v[20:23], v0 offset:0
	ds_read_b128 v[38:41], v0 offset:1024
	ds_read_b128 v[62:65], v0 offset:2048
	ds_read_b32 v54, v1 offset:3072
	ds_read_b128 v[24:27], v0 offset:128
	ds_read_b128 v[42:45], v0 offset:1152
	ds_read_b128 v[66:69], v0 offset:2176
	ds_read_b32 v56, v1 offset:3104
	ds_read_b128 v[28:31], v0 offset:256
	ds_read_b128 v[46:49], v0 offset:1280
	ds_read_b128 v[70:73], v0 offset:2304
	ds_read_b32 v58, v1 offset:3136
.Lls1_8_loop:
	s_waitcnt lgkmcnt(8)
	v_mul_f32_e32 v10, v62, v10
	v_mul_f32_e32 v11, v63, v11
	v_mul_f32_e32 v12, v64, v12
	s_waitcnt vmcnt(11)
	v_mul_f32_e32 v13, v65, v13
	v_fmac_f32_e32 v10, v20, v54
	v_fmac_f32_e32 v11, v21, v54
	v_lshlrev_b32_e32 v110, 16, v86
	v_mul_f32_e32 v61, v38, v10
	v_fmac_f32_e32 v12, v22, v54
	v_fmac_f32_e32 v61, v39, v11
	v_and_b32_e32 v111, 0xffff0000, v86
	v_fmac_f32_e32 v13, v23, v54
	v_fmac_f32_e32 v61, v40, v12
	v_fmac_f32_e32 v61, v41, v13
	v_lshlrev_b32_e32 v112, 16, v87
	ds_write_b32 v128, v61 offset:6656
	ds_read_b128 v[32:35], v0 offset:384
	ds_read_b128 v[50:53], v0 offset:1408
	ds_read_b128 v[74:77], v0 offset:2432
	ds_read_b32 v60, v1 offset:3168
	v_and_b32_e32 v113, 0xffff0000, v87
	s_waitcnt lgkmcnt(9)
	v_mul_f32_e32 v10, v66, v10
	v_mul_f32_e32 v11, v67, v11
	v_mul_f32_e32 v12, v68, v12
	ds_write_b128 v2, v[110:113] offset:3328
	v_mul_f32_e32 v13, v69, v13
	v_fmac_f32_e32 v10, v24, v56
	v_fmac_f32_e32 v11, v25, v56
	v_lshlrev_b32_e32 v114, 16, v88
	v_mul_f32_e32 v118, v42, v10
	v_fmac_f32_e32 v12, v26, v56
	v_fmac_f32_e32 v118, v43, v11
	v_and_b32_e32 v115, 0xffff0000, v88
	v_fmac_f32_e32 v13, v27, v56
	v_fmac_f32_e32 v118, v44, v12
	v_fmac_f32_e32 v118, v45, v13
	v_lshlrev_b32_e32 v116, 16, v89
	ds_write_b32 v128, v118 offset:6912
	ds_read_b128 v[20:23], v0 offset:512
	ds_read_b128 v[38:41], v0 offset:1536
	ds_read_b128 v[62:65], v0 offset:2560
	ds_read_b32 v54, v1 offset:3200
	v_and_b32_e32 v117, 0xffff0000, v89
	s_waitcnt lgkmcnt(11)
	v_mul_f32_e32 v10, v70, v10
	v_mul_f32_e32 v11, v71, v11
	v_mul_f32_e32 v12, v72, v12
	ds_write_b128 v2, v[114:117] offset:3344
	v_mul_f32_e32 v13, v73, v13
	v_fmac_f32_e32 v10, v28, v58
	v_fmac_f32_e32 v11, v29, v58
	s_waitcnt vmcnt(10)
	v_mul_f32_e32 v61, v46, v10
	v_fmac_f32_e32 v12, v30, v58
	v_fmac_f32_e32 v61, v47, v11
	ds_write_b128 v119, v[90:93] offset:5376
	v_fmac_f32_e32 v13, v31, v58
	v_fmac_f32_e32 v61, v48, v12
	v_fmac_f32_e32 v61, v49, v13
	s_waitcnt vmcnt(9)
	ds_write_b32 v128, v61 offset:7168
	ds_read_b128 v[24:27], v0 offset:640
	ds_read_b128 v[42:45], v0 offset:1664
	ds_read_b128 v[66:69], v0 offset:2688
	ds_read_b32 v56, v1 offset:3232
	v_lshlrev_b32_e32 v55, 16, v55
	s_waitcnt lgkmcnt(13)
	v_mul_f32_e32 v10, v74, v10
	v_mul_f32_e32 v11, v75, v11
	v_mul_f32_e32 v12, v76, v12
	s_nop 0
	v_mul_f32_e32 v13, v77, v13
	v_fmac_f32_e32 v10, v32, v60
	v_fmac_f32_e32 v11, v33, v60
	ds_write_b32 v4, v55 offset:6400
	v_mul_f32_e32 v118, v50, v10
	v_fmac_f32_e32 v12, v34, v60
	v_fmac_f32_e32 v118, v51, v11
	ds_read_b128 v[28:31], v0 offset:768
	v_fmac_f32_e32 v13, v35, v60
	v_fmac_f32_e32 v118, v52, v12
	v_fmac_f32_e32 v118, v53, v13
	ds_read_b128 v[46:49], v0 offset:1792
	ds_write_b32 v128, v118 offset:7424
	ds_read_b128 v[70:73], v0 offset:2816
	ds_read_b32 v58, v1 offset:3264
	s_waitcnt lgkmcnt(13)
	v_mul_f32_e32 v10, v62, v10
	v_mul_f32_e32 v11, v63, v11
	v_mul_f32_e32 v12, v64, v12
	global_load_dwordx4 v[86:89], v5, s[94:95]
	global_load_dwordx4 v[90:93], v8, s[94:95]
	global_load_ushort v55, v6, s[94:95]
	v_add_u32_e32 v5, v5, v9
	v_add_u32_e32 v8, 0x3180, v8
	v_add_u32_e32 v6, 0x10000, v6
	v_mul_f32_e32 v13, v65, v13
	v_fmac_f32_e32 v10, v20, v54
	v_fmac_f32_e32 v11, v21, v54
	ds_read_b128 v[132:135], v129 offset:8704
	v_mul_f32_e32 v61, v38, v10
	v_fmac_f32_e32 v12, v22, v54
	v_fmac_f32_e32 v61, v39, v11
	ds_read_b128 v[136:139], v130 offset:8704
	v_fmac_f32_e32 v13, v23, v54
	v_fmac_f32_e32 v61, v40, v12
	v_fmac_f32_e32 v61, v41, v13
	ds_read_b128 v[32:35], v0 offset:896
	ds_write_b32 v128, v61 offset:7680
	ds_read_b128 v[50:53], v0 offset:1920
	ds_read_b128 v[74:77], v0 offset:2944
	ds_read_b32 v60, v1 offset:3296
	s_waitcnt lgkmcnt(13)
	v_mul_f32_e32 v10, v66, v10
	v_mul_f32_e32 v11, v67, v11
	v_mul_f32_e32 v12, v68, v12
	ds_read_b128 v[20:23], v0 offset:3328
	v_mul_f32_e32 v13, v69, v13
	v_fmac_f32_e32 v10, v24, v56
	v_fmac_f32_e32 v11, v25, v56
	ds_read_b128 v[38:41], v0 offset:4352
	v_mul_f32_e32 v118, v42, v10
	v_fmac_f32_e32 v12, v26, v56
	v_fmac_f32_e32 v118, v43, v11
	ds_read_b128 v[62:65], v0 offset:5376
	v_fmac_f32_e32 v13, v27, v56
	v_fmac_f32_e32 v118, v44, v12
	v_fmac_f32_e32 v118, v45, v13
	ds_read_b32 v54, v1 offset:6400
	ds_write_b32 v128, v118 offset:7936
	s_waitcnt lgkmcnt(12)
	v_mul_f32_e32 v10, v70, v10
	v_mul_f32_e32 v11, v71, v11
	v_mul_f32_e32 v12, v72, v12
	s_waitcnt lgkmcnt(10)
	v_mul_f32_e32 v13, v73, v13
	v_fmac_f32_e32 v10, v28, v58
	v_fmac_f32_e32 v11, v29, v58
	v_add_f32_e32 v132, v132, v136
	v_mul_f32_e32 v61, v46, v10
	v_fmac_f32_e32 v12, v30, v58
	v_fmac_f32_e32 v61, v47, v11
	v_add_f32_e32 v133, v133, v137
	v_fmac_f32_e32 v13, v31, v58
	v_fmac_f32_e32 v61, v48, v12
	v_fmac_f32_e32 v61, v49, v13
	v_add_f32_e32 v134, v134, v138
	ds_write_b32 v128, v61 offset:8192
	ds_read_b128 v[24:27], v0 offset:3456
	ds_read_b128 v[42:45], v0 offset:4480
	ds_read_b128 v[66:69], v0 offset:5504
	ds_read_b32 v56, v1 offset:6432
	v_add_f32_e32 v135, v135, v139
	v_add_f32_e32 v132, v132, v133
	v_add_f32_e32 v134, v134, v135
	v_add_f32_e32 v132, v132, v134
	v_cvt_pk_bf16_f32 v19, v132, v132
	ds_write_b16 v121, v19 offset:11648
	v_add_u32_e32 v121, 0x200, v121
	s_and_b32 s24, s12, 15
	s_cmp_eq_u32 s24, 0
	s_cbranch_scc0 .Lls1_8_noflush
	s_cmp_eq_u32 s12, 64
	s_cbranch_scc1 .Lls1_8_noflush
	s_waitcnt lgkmcnt(0)
	ds_read_b128 v[124:127], v122 offset:11264
	s_waitcnt lgkmcnt(0)
	global_store_dwordx4 v7, v[124:127], s[94:95]
	v_add_u32_e32 v7, 0x20000, v7
	s_nop 0
	ds_read_b128 v[124:127], v122 offset:12288
	s_waitcnt lgkmcnt(0)
	global_store_dwordx4 v7, v[124:127], s[94:95]
	v_add_u32_e32 v7, 0x20000, v7
	s_nop 0
	ds_read_b128 v[124:127], v122 offset:13312
	s_waitcnt lgkmcnt(0)
	global_store_dwordx4 v7, v[124:127], s[94:95]
	v_add_u32_e32 v7, 0x20000, v7
	s_nop 0
	ds_read_b128 v[124:127], v122 offset:14336
	s_waitcnt lgkmcnt(0)
	global_store_dwordx4 v7, v[124:127], s[94:95]
	v_add_u32_e32 v7, 0x20000, v7
	s_nop 0
	ds_read_b128 v[124:127], v122 offset:15360
	s_waitcnt lgkmcnt(0)
	global_store_dwordx4 v7, v[124:127], s[94:95]
	v_add_u32_e32 v7, 0x20000, v7
	s_nop 0
	ds_read_b128 v[124:127], v122 offset:16384
	s_waitcnt lgkmcnt(0)
	global_store_dwordx4 v7, v[124:127], s[94:95]
	v_add_u32_e32 v7, 0x20000, v7
	s_nop 0
	ds_read_b128 v[124:127], v122 offset:17408
	s_waitcnt lgkmcnt(0)
	global_store_dwordx4 v7, v[124:127], s[94:95]
	v_add_u32_e32 v7, 0x20000, v7
	s_nop 0
	ds_read_b128 v[124:127], v122 offset:18432
	s_waitcnt lgkmcnt(0)
	global_store_dwordx4 v7, v[124:127], s[94:95]
	v_add_u32_e32 v7, 0x20000, v7
	s_nop 0
	v_subrev_u32_e32 v121, 0x2000, v121
.Lls1_8_noflush:
	s_waitcnt lgkmcnt(11)
	v_mul_f32_e32 v10, v74, v10
	v_mul_f32_e32 v11, v75, v11
	v_mul_f32_e32 v12, v76, v12
	ds_read_b128 v[28:31], v0 offset:3584
	v_mul_f32_e32 v13, v77, v13
	v_fmac_f32_e32 v10, v32, v60
	v_fmac_f32_e32 v11, v33, v60
	ds_read_b128 v[46:49], v0 offset:4608
	v_mul_f32_e32 v118, v50, v10
	v_fmac_f32_e32 v12, v34, v60
	v_fmac_f32_e32 v118, v51, v11
	ds_read_b128 v[70:73], v0 offset:5632
	v_fmac_f32_e32 v13, v35, v60
	v_fmac_f32_e32 v118, v52, v12
	v_fmac_f32_e32 v118, v53, v13
	ds_read_b32 v58, v1 offset:6464
	ds_write_b32 v128, v118 offset:8448
	s_waitcnt lgkmcnt(12)
	v_mul_f32_e32 v10, v62, v10
	v_mul_f32_e32 v11, v63, v11
	v_mul_f32_e32 v12, v64, v12
	s_waitcnt vmcnt(11)
	v_mul_f32_e32 v13, v65, v13
	v_fmac_f32_e32 v10, v20, v54
	v_fmac_f32_e32 v11, v21, v54
	v_lshlrev_b32_e32 v110, 16, v94
	v_mul_f32_e32 v61, v38, v10
	v_fmac_f32_e32 v12, v22, v54
	v_fmac_f32_e32 v61, v39, v11
	v_and_b32_e32 v111, 0xffff0000, v94
	v_fmac_f32_e32 v13, v23, v54
	v_fmac_f32_e32 v61, v40, v12
	v_fmac_f32_e32 v61, v41, v13
	v_lshlrev_b32_e32 v112, 16, v95
	ds_write_b32 v128, v61 offset:8704
	ds_read_b128 v[32:35], v0 offset:3712
	ds_read_b128 v[50:53], v0 offset:4736
	ds_read_b128 v[74:77], v0 offset:5760
	ds_read_b32 v60, v1 offset:6496
	v_and_b32_e32 v113, 0xffff0000, v95
	s_waitcnt lgkmcnt(11)
	v_mul_f32_e32 v10, v66, v10
	v_mul_f32_e32 v11, v67, v11
	v_mul_f32_e32 v12, v68, v12
	ds_write_b128 v2, v[110:113] offset:0
	v_mul_f32_e32 v13, v69, v13
	v_fmac_f32_e32 v10, v24, v56
	v_fmac_f32_e32 v11, v25, v56
	v_lshlrev_b32_e32 v114, 16, v96
	v_mul_f32_e32 v118, v42, v10
	v_fmac_f32_e32 v12, v26, v56
	v_fmac_f32_e32 v118, v43, v11
	v_and_b32_e32 v115, 0xffff0000, v96
	v_fmac_f32_e32 v13, v27, v56
	v_fmac_f32_e32 v118, v44, v12
	v_fmac_f32_e32 v118, v45, v13
	v_lshlrev_b32_e32 v116, 16, v97
	ds_write_b32 v128, v118 offset:8960
	ds_read_b128 v[20:23], v0 offset:3840
	ds_read_b128 v[38:41], v0 offset:4864
	ds_read_b128 v[62:65], v0 offset:5888
	ds_read_b32 v54, v1 offset:6528
	v_and_b32_e32 v117, 0xffff0000, v97
	s_waitcnt lgkmcnt(12)
	v_mul_f32_e32 v10, v70, v10
	v_mul_f32_e32 v11, v71, v11
	v_mul_f32_e32 v12, v72, v12
	ds_write_b128 v2, v[114:117] offset:16
	v_mul_f32_e32 v13, v73, v13
	v_fmac_f32_e32 v10, v28, v58
	v_fmac_f32_e32 v11, v29, v58
	s_waitcnt vmcnt(10)
	v_mul_f32_e32 v61, v46, v10
	v_fmac_f32_e32 v12, v30, v58
	v_fmac_f32_e32 v61, v47, v11
	ds_write_b128 v119, v[98:101] offset:2048
	v_fmac_f32_e32 v13, v31, v58
	v_fmac_f32_e32 v61, v48, v12
	v_fmac_f32_e32 v61, v49, v13
	s_waitcnt vmcnt(9)
	ds_write_b32 v128, v61 offset:9216
	ds_read_b128 v[24:27], v0 offset:3968
	ds_read_b128 v[42:45], v0 offset:4992
	ds_read_b128 v[66:69], v0 offset:6016
	ds_read_b32 v56, v1 offset:6560
	v_lshlrev_b32_e32 v57, 16, v57
	s_waitcnt lgkmcnt(13)
	v_mul_f32_e32 v10, v74, v10
	v_mul_f32_e32 v11, v75, v11
	v_mul_f32_e32 v12, v76, v12
	s_nop 0
	v_mul_f32_e32 v13, v77, v13
	v_fmac_f32_e32 v10, v32, v60
	v_fmac_f32_e32 v11, v33, v60
	ds_write_b32 v4, v57 offset:3072
	v_mul_f32_e32 v118, v50, v10
	v_fmac_f32_e32 v12, v34, v60
	v_fmac_f32_e32 v118, v51, v11
	ds_read_b128 v[28:31], v0 offset:4096
	v_fmac_f32_e32 v13, v35, v60
	v_fmac_f32_e32 v118, v52, v12
	v_fmac_f32_e32 v118, v53, v13
	ds_read_b128 v[46:49], v0 offset:5120
	ds_write_b32 v128, v118 offset:9472
	ds_read_b128 v[70:73], v0 offset:6144
	ds_read_b32 v58, v1 offset:6592
	s_waitcnt lgkmcnt(13)
	v_mul_f32_e32 v10, v62, v10
	v_mul_f32_e32 v11, v63, v11
	v_mul_f32_e32 v12, v64, v12
	global_load_dwordx4 v[94:97], v5, s[94:95]
	global_load_dwordx4 v[98:101], v8, s[94:95]
	global_load_ushort v57, v6, s[94:95]
	v_add_u32_e32 v5, v5, v9
	v_add_u32_e32 v8, 0x3180, v8
	v_add_u32_e32 v6, 0x10000, v6
	v_mul_f32_e32 v13, v65, v13
	v_fmac_f32_e32 v10, v20, v54
	v_fmac_f32_e32 v11, v21, v54
	ds_read_b128 v[132:135], v129 offset:6656
	v_mul_f32_e32 v61, v38, v10
	v_fmac_f32_e32 v12, v22, v54
	v_fmac_f32_e32 v61, v39, v11
	ds_read_b128 v[136:139], v130 offset:6656
	v_fmac_f32_e32 v13, v23, v54
	v_fmac_f32_e32 v61, v40, v12
	v_fmac_f32_e32 v61, v41, v13
	ds_read_b128 v[32:35], v0 offset:4224
	ds_write_b32 v128, v61 offset:9728
	ds_read_b128 v[50:53], v0 offset:5248
	ds_read_b128 v[74:77], v0 offset:6272
	ds_read_b32 v60, v1 offset:6624
	s_waitcnt lgkmcnt(13)
	v_mul_f32_e32 v10, v66, v10
	v_mul_f32_e32 v11, v67, v11
	v_mul_f32_e32 v12, v68, v12
	ds_read_b128 v[20:23], v0 offset:0
	v_mul_f32_e32 v13, v69, v13
	v_fmac_f32_e32 v10, v24, v56
	v_fmac_f32_e32 v11, v25, v56
	ds_read_b128 v[38:41], v0 offset:1024
	v_mul_f32_e32 v118, v42, v10
	v_fmac_f32_e32 v12, v26, v56
	v_fmac_f32_e32 v118, v43, v11
	ds_read_b128 v[62:65], v0 offset:2048
	v_fmac_f32_e32 v13, v27, v56
	v_fmac_f32_e32 v118, v44, v12
	v_fmac_f32_e32 v118, v45, v13
	ds_read_b32 v54, v1 offset:3072
	ds_write_b32 v128, v118 offset:9984
	s_waitcnt lgkmcnt(12)
	v_mul_f32_e32 v10, v70, v10
	v_mul_f32_e32 v11, v71, v11
	v_mul_f32_e32 v12, v72, v12
	s_waitcnt lgkmcnt(10)
	v_mul_f32_e32 v13, v73, v13
	v_fmac_f32_e32 v10, v28, v58
	v_fmac_f32_e32 v11, v29, v58
	v_add_f32_e32 v132, v132, v136
	v_mul_f32_e32 v61, v46, v10
	v_fmac_f32_e32 v12, v30, v58
	v_fmac_f32_e32 v61, v47, v11
	v_add_f32_e32 v133, v133, v137
	v_fmac_f32_e32 v13, v31, v58
	v_fmac_f32_e32 v61, v48, v12
	v_fmac_f32_e32 v61, v49, v13
	v_add_f32_e32 v134, v134, v138
	ds_write_b32 v128, v61 offset:10240
	ds_read_b128 v[24:27], v0 offset:128
	ds_read_b128 v[42:45], v0 offset:1152
	ds_read_b128 v[66:69], v0 offset:2176
	ds_read_b32 v56, v1 offset:3104
	v_add_f32_e32 v135, v135, v139
	v_add_f32_e32 v132, v132, v133
	v_add_f32_e32 v134, v134, v135
	v_add_f32_e32 v132, v132, v134
	v_cvt_pk_bf16_f32 v19, v132, v132
	ds_write_b16 v121, v19 offset:11264
	s_waitcnt lgkmcnt(11)
	v_mul_f32_e32 v10, v74, v10
	v_mul_f32_e32 v11, v75, v11
	v_mul_f32_e32 v12, v76, v12
	ds_read_b128 v[28:31], v0 offset:256
	v_mul_f32_e32 v13, v77, v13
	v_fmac_f32_e32 v10, v32, v60
	v_fmac_f32_e32 v11, v33, v60
	ds_read_b128 v[46:49], v0 offset:1280
	v_mul_f32_e32 v118, v50, v10
	v_fmac_f32_e32 v12, v34, v60
	v_fmac_f32_e32 v118, v51, v11
	ds_read_b128 v[70:73], v0 offset:2304
	v_fmac_f32_e32 v13, v35, v60
	v_fmac_f32_e32 v118, v52, v12
	v_fmac_f32_e32 v118, v53, v13
	ds_read_b32 v58, v1 offset:3136
	ds_write_b32 v128, v118 offset:10496
	s_waitcnt lgkmcnt(12)
	v_mul_f32_e32 v10, v62, v10
	v_mul_f32_e32 v11, v63, v11
	v_mul_f32_e32 v12, v64, v12
	s_waitcnt vmcnt(11)
	v_mul_f32_e32 v13, v65, v13
	v_fmac_f32_e32 v10, v20, v54
	v_fmac_f32_e32 v11, v21, v54
	v_lshlrev_b32_e32 v110, 16, v102
	v_mul_f32_e32 v61, v38, v10
	v_fmac_f32_e32 v12, v22, v54
	v_fmac_f32_e32 v61, v39, v11
	v_and_b32_e32 v111, 0xffff0000, v102
	v_fmac_f32_e32 v13, v23, v54
	v_fmac_f32_e32 v61, v40, v12
	v_fmac_f32_e32 v61, v41, v13
	v_lshlrev_b32_e32 v112, 16, v103
	ds_write_b32 v128, v61 offset:6656
	ds_read_b128 v[32:35], v0 offset:384
	ds_read_b128 v[50:53], v0 offset:1408
	ds_read_b128 v[74:77], v0 offset:2432
	ds_read_b32 v60, v1 offset:3168
	v_and_b32_e32 v113, 0xffff0000, v103
	s_waitcnt lgkmcnt(11)
	v_mul_f32_e32 v10, v66, v10
	v_mul_f32_e32 v11, v67, v11
	v_mul_f32_e32 v12, v68, v12
	ds_write_b128 v2, v[110:113] offset:3328
	v_mul_f32_e32 v13, v69, v13
	v_fmac_f32_e32 v10, v24, v56
	v_fmac_f32_e32 v11, v25, v56
	v_lshlrev_b32_e32 v114, 16, v104
	v_mul_f32_e32 v118, v42, v10
	v_fmac_f32_e32 v12, v26, v56
	v_fmac_f32_e32 v118, v43, v11
	v_and_b32_e32 v115, 0xffff0000, v104
	v_fmac_f32_e32 v13, v27, v56
	v_fmac_f32_e32 v118, v44, v12
	v_fmac_f32_e32 v118, v45, v13
	v_lshlrev_b32_e32 v116, 16, v105
	ds_write_b32 v128, v118 offset:6912
	ds_read_b128 v[20:23], v0 offset:512
	ds_read_b128 v[38:41], v0 offset:1536
	ds_read_b128 v[62:65], v0 offset:2560
	ds_read_b32 v54, v1 offset:3200
	v_and_b32_e32 v117, 0xffff0000, v105
	s_waitcnt lgkmcnt(12)
	v_mul_f32_e32 v10, v70, v10
	v_mul_f32_e32 v11, v71, v11
	v_mul_f32_e32 v12, v72, v12
	ds_write_b128 v2, v[114:117] offset:3344
	v_mul_f32_e32 v13, v73, v13
	v_fmac_f32_e32 v10, v28, v58
	v_fmac_f32_e32 v11, v29, v58
	s_waitcnt vmcnt(10)
	v_mul_f32_e32 v61, v46, v10
	v_fmac_f32_e32 v12, v30, v58
	v_fmac_f32_e32 v61, v47, v11
	ds_write_b128 v119, v[106:109] offset:5376
	v_fmac_f32_e32 v13, v31, v58
	v_fmac_f32_e32 v61, v48, v12
	v_fmac_f32_e32 v61, v49, v13
	s_waitcnt vmcnt(9)
	ds_write_b32 v128, v61 offset:7168
	ds_read_b128 v[24:27], v0 offset:640
	ds_read_b128 v[42:45], v0 offset:1664
	ds_read_b128 v[66:69], v0 offset:2688
	ds_read_b32 v56, v1 offset:3232
	v_lshlrev_b32_e32 v59, 16, v59
	s_waitcnt lgkmcnt(13)
	v_mul_f32_e32 v10, v74, v10
	v_mul_f32_e32 v11, v75, v11
	v_mul_f32_e32 v12, v76, v12
	s_nop 0
	v_mul_f32_e32 v13, v77, v13
	v_fmac_f32_e32 v10, v32, v60
	v_fmac_f32_e32 v11, v33, v60
	ds_write_b32 v4, v59 offset:6400
	v_mul_f32_e32 v118, v50, v10
	v_fmac_f32_e32 v12, v34, v60
	v_fmac_f32_e32 v118, v51, v11
	ds_read_b128 v[28:31], v0 offset:768
	v_fmac_f32_e32 v13, v35, v60
	v_fmac_f32_e32 v118, v52, v12
	v_fmac_f32_e32 v118, v53, v13
	ds_read_b128 v[46:49], v0 offset:1792
	ds_write_b32 v128, v118 offset:7424
	ds_read_b128 v[70:73], v0 offset:2816
	ds_read_b32 v58, v1 offset:3264
	s_waitcnt lgkmcnt(13)
	v_mul_f32_e32 v10, v62, v10
	v_mul_f32_e32 v11, v63, v11
	v_mul_f32_e32 v12, v64, v12
	global_load_dwordx4 v[102:105], v5, s[94:95]
	global_load_dwordx4 v[106:109], v8, s[94:95]
	global_load_ushort v59, v6, s[94:95]
	v_add_u32_e32 v5, v5, v9
	v_add_u32_e32 v8, 0x3180, v8
	v_add_u32_e32 v6, 0x10000, v6
	v_mul_f32_e32 v13, v65, v13
	v_fmac_f32_e32 v10, v20, v54
	v_fmac_f32_e32 v11, v21, v54
	ds_read_b128 v[132:135], v129 offset:8704
	v_mul_f32_e32 v61, v38, v10
	v_fmac_f32_e32 v12, v22, v54
	v_fmac_f32_e32 v61, v39, v11
	ds_read_b128 v[136:139], v130 offset:8704
	v_fmac_f32_e32 v13, v23, v54
	v_fmac_f32_e32 v61, v40, v12
	v_fmac_f32_e32 v61, v41, v13
	ds_read_b128 v[32:35], v0 offset:896
	ds_write_b32 v128, v61 offset:7680
	ds_read_b128 v[50:53], v0 offset:1920
	ds_read_b128 v[74:77], v0 offset:2944
	ds_read_b32 v60, v1 offset:3296
	s_waitcnt lgkmcnt(13)
	v_mul_f32_e32 v10, v66, v10
	v_mul_f32_e32 v11, v67, v11
	v_mul_f32_e32 v12, v68, v12
	ds_read_b128 v[20:23], v0 offset:3328
	v_mul_f32_e32 v13, v69, v13
	v_fmac_f32_e32 v10, v24, v56
	v_fmac_f32_e32 v11, v25, v56
	ds_read_b128 v[38:41], v0 offset:4352
	v_mul_f32_e32 v118, v42, v10
	v_fmac_f32_e32 v12, v26, v56
	v_fmac_f32_e32 v118, v43, v11
	ds_read_b128 v[62:65], v0 offset:5376
	v_fmac_f32_e32 v13, v27, v56
	v_fmac_f32_e32 v118, v44, v12
	v_fmac_f32_e32 v118, v45, v13
	ds_read_b32 v54, v1 offset:6400
	ds_write_b32 v128, v118 offset:7936
	s_waitcnt lgkmcnt(12)
	v_mul_f32_e32 v10, v70, v10
	v_mul_f32_e32 v11, v71, v11
	v_mul_f32_e32 v12, v72, v12
	s_waitcnt lgkmcnt(10)
	v_mul_f32_e32 v13, v73, v13
	v_fmac_f32_e32 v10, v28, v58
	v_fmac_f32_e32 v11, v29, v58
	v_add_f32_e32 v132, v132, v136
	v_mul_f32_e32 v61, v46, v10
	v_fmac_f32_e32 v12, v30, v58
	v_fmac_f32_e32 v61, v47, v11
	v_add_f32_e32 v133, v133, v137
	v_fmac_f32_e32 v13, v31, v58
	v_fmac_f32_e32 v61, v48, v12
	v_fmac_f32_e32 v61, v49, v13
	v_add_f32_e32 v134, v134, v138
	ds_write_b32 v128, v61 offset:8192
	ds_read_b128 v[24:27], v0 offset:3456
	ds_read_b128 v[42:45], v0 offset:4480
	ds_read_b128 v[66:69], v0 offset:5504
	ds_read_b32 v56, v1 offset:6432
	v_add_f32_e32 v135, v135, v139
	v_add_f32_e32 v132, v132, v133
	v_add_f32_e32 v134, v134, v135
	v_add_f32_e32 v132, v132, v134
	v_cvt_pk_bf16_f32 v19, v132, v132
	ds_write_b16 v121, v19 offset:11392
	s_waitcnt lgkmcnt(11)
	v_mul_f32_e32 v10, v74, v10
	v_mul_f32_e32 v11, v75, v11
	v_mul_f32_e32 v12, v76, v12
	ds_read_b128 v[28:31], v0 offset:3584
	v_mul_f32_e32 v13, v77, v13
	v_fmac_f32_e32 v10, v32, v60
	v_fmac_f32_e32 v11, v33, v60
	ds_read_b128 v[46:49], v0 offset:4608
	v_mul_f32_e32 v118, v50, v10
	v_fmac_f32_e32 v12, v34, v60
	v_fmac_f32_e32 v118, v51, v11
	ds_read_b128 v[70:73], v0 offset:5632
	v_fmac_f32_e32 v13, v35, v60
	v_fmac_f32_e32 v118, v52, v12
	v_fmac_f32_e32 v118, v53, v13
	ds_read_b32 v58, v1 offset:6464
	ds_write_b32 v128, v118 offset:8448
	s_waitcnt lgkmcnt(12)
	v_mul_f32_e32 v10, v62, v10
	v_mul_f32_e32 v11, v63, v11
	v_mul_f32_e32 v12, v64, v12
	s_waitcnt vmcnt(11)
	v_mul_f32_e32 v13, v65, v13
	v_fmac_f32_e32 v10, v20, v54
	v_fmac_f32_e32 v11, v21, v54
	v_lshlrev_b32_e32 v110, 16, v78
	v_mul_f32_e32 v61, v38, v10
	v_fmac_f32_e32 v12, v22, v54
	v_fmac_f32_e32 v61, v39, v11
	v_and_b32_e32 v111, 0xffff0000, v78
	v_fmac_f32_e32 v13, v23, v54
	v_fmac_f32_e32 v61, v40, v12
	v_fmac_f32_e32 v61, v41, v13
	v_lshlrev_b32_e32 v112, 16, v79
	ds_write_b32 v128, v61 offset:8704
	ds_read_b128 v[32:35], v0 offset:3712
	ds_read_b128 v[50:53], v0 offset:4736
	ds_read_b128 v[74:77], v0 offset:5760
	ds_read_b32 v60, v1 offset:6496
	v_and_b32_e32 v113, 0xffff0000, v79
	s_waitcnt lgkmcnt(11)
	v_mul_f32_e32 v10, v66, v10
	v_mul_f32_e32 v11, v67, v11
	v_mul_f32_e32 v12, v68, v12
	ds_write_b128 v2, v[110:113] offset:0
	v_mul_f32_e32 v13, v69, v13
	v_fmac_f32_e32 v10, v24, v56
	v_fmac_f32_e32 v11, v25, v56
	v_lshlrev_b32_e32 v114, 16, v80
	v_mul_f32_e32 v118, v42, v10
	v_fmac_f32_e32 v12, v26, v56
	v_fmac_f32_e32 v118, v43, v11
	v_and_b32_e32 v115, 0xffff0000, v80
	v_fmac_f32_e32 v13, v27, v56
	v_fmac_f32_e32 v118, v44, v12
	v_fmac_f32_e32 v118, v45, v13
	v_lshlrev_b32_e32 v116, 16, v81
	ds_write_b32 v128, v118 offset:8960
	ds_read_b128 v[20:23], v0 offset:3840
	ds_read_b128 v[38:41], v0 offset:4864
	ds_read_b128 v[62:65], v0 offset:5888
	ds_read_b32 v54, v1 offset:6528
	v_and_b32_e32 v117, 0xffff0000, v81
	s_waitcnt lgkmcnt(12)
	v_mul_f32_e32 v10, v70, v10
	v_mul_f32_e32 v11, v71, v11
	v_mul_f32_e32 v12, v72, v12
	ds_write_b128 v2, v[114:117] offset:16
	v_mul_f32_e32 v13, v73, v13
	v_fmac_f32_e32 v10, v28, v58
	v_fmac_f32_e32 v11, v29, v58
	s_waitcnt vmcnt(10)
	v_mul_f32_e32 v61, v46, v10
	v_fmac_f32_e32 v12, v30, v58
	v_fmac_f32_e32 v61, v47, v11
	ds_write_b128 v119, v[82:85] offset:2048
	v_fmac_f32_e32 v13, v31, v58
	v_fmac_f32_e32 v61, v48, v12
	v_fmac_f32_e32 v61, v49, v13
	s_waitcnt vmcnt(9)
	ds_write_b32 v128, v61 offset:9216
	ds_read_b128 v[24:27], v0 offset:3968
	ds_read_b128 v[42:45], v0 offset:4992
	ds_read_b128 v[66:69], v0 offset:6016
	ds_read_b32 v56, v1 offset:6560
	v_lshlrev_b32_e32 v36, 16, v36
	s_waitcnt lgkmcnt(13)
	v_mul_f32_e32 v10, v74, v10
	v_mul_f32_e32 v11, v75, v11
	v_mul_f32_e32 v12, v76, v12
	s_nop 0
	v_mul_f32_e32 v13, v77, v13
	v_fmac_f32_e32 v10, v32, v60
	v_fmac_f32_e32 v11, v33, v60
	ds_write_b32 v4, v36 offset:3072
	v_mul_f32_e32 v118, v50, v10
	v_fmac_f32_e32 v12, v34, v60
	v_fmac_f32_e32 v118, v51, v11
	ds_read_b128 v[28:31], v0 offset:4096
	v_fmac_f32_e32 v13, v35, v60
	v_fmac_f32_e32 v118, v52, v12
	v_fmac_f32_e32 v118, v53, v13
	ds_read_b128 v[46:49], v0 offset:5120
	ds_write_b32 v128, v118 offset:9472
	ds_read_b128 v[70:73], v0 offset:6144
	ds_read_b32 v58, v1 offset:6592
	s_waitcnt lgkmcnt(13)
	v_mul_f32_e32 v10, v62, v10
	v_mul_f32_e32 v11, v63, v11
	v_mul_f32_e32 v12, v64, v12
	global_load_dwordx4 v[78:81], v5, s[94:95]
	global_load_dwordx4 v[82:85], v8, s[94:95]
	global_load_ushort v36, v6, s[94:95]
	v_add_u32_e32 v5, v5, v9
	v_add_u32_e32 v8, 0x3180, v8
	v_add_u32_e32 v6, 0x10000, v6
	v_mul_f32_e32 v13, v65, v13
	v_fmac_f32_e32 v10, v20, v54
	v_fmac_f32_e32 v11, v21, v54
	ds_read_b128 v[132:135], v129 offset:6656
	v_mul_f32_e32 v61, v38, v10
	v_fmac_f32_e32 v12, v22, v54
	v_fmac_f32_e32 v61, v39, v11
	ds_read_b128 v[136:139], v130 offset:6656
	v_fmac_f32_e32 v13, v23, v54
	v_fmac_f32_e32 v61, v40, v12
	v_fmac_f32_e32 v61, v41, v13
	ds_read_b128 v[32:35], v0 offset:4224
	ds_write_b32 v128, v61 offset:9728
	ds_read_b128 v[50:53], v0 offset:5248
	ds_read_b128 v[74:77], v0 offset:6272
	ds_read_b32 v60, v1 offset:6624
	s_waitcnt lgkmcnt(13)
	v_mul_f32_e32 v10, v66, v10
	v_mul_f32_e32 v11, v67, v11
	v_mul_f32_e32 v12, v68, v12
	ds_read_b128 v[20:23], v0 offset:0
	v_mul_f32_e32 v13, v69, v13
	v_fmac_f32_e32 v10, v24, v56
	v_fmac_f32_e32 v11, v25, v56
	ds_read_b128 v[38:41], v0 offset:1024
	v_mul_f32_e32 v118, v42, v10
	v_fmac_f32_e32 v12, v26, v56
	v_fmac_f32_e32 v118, v43, v11
	ds_read_b128 v[62:65], v0 offset:2048
	v_fmac_f32_e32 v13, v27, v56
	v_fmac_f32_e32 v118, v44, v12
	v_fmac_f32_e32 v118, v45, v13
	ds_read_b32 v54, v1 offset:3072
	ds_write_b32 v128, v118 offset:9984
	s_waitcnt lgkmcnt(12)
	v_mul_f32_e32 v10, v70, v10
	v_mul_f32_e32 v11, v71, v11
	v_mul_f32_e32 v12, v72, v12
	s_waitcnt lgkmcnt(10)
	v_mul_f32_e32 v13, v73, v13
	v_fmac_f32_e32 v10, v28, v58
	v_fmac_f32_e32 v11, v29, v58
	v_add_f32_e32 v132, v132, v136
	v_mul_f32_e32 v61, v46, v10
	v_fmac_f32_e32 v12, v30, v58
	v_fmac_f32_e32 v61, v47, v11
	v_add_f32_e32 v133, v133, v137
	v_fmac_f32_e32 v13, v31, v58
	v_fmac_f32_e32 v61, v48, v12
	v_fmac_f32_e32 v61, v49, v13
	v_add_f32_e32 v134, v134, v138
	ds_write_b32 v128, v61 offset:10240
	ds_read_b128 v[24:27], v0 offset:128
	ds_read_b128 v[42:45], v0 offset:1152
	ds_read_b128 v[66:69], v0 offset:2176
	ds_read_b32 v56, v1 offset:3104
	v_add_f32_e32 v135, v135, v139
	v_add_f32_e32 v132, v132, v133
	v_add_f32_e32 v134, v134, v135
	v_add_f32_e32 v132, v132, v134
	v_cvt_pk_bf16_f32 v19, v132, v132
	ds_write_b16 v121, v19 offset:11520
	s_waitcnt lgkmcnt(11)
	v_mul_f32_e32 v10, v74, v10
	v_mul_f32_e32 v11, v75, v11
	v_mul_f32_e32 v12, v76, v12
	ds_read_b128 v[28:31], v0 offset:256
	v_mul_f32_e32 v13, v77, v13
	v_fmac_f32_e32 v10, v32, v60
	v_fmac_f32_e32 v11, v33, v60
	ds_read_b128 v[46:49], v0 offset:1280
	v_mul_f32_e32 v118, v50, v10
	v_fmac_f32_e32 v12, v34, v60
	v_fmac_f32_e32 v118, v51, v11
	ds_read_b128 v[70:73], v0 offset:2304
	v_fmac_f32_e32 v13, v35, v60
	v_fmac_f32_e32 v118, v52, v12
	v_fmac_f32_e32 v118, v53, v13
	ds_read_b32 v58, v1 offset:3136
	ds_write_b32 v128, v118 offset:10496
	s_sub_u32 s12, s12, 1
	s_cmp_lg_u32 s12, 0
	s_cbranch_scc1 .Lls1_8_loop
	ds_read_b128 v[132:135], v129 offset:8704
	ds_read_b128 v[136:139], v130 offset:8704
	s_waitcnt lgkmcnt(0)
	v_add_f32_e32 v132, v132, v136
	v_add_f32_e32 v133, v133, v137
	v_add_f32_e32 v134, v134, v138
	v_add_f32_e32 v135, v135, v139
	v_add_f32_e32 v132, v132, v133
	v_add_f32_e32 v134, v134, v135
	v_add_f32_e32 v132, v132, v134
	v_cvt_pk_bf16_f32 v19, v132, v132
	ds_write_b16 v121, v19 offset:11648
	s_waitcnt lgkmcnt(0)
	ds_read_b128 v[124:127], v122 offset:11264
	s_waitcnt lgkmcnt(0)
	global_store_dwordx4 v7, v[124:127], s[94:95]
	v_add_u32_e32 v7, 0x20000, v7
	s_nop 0
	ds_read_b128 v[124:127], v122 offset:12288
	s_waitcnt lgkmcnt(0)
	global_store_dwordx4 v7, v[124:127], s[94:95]
	v_add_u32_e32 v7, 0x20000, v7
	s_nop 0
	ds_read_b128 v[124:127], v122 offset:13312
	s_waitcnt lgkmcnt(0)
	global_store_dwordx4 v7, v[124:127], s[94:95]
	v_add_u32_e32 v7, 0x20000, v7
	s_nop 0
	ds_read_b128 v[124:127], v122 offset:14336
	s_waitcnt lgkmcnt(0)
	global_store_dwordx4 v7, v[124:127], s[94:95]
	v_add_u32_e32 v7, 0x20000, v7
	s_nop 0
	ds_read_b128 v[124:127], v122 offset:15360
	s_waitcnt lgkmcnt(0)
	global_store_dwordx4 v7, v[124:127], s[94:95]
	v_add_u32_e32 v7, 0x20000, v7
	s_nop 0
	ds_read_b128 v[124:127], v122 offset:16384
	s_waitcnt lgkmcnt(0)
	global_store_dwordx4 v7, v[124:127], s[94:95]
	v_add_u32_e32 v7, 0x20000, v7
	s_nop 0
	ds_read_b128 v[124:127], v122 offset:17408
	s_waitcnt lgkmcnt(0)
	global_store_dwordx4 v7, v[124:127], s[94:95]
	v_add_u32_e32 v7, 0x20000, v7
	s_nop 0
	ds_read_b128 v[124:127], v122 offset:18432
	s_waitcnt lgkmcnt(0)
	global_store_dwordx4 v7, v[124:127], s[94:95]
	v_add_u32_e32 v7, 0x20000, v7
	s_nop 0
	global_store_dword v120, v10, s[26:27] offset:0
	global_store_dword v120, v11, s[26:27] offset:256
	global_store_dword v120, v12, s[26:27] offset:512
	global_store_dword v120, v13, s[26:27] offset:768
	s_waitcnt vmcnt(0) lgkmcnt(0)
	s_setprio 0
	s_branch .Lls_done
